# scan: y reduced over quads only, two partials per row summed in the flush; 1/cw by v_rcp in staging (no table)
# speedup vs baseline: 1.0208x; 1.0039x over previous
.LBB0_190:
	s_or_b64 exec, exec, s[4:5]
	v_add_f32_e32 v0, v0, v44
	v_max_f32_e32 v0, 0x179abe15, v0
	v_cvt_f32_f16_e32 v43, v28
	v_rsq_f32_e32 v0, v0
	v_cvt_f32_f16_sdwa v45, v28 dst_sel:DWORD dst_unused:UNUSED_PAD src0_sel:WORD_1
	v_cvt_f32_f16_e32 v46, v29
	v_cvt_f32_f16_sdwa v47, v29 dst_sel:DWORD dst_unused:UNUSED_PAD src0_sel:WORD_1
	v_pk_mul_f32 v[36:37], v[36:37], v[0:1] op_sel_hi:[1,0] neg_lo:[0,1] neg_hi:[0,1]
	v_pk_mul_f32 v[34:35], v[34:35], v[0:1] op_sel_hi:[1,0] neg_lo:[0,1] neg_hi:[0,1]
	v_mul_f32_e32 v0, 0xbfb8aa3b, v43
	v_exp_f32_e32 v44, v0
	v_mul_f32_e32 v0, 0xbfb8aa3b, v45
	v_exp_f32_e32 v45, v0
	v_mul_f32_e32 v0, 0xbfb8aa3b, v46
	v_exp_f32_e32 v46, v0
	v_mul_f32_e32 v0, 0xbfb8aa3b, v47
	v_exp_f32_e32 v47, v0
	s_add_u32 s2, s42, s34
	s_addc_u32 s3, s43, 0
	v_pk_mul_f32 v[40:41], v[38:39], v[36:37] neg_lo:[0,1] neg_hi:[0,1]
	v_pk_mul_f32 v[38:39], v[32:33], v[34:35] neg_lo:[0,1] neg_hi:[0,1]
	ds_read_b128 v[66:69], v57 offset:16384
	ds_read_b128 v[74:77], v57 offset:24576
	s_waitcnt lgkmcnt(0)
	v_rcp_f32_e32 v70, v66
	v_rcp_f32_e32 v71, v67
	v_rcp_f32_e32 v72, v68
	v_rcp_f32_e32 v73, v69
	v_pk_mul_f32 v[34:35], v[34:35], v[74:75]
	v_pk_mul_f32 v[36:37], v[36:37], v[76:77]
	v_pk_mul_f32 v[14:15], v[14:15], v[66:67]
	v_pk_mul_f32 v[16:17], v[16:17], v[68:69]
	v_pk_mul_f32 v[18:19], v[18:19], v[70:71]
	v_pk_mul_f32 v[20:21], v[20:21], v[72:73]
	v_pk_mul_f32 v[38:39], v[38:39], v[70:71]
	v_pk_mul_f32 v[40:41], v[40:41], v[72:73]
	ds_write_b128 v55, v[66:69]
	ds_write_b128 v55, v[18:21] offset:256
	ds_write_b128 v55, v[34:37] offset:512
	ds_write_b128 v55, v[38:41] offset:768
	ds_write_b128 v55, v[14:17] offset:1024
	v_lshlrev_b32_e32 v14, 16, v26
	v_and_b32_e32 v15, 0xffff0000, v26
	v_lshlrev_b32_e32 v16, 16, v27
	v_and_b32_e32 v17, 0xffff0000, v27
	v_lshlrev_b32_e32 v0, 1, v60
	ds_write_b128 v55, v[14:17] offset:1280
	v_lshl_add_u64 v[14:15], s[2:3], 0, v[0:1]
	s_mov_b64 s[2:3], 0x18300000
	v_lshlrev_b32_e32 v0, 2, v42
	v_mov_b32_e32 v36, 0
	s_lshl_b32 s33, s33, 12
	v_lshl_add_u64 v[32:33], v[14:15], 0, s[2:3]
	v_lshl_add_u64 v[34:35], s[0:1], 0, v[0:1]
	s_mov_b32 s3, 0
	v_mov_b32_e32 v37, v36
	v_mov_b32_e32 v40, v36
	v_mov_b32_e32 v41, v36
	v_mov_b32_e32 v38, v36
	v_mov_b32_e32 v39, v36
	v_mov_b32_e32 v42, v36
	v_mov_b32_e32 v43, v36
	v_mov_b32_e32 v96, v36
	v_mov_b32_e32 v97, v36
	v_mov_b32_e32 v98, v36
	v_mov_b32_e32 v99, v36
	v_mov_b32_e32 v100, v36
	v_mov_b32_e32 v101, v36
	v_mov_b32_e32 v102, v36
	v_mov_b32_e32 v103, v36
	v_mov_b32_e32 v104, v36
	v_mov_b32_e32 v105, v36
	v_mov_b32_e32 v106, v36
	v_mov_b32_e32 v107, v36
	v_mov_b32_e32 v108, v36
	v_mov_b32_e32 v109, v36
	v_mov_b32_e32 v110, v36
	v_mov_b32_e32 v111, v36
	s_waitcnt lgkmcnt(0)
	s_barrier
	s_branch .LBB0_193
.LBB0_191:
	s_or_b64 exec, exec, s[0:1]
	v_add_f32_e32 v0, v0, v61
	v_max_f32_e32 v0, 0x179abe15, v0
	v_cvt_f32_f16_e32 v62, v28
	v_rsq_f32_e32 v0, v0
	v_cvt_f32_f16_sdwa v61, v28 dst_sel:DWORD dst_unused:UNUSED_PAD src0_sel:WORD_1
	v_cvt_f32_f16_e32 v64, v29
	v_cvt_f32_f16_sdwa v65, v29 dst_sel:DWORD dst_unused:UNUSED_PAD src0_sel:WORD_1
	v_pk_mul_f32 v[50:51], v[50:51], v[0:1] op_sel_hi:[1,0] neg_lo:[0,1] neg_hi:[0,1]
	v_pk_mul_f32 v[48:49], v[48:49], v[0:1] op_sel_hi:[1,0] neg_lo:[0,1] neg_hi:[0,1]
	v_mul_f32_e32 v0, 0xbfb8aa3b, v62
	v_exp_f32_e32 v62, v0
	v_mul_f32_e32 v0, 0xbfb8aa3b, v61
	v_exp_f32_e32 v63, v0
	v_mul_f32_e32 v0, 0xbfb8aa3b, v64
	v_exp_f32_e32 v64, v0
	v_mul_f32_e32 v0, 0xbfb8aa3b, v65
	v_exp_f32_e32 v65, v0
	s_bitcmp1_b32 s2, 0
	s_cselect_b32 s0, 0xc000, 0
	v_add_u32_e32 v0, s0, v55
	v_pk_mul_f32 v[46:47], v[46:47], v[50:51] neg_lo:[0,1] neg_hi:[0,1]
	v_pk_mul_f32 v[44:45], v[44:45], v[48:49] neg_lo:[0,1] neg_hi:[0,1]
	ds_read_b128 v[66:69], v57 offset:16384
	ds_read_b128 v[74:77], v57 offset:24576
	s_waitcnt lgkmcnt(0)
	v_rcp_f32_e32 v70, v66
	v_rcp_f32_e32 v71, v67
	v_rcp_f32_e32 v72, v68
	v_rcp_f32_e32 v73, v69
	v_pk_mul_f32 v[48:49], v[48:49], v[74:75]
	v_pk_mul_f32 v[50:51], v[50:51], v[76:77]
	v_pk_mul_f32 v[14:15], v[14:15], v[66:67]
	v_pk_mul_f32 v[16:17], v[16:17], v[68:69]
	v_pk_mul_f32 v[18:19], v[18:19], v[70:71]
	v_pk_mul_f32 v[20:21], v[20:21], v[72:73]
	v_pk_mul_f32 v[44:45], v[44:45], v[70:71]
	v_pk_mul_f32 v[46:47], v[46:47], v[72:73]
	ds_write_b128 v0, v[66:69]
	ds_write_b128 v0, v[18:21] offset:256
	ds_write_b128 v0, v[48:51] offset:512
	ds_write_b128 v0, v[44:47] offset:768
	ds_write_b128 v0, v[14:17] offset:1024
	v_lshlrev_b32_e32 v14, 16, v26
	v_and_b32_e32 v15, 0xffff0000, v26
	v_lshlrev_b32_e32 v16, 16, v27
	v_and_b32_e32 v17, 0xffff0000, v27
	ds_write_b128 v0, v[14:17] offset:1280

.Lscan_cw_com:
	s_add_u32 s35, s38, s35
	s_lshl_b32 s35, s35, 12
	s_add_u32 s86, s20, s35
	s_addc_u32 s87, s21, 0
	global_load_ushort v62, v44, s[86:87]
	v_add_u32_e32 v44, s32, v44
	global_load_ushort v63, v44, s[86:87]
	v_add_u32_e32 v44, s32, v44
	global_load_ushort v64, v44, s[86:87]
	v_add_u32_e32 v44, s32, v44
	global_load_ushort v65, v44, s[86:87]
	v_add_u32_e32 v44, s32, v44
	global_load_ushort v66, v44, s[86:87]
	v_add_u32_e32 v44, s32, v44
	global_load_ushort v67, v44, s[86:87]
	v_add_u32_e32 v44, s32, v44
	global_load_ushort v68, v44, s[86:87]
	v_add_u32_e32 v44, s32, v44
	global_load_ushort v69, v44, s[86:87]
	v_add_u32_e32 v44, s32, v44
	global_load_ushort v70, v44, s[86:87]
	v_add_u32_e32 v44, s32, v44
	global_load_ushort v71, v44, s[86:87]
	v_add_u32_e32 v44, s32, v44
	global_load_ushort v72, v44, s[86:87]
	v_add_u32_e32 v44, s32, v44
	global_load_ushort v73, v44, s[86:87]
	v_add_u32_e32 v44, s32, v44
	global_load_ushort v74, v44, s[86:87]
	v_add_u32_e32 v44, s32, v44
	global_load_ushort v75, v44, s[86:87]
	v_add_u32_e32 v44, s32, v44
	global_load_ushort v76, v44, s[86:87]
	v_add_u32_e32 v44, s32, v44
	global_load_ushort v77, v44, s[86:87]
	v_add_u32_e32 v44, s32, v44
	global_load_ushort v78, v44, s[86:87]
	v_add_u32_e32 v44, s32, v44
	global_load_ushort v79, v44, s[86:87]
	v_add_u32_e32 v44, s32, v44
	global_load_ushort v80, v44, s[86:87]
	v_add_u32_e32 v44, s32, v44
	global_load_ushort v81, v44, s[86:87]
	v_add_u32_e32 v44, s32, v44
	global_load_ushort v82, v44, s[86:87]
	v_add_u32_e32 v44, s32, v44
	global_load_ushort v83, v44, s[86:87]
	v_add_u32_e32 v44, s32, v44
	global_load_ushort v84, v44, s[86:87]
	v_add_u32_e32 v44, s32, v44
	global_load_ushort v85, v44, s[86:87]
	v_add_u32_e32 v44, s32, v44
	global_load_ushort v86, v44, s[86:87]
	v_add_u32_e32 v44, s32, v44
	global_load_ushort v87, v44, s[86:87]
	v_add_u32_e32 v44, s32, v44
	global_load_ushort v88, v44, s[86:87]
	v_add_u32_e32 v44, s32, v44
	global_load_ushort v89, v44, s[86:87]
	v_add_u32_e32 v44, s32, v44
	global_load_ushort v90, v44, s[86:87]
	v_add_u32_e32 v44, s32, v44
	global_load_ushort v91, v44, s[86:87]
	v_add_u32_e32 v44, s32, v44
	global_load_ushort v92, v44, s[86:87]
	v_add_u32_e32 v44, s32, v44
	global_load_ushort v93, v44, s[86:87]
	v_add_u32_e32 v44, s32, v44
	v_mov_b32_e32 v46, 0
	s_waitcnt vmcnt(0)
	v_cvt_f32_f16_e32 v47, v62
	v_mul_f32_e32 v48, 0xbfb8aa3b, v46
	v_add_f32_e32 v46, v46, v47
	v_exp_f32_e32 v48, v48
	v_mul_f32_e32 v49, 0xbfb8aa3b, v46
	v_exp_f32_e32 v49, v49
	ds_write_b32 v45, v48 offset:16384
	s_nop 0
	ds_write_b32 v45, v49 offset:8192
	v_cvt_f32_f16_e32 v47, v63
	v_mul_f32_e32 v48, 0xbfb8aa3b, v46
	v_add_f32_e32 v46, v46, v47
	v_exp_f32_e32 v48, v48
	v_mul_f32_e32 v49, 0xbfb8aa3b, v46
	v_exp_f32_e32 v49, v49
	ds_write_b32 v45, v48 offset:16640
	s_nop 0
	ds_write_b32 v45, v49 offset:8448
	v_cvt_f32_f16_e32 v47, v64
	v_mul_f32_e32 v48, 0xbfb8aa3b, v46
	v_add_f32_e32 v46, v46, v47
	v_exp_f32_e32 v48, v48
	v_mul_f32_e32 v49, 0xbfb8aa3b, v46
	v_exp_f32_e32 v49, v49
	ds_write_b32 v45, v48 offset:16896
	s_nop 0
	ds_write_b32 v45, v49 offset:8704
	v_cvt_f32_f16_e32 v47, v65
	v_mul_f32_e32 v48, 0xbfb8aa3b, v46
	v_add_f32_e32 v46, v46, v47
	v_exp_f32_e32 v48, v48
	v_mul_f32_e32 v49, 0xbfb8aa3b, v46
	v_exp_f32_e32 v49, v49
	ds_write_b32 v45, v48 offset:17152
	s_nop 0
	ds_write_b32 v45, v49 offset:8960
	v_cvt_f32_f16_e32 v47, v66
	v_mul_f32_e32 v48, 0xbfb8aa3b, v46
	v_add_f32_e32 v46, v46, v47
	v_exp_f32_e32 v48, v48
	v_mul_f32_e32 v49, 0xbfb8aa3b, v46
	v_exp_f32_e32 v49, v49
	ds_write_b32 v45, v48 offset:17408
	s_nop 0
	ds_write_b32 v45, v49 offset:9216
	v_cvt_f32_f16_e32 v47, v67
	v_mul_f32_e32 v48, 0xbfb8aa3b, v46
	v_add_f32_e32 v46, v46, v47
	v_exp_f32_e32 v48, v48
	v_mul_f32_e32 v49, 0xbfb8aa3b, v46
	v_exp_f32_e32 v49, v49
	ds_write_b32 v45, v48 offset:17664
	s_nop 0
	ds_write_b32 v45, v49 offset:9472
	v_cvt_f32_f16_e32 v47, v68
	v_mul_f32_e32 v48, 0xbfb8aa3b, v46
	v_add_f32_e32 v46, v46, v47
	v_exp_f32_e32 v48, v48
	v_mul_f32_e32 v49, 0xbfb8aa3b, v46
	v_exp_f32_e32 v49, v49
	ds_write_b32 v45, v48 offset:17920
	s_nop 0
	ds_write_b32 v45, v49 offset:9728
	v_cvt_f32_f16_e32 v47, v69
	v_mul_f32_e32 v48, 0xbfb8aa3b, v46
	v_add_f32_e32 v46, v46, v47
	v_exp_f32_e32 v48, v48
	v_mul_f32_e32 v49, 0xbfb8aa3b, v46
	v_exp_f32_e32 v49, v49
	ds_write_b32 v45, v48 offset:18176
	s_nop 0
	ds_write_b32 v45, v49 offset:9984
	v_cvt_f32_f16_e32 v47, v70
	v_mul_f32_e32 v48, 0xbfb8aa3b, v46
	v_add_f32_e32 v46, v46, v47
	v_exp_f32_e32 v48, v48
	v_mul_f32_e32 v49, 0xbfb8aa3b, v46
	v_exp_f32_e32 v49, v49
	ds_write_b32 v45, v48 offset:18432
	s_nop 0
	ds_write_b32 v45, v49 offset:10240
	v_cvt_f32_f16_e32 v47, v71
	v_mul_f32_e32 v48, 0xbfb8aa3b, v46
	v_add_f32_e32 v46, v46, v47
	v_exp_f32_e32 v48, v48
	v_mul_f32_e32 v49, 0xbfb8aa3b, v46
	v_exp_f32_e32 v49, v49
	ds_write_b32 v45, v48 offset:18688
	s_nop 0
	ds_write_b32 v45, v49 offset:10496
	v_cvt_f32_f16_e32 v47, v72
	v_mul_f32_e32 v48, 0xbfb8aa3b, v46
	v_add_f32_e32 v46, v46, v47
	v_exp_f32_e32 v48, v48
	v_mul_f32_e32 v49, 0xbfb8aa3b, v46
	v_exp_f32_e32 v49, v49
	ds_write_b32 v45, v48 offset:18944
	s_nop 0
	ds_write_b32 v45, v49 offset:10752
	v_cvt_f32_f16_e32 v47, v73
	v_mul_f32_e32 v48, 0xbfb8aa3b, v46
	v_add_f32_e32 v46, v46, v47
	v_exp_f32_e32 v48, v48
	v_mul_f32_e32 v49, 0xbfb8aa3b, v46
	v_exp_f32_e32 v49, v49
	ds_write_b32 v45, v48 offset:19200
	s_nop 0
	ds_write_b32 v45, v49 offset:11008
	v_cvt_f32_f16_e32 v47, v74
	v_mul_f32_e32 v48, 0xbfb8aa3b, v46
	v_add_f32_e32 v46, v46, v47
	v_exp_f32_e32 v48, v48
	v_mul_f32_e32 v49, 0xbfb8aa3b, v46
	v_exp_f32_e32 v49, v49
	ds_write_b32 v45, v48 offset:19456
	s_nop 0
	ds_write_b32 v45, v49 offset:11264
	v_cvt_f32_f16_e32 v47, v75
	v_mul_f32_e32 v48, 0xbfb8aa3b, v46
	v_add_f32_e32 v46, v46, v47
	v_exp_f32_e32 v48, v48
	v_mul_f32_e32 v49, 0xbfb8aa3b, v46
	v_exp_f32_e32 v49, v49
	ds_write_b32 v45, v48 offset:19712
	s_nop 0
	ds_write_b32 v45, v49 offset:11520
	v_cvt_f32_f16_e32 v47, v76
	v_mul_f32_e32 v48, 0xbfb8aa3b, v46
	v_add_f32_e32 v46, v46, v47
	v_exp_f32_e32 v48, v48
	v_mul_f32_e32 v49, 0xbfb8aa3b, v46
	v_exp_f32_e32 v49, v49
	ds_write_b32 v45, v48 offset:19968
	s_nop 0
	ds_write_b32 v45, v49 offset:11776
	v_cvt_f32_f16_e32 v47, v77
	v_mul_f32_e32 v48, 0xbfb8aa3b, v46
	v_add_f32_e32 v46, v46, v47
	v_exp_f32_e32 v48, v48
	v_mul_f32_e32 v49, 0xbfb8aa3b, v46
	v_exp_f32_e32 v49, v49
	ds_write_b32 v45, v48 offset:20224
	s_nop 0
	ds_write_b32 v45, v49 offset:12032
	v_cvt_f32_f16_e32 v47, v78
	v_mul_f32_e32 v48, 0xbfb8aa3b, v46
	v_add_f32_e32 v46, v46, v47
	v_exp_f32_e32 v48, v48
	v_mul_f32_e32 v49, 0xbfb8aa3b, v46
	v_exp_f32_e32 v49, v49
	ds_write_b32 v45, v48 offset:20480
	s_nop 0
	ds_write_b32 v45, v49 offset:12288
	v_cvt_f32_f16_e32 v47, v79
	v_mul_f32_e32 v48, 0xbfb8aa3b, v46
	v_add_f32_e32 v46, v46, v47
	v_exp_f32_e32 v48, v48
	v_mul_f32_e32 v49, 0xbfb8aa3b, v46
	v_exp_f32_e32 v49, v49
	ds_write_b32 v45, v48 offset:20736
	s_nop 0
	ds_write_b32 v45, v49 offset:12544
	v_cvt_f32_f16_e32 v47, v80
	v_mul_f32_e32 v48, 0xbfb8aa3b, v46
	v_add_f32_e32 v46, v46, v47
	v_exp_f32_e32 v48, v48
	v_mul_f32_e32 v49, 0xbfb8aa3b, v46
	v_exp_f32_e32 v49, v49
	ds_write_b32 v45, v48 offset:20992
	s_nop 0
	ds_write_b32 v45, v49 offset:12800
	v_cvt_f32_f16_e32 v47, v81
	v_mul_f32_e32 v48, 0xbfb8aa3b, v46
	v_add_f32_e32 v46, v46, v47
	v_exp_f32_e32 v48, v48
	v_mul_f32_e32 v49, 0xbfb8aa3b, v46
	v_exp_f32_e32 v49, v49
	ds_write_b32 v45, v48 offset:21248
	s_nop 0
	ds_write_b32 v45, v49 offset:13056
	v_cvt_f32_f16_e32 v47, v82
	v_mul_f32_e32 v48, 0xbfb8aa3b, v46
	v_add_f32_e32 v46, v46, v47
	v_exp_f32_e32 v48, v48
	v_mul_f32_e32 v49, 0xbfb8aa3b, v46
	v_exp_f32_e32 v49, v49
	ds_write_b32 v45, v48 offset:21504
	s_nop 0
	ds_write_b32 v45, v49 offset:13312
	v_cvt_f32_f16_e32 v47, v83
	v_mul_f32_e32 v48, 0xbfb8aa3b, v46
	v_add_f32_e32 v46, v46, v47
	v_exp_f32_e32 v48, v48
	v_mul_f32_e32 v49, 0xbfb8aa3b, v46
	v_exp_f32_e32 v49, v49
	ds_write_b32 v45, v48 offset:21760
	s_nop 0
	ds_write_b32 v45, v49 offset:13568
	v_cvt_f32_f16_e32 v47, v84
	v_mul_f32_e32 v48, 0xbfb8aa3b, v46
	v_add_f32_e32 v46, v46, v47
	v_exp_f32_e32 v48, v48
	v_mul_f32_e32 v49, 0xbfb8aa3b, v46
	v_exp_f32_e32 v49, v49
	ds_write_b32 v45, v48 offset:22016
	s_nop 0
	ds_write_b32 v45, v49 offset:13824
	v_cvt_f32_f16_e32 v47, v85
	v_mul_f32_e32 v48, 0xbfb8aa3b, v46
	v_add_f32_e32 v46, v46, v47
	v_exp_f32_e32 v48, v48
	v_mul_f32_e32 v49, 0xbfb8aa3b, v46
	v_exp_f32_e32 v49, v49
	ds_write_b32 v45, v48 offset:22272
	s_nop 0
	ds_write_b32 v45, v49 offset:14080
	v_cvt_f32_f16_e32 v47, v86
	v_mul_f32_e32 v48, 0xbfb8aa3b, v46
	v_add_f32_e32 v46, v46, v47
	v_exp_f32_e32 v48, v48
	v_mul_f32_e32 v49, 0xbfb8aa3b, v46
	v_exp_f32_e32 v49, v49
	ds_write_b32 v45, v48 offset:22528
	s_nop 0
	ds_write_b32 v45, v49 offset:14336
	v_cvt_f32_f16_e32 v47, v87
	v_mul_f32_e32 v48, 0xbfb8aa3b, v46
	v_add_f32_e32 v46, v46, v47
	v_exp_f32_e32 v48, v48
	v_mul_f32_e32 v49, 0xbfb8aa3b, v46
	v_exp_f32_e32 v49, v49
	ds_write_b32 v45, v48 offset:22784
	s_nop 0
	ds_write_b32 v45, v49 offset:14592
	v_cvt_f32_f16_e32 v47, v88
	v_mul_f32_e32 v48, 0xbfb8aa3b, v46
	v_add_f32_e32 v46, v46, v47
	v_exp_f32_e32 v48, v48
	v_mul_f32_e32 v49, 0xbfb8aa3b, v46
	v_exp_f32_e32 v49, v49
	ds_write_b32 v45, v48 offset:23040
	s_nop 0
	ds_write_b32 v45, v49 offset:14848
	v_cvt_f32_f16_e32 v47, v89
	v_mul_f32_e32 v48, 0xbfb8aa3b, v46
	v_add_f32_e32 v46, v46, v47
	v_exp_f32_e32 v48, v48
	v_mul_f32_e32 v49, 0xbfb8aa3b, v46
	v_exp_f32_e32 v49, v49
	ds_write_b32 v45, v48 offset:23296
	s_nop 0
	ds_write_b32 v45, v49 offset:15104
	v_cvt_f32_f16_e32 v47, v90
	v_mul_f32_e32 v48, 0xbfb8aa3b, v46
	v_add_f32_e32 v46, v46, v47
	v_exp_f32_e32 v48, v48
	v_mul_f32_e32 v49, 0xbfb8aa3b, v46
	v_exp_f32_e32 v49, v49
	ds_write_b32 v45, v48 offset:23552
	s_nop 0
	ds_write_b32 v45, v49 offset:15360
	v_cvt_f32_f16_e32 v47, v91
	v_mul_f32_e32 v48, 0xbfb8aa3b, v46
	v_add_f32_e32 v46, v46, v47
	v_exp_f32_e32 v48, v48
	v_mul_f32_e32 v49, 0xbfb8aa3b, v46
	v_exp_f32_e32 v49, v49
	ds_write_b32 v45, v48 offset:23808
	s_nop 0
	ds_write_b32 v45, v49 offset:15616
	v_cvt_f32_f16_e32 v47, v92
	v_mul_f32_e32 v48, 0xbfb8aa3b, v46
	v_add_f32_e32 v46, v46, v47
	v_exp_f32_e32 v48, v48
	v_mul_f32_e32 v49, 0xbfb8aa3b, v46
	v_exp_f32_e32 v49, v49
	ds_write_b32 v45, v48 offset:24064
	s_nop 0
	ds_write_b32 v45, v49 offset:15872
	v_cvt_f32_f16_e32 v47, v93
	v_mul_f32_e32 v48, 0xbfb8aa3b, v46
	v_add_f32_e32 v46, v46, v47
	v_exp_f32_e32 v48, v48
	v_mul_f32_e32 v49, 0xbfb8aa3b, v46
	v_exp_f32_e32 v49, v49
	ds_write_b32 v45, v48 offset:24320
	s_nop 0
	ds_write_b32 v45, v49 offset:16128
	s_waitcnt lgkmcnt(0)
	s_cmp_eq_u32 s47, 0
	s_cbranch_scc1 .Lscan_cw0_ret
	s_branch .LBB0_229
; #define LAS __attribute__((address_space(3)))
; __device__ __forceinline__ float red8(float x) { x += dpp_mov<0xB1>(x); x += dpp_mov<0x4E>(x); x += dpp_mov<0x141>(x); return x; }
; __device__ __forceinline__ void scan_phase(const KP& P, LAS unsigned char* lds, const int tid, const int bx, const int G) {
;     ...
;         for (int c = 0; c < NCH; ++c) {
;             if (c + 1 < NCH) SC_LOAD(c + 1);
;             const LAS float* cb = buf + (c & 1) * 12288 + kc * 8;
; #pragma unroll 16
;             for (int s = 0; s < 32; ++s) {
;                 const LAS float* p = cb + s * 384;
;                 const f32x4 w0 = *(const LAS f32x4*)(p), w1 = *(const LAS f32x4*)(p + 4);
;                 const f32x4 k0 = *(const LAS f32x4*)(p + 64), k1 = *(const LAS f32x4*)(p + 68);
;                 const f32x4 a0 = *(const LAS f32x4*)(p + 128), a1 = *(const LAS f32x4*)(p + 132);
;                 const f32x4 b0 = *(const LAS f32x4*)(p + 192), b1 = *(const LAS f32x4*)(p + 196);
;                 const f32x4 r0 = *(const LAS f32x4*)(p + 256), r1 = *(const LAS f32x4*)(p + 260);
;                 const float vv = buf[(c & 1) * 12288 + s * 384 + 320 + v];
;                 f32x2 sa2 = S[0] * (f32x2){a0.x, a0.y};
;                 sa2 += S[1] * (f32x2){a0.z, a0.w}; sa2 += S[2] * (f32x2){a1.x, a1.y}; sa2 += S[3] * (f32x2){a1.z, a1.w};
;                 const float sa = red8(sa2.x + sa2.y);
;                 const f32x2 sav = {sa, sa}, vv2 = {vv, vv};
;                 S[0] = S[0] * (f32x2){w0.x, w0.y} + sav * (f32x2){b0.x, b0.y} + vv2 * (f32x2){k0.x, k0.y};
;                 S[1] = S[1] * (f32x2){w0.z, w0.w} + sav * (f32x2){b0.z, b0.w} + vv2 * (f32x2){k0.z, k0.w};
;                 S[2] = S[2] * (f32x2){w1.x, w1.y} + sav * (f32x2){b1.x, b1.y} + vv2 * (f32x2){k1.x, k1.y};
;                 S[3] = S[3] * (f32x2){w1.z, w1.w} + sav * (f32x2){b1.z, b1.w} + vv2 * (f32x2){k1.z, k1.w};
;                 f32x2 y2 = S[0] * (f32x2){r0.x, r0.y};
;                 y2 += S[1] * (f32x2){r0.z, r0.w}; y2 += S[2] * (f32x2){r1.x, r1.y}; y2 += S[3] * (f32x2){r1.z, r1.w};
;                 const float y = red8(y2.x + y2.y);
;                 if (kc == 0) ybuf[s * 64 + v] = y;
.Lscan_compute:
	s_bitcmp1_b32 s3, 0
	s_cselect_b32 s0, 0xc000, 0
	v_lshlrev_b32_e32 v45, 1, v58
	v_or_b32_e32 v44, s0, v56
	v_add_u32_e32 v46, s0, v45
	v_add_u32_e32 v46, 0x500, v46
	v_bfe_u32 v47, v166, 2, 1
	v_lshl_add_u32 v45, v47, 8, v45
	v_add_u32_e32 v45, 0x18000, v45
	v_and_b32_e32 v47, 3, v166
	v_cmp_eq_u32_e64 s[86:87], 0, v47
	s_mov_b64 s[0:1], exec
	ds_read_b128 v[148:151], v44 offset:512
	ds_read_b128 v[152:155], v44 offset:528
	ds_read_b128 v[156:159], v44 offset:2048
	ds_read_b128 v[160:163], v44 offset:2064
	ds_read_b128 v[120:123], v44 offset:256
	ds_read_b128 v[124:127], v44 offset:272
	ds_read_b128 v[128:131], v44 offset:768
	ds_read_b128 v[132:135], v44 offset:784
	ds_read_b128 v[136:139], v44 offset:1024
	ds_read_b128 v[140:143], v44 offset:1040
	ds_read_b64 v[144:145], v46 offset:0
	ds_read_b128 v[112:115], v44 offset:47616
	ds_read_b128 v[116:119], v44 offset:47632
	ds_read_b128 v[62:65], v44 offset:3584
	ds_read_b128 v[66:69], v44 offset:3600
	ds_read_b128 v[70:73], v44 offset:1792
	ds_read_b128 v[74:77], v44 offset:1808
	ds_read_b128 v[78:81], v44 offset:2304
	ds_read_b128 v[82:85], v44 offset:2320
	ds_read_b128 v[86:89], v44 offset:2560
	ds_read_b128 v[90:93], v44 offset:2576
	ds_read_b64 v[146:147], v46 offset:1536
	s_waitcnt lgkmcnt(15)
	v_pk_mul_f32 v[50:51], v[96:97], v[148:149] op_sel:[0,0] op_sel_hi:[1,0]
	s_nop 0
	v_pk_fma_f32 v[50:51], v[98:99], v[148:149], v[50:51] op_sel:[0,1,0] op_sel_hi:[1,1,1]
	s_nop 0
	v_pk_fma_f32 v[50:51], v[100:101], v[150:151], v[50:51] op_sel:[0,0,0] op_sel_hi:[1,0,1]
	s_nop 0
	v_pk_fma_f32 v[50:51], v[102:103], v[150:151], v[50:51] op_sel:[0,1,0] op_sel_hi:[1,1,1]
	s_nop 0
	v_pk_fma_f32 v[50:51], v[104:105], v[152:153], v[50:51] op_sel:[0,0,0] op_sel_hi:[1,0,1]
	s_nop 0
	v_pk_fma_f32 v[50:51], v[106:107], v[152:153], v[50:51] op_sel:[0,1,0] op_sel_hi:[1,1,1]
	s_nop 0
	v_pk_fma_f32 v[50:51], v[108:109], v[154:155], v[50:51] op_sel:[0,0,0] op_sel_hi:[1,0,1]
	s_nop 0
	v_pk_fma_f32 v[50:51], v[110:111], v[154:155], v[50:51] op_sel:[0,1,0] op_sel_hi:[1,1,1]
	s_nop 0
	s_waitcnt lgkmcnt(9)
	ds_read_b128 v[168:171], v44 offset:3328
	ds_read_b128 v[172:175], v44 offset:3344
	ds_read_b128 v[176:179], v44 offset:3840
	ds_read_b128 v[180:183], v44 offset:3856
	ds_read_b128 v[184:187], v44 offset:4096
	ds_read_b128 v[188:191], v44 offset:4112
	ds_read_b64 v[192:193], v46 offset:3072
	ds_read_b128 v[148:151], v44 offset:5120
	ds_read_b128 v[152:155], v44 offset:5136
	v_add_f32_dpp v50, v50, v50 quad_perm:[1,0,3,2] row_mask:0xf bank_mask:0xf bound_ctrl:1
	v_add_f32_dpp v51, v51, v51 quad_perm:[1,0,3,2] row_mask:0xf bank_mask:0xf bound_ctrl:1
	v_pk_fma_f32 v[96:97], v[144:145], v[120:121], v[96:97] op_sel:[0,0,0] op_sel_hi:[1,0,1]
	v_pk_fma_f32 v[98:99], v[144:145], v[120:121], v[98:99] op_sel:[0,1,0] op_sel_hi:[1,1,1]
	v_pk_fma_f32 v[100:101], v[144:145], v[122:123], v[100:101] op_sel:[0,0,0] op_sel_hi:[1,0,1]
	v_add_f32_dpp v50, v50, v50 quad_perm:[2,3,0,1] row_mask:0xf bank_mask:0xf bound_ctrl:1
	v_add_f32_dpp v51, v51, v51 quad_perm:[2,3,0,1] row_mask:0xf bank_mask:0xf bound_ctrl:1
	v_pk_fma_f32 v[102:103], v[144:145], v[122:123], v[102:103] op_sel:[0,1,0] op_sel_hi:[1,1,1]
	v_pk_fma_f32 v[104:105], v[144:145], v[124:125], v[104:105] op_sel:[0,0,0] op_sel_hi:[1,0,1]
	v_pk_fma_f32 v[106:107], v[144:145], v[124:125], v[106:107] op_sel:[0,1,0] op_sel_hi:[1,1,1]
	v_add_f32_dpp v50, v50, v50 row_half_mirror row_mask:0xf bank_mask:0xf bound_ctrl:1
	v_add_f32_dpp v51, v51, v51 row_half_mirror row_mask:0xf bank_mask:0xf bound_ctrl:1
	v_pk_fma_f32 v[108:109], v[144:145], v[126:127], v[108:109] op_sel:[0,0,0] op_sel_hi:[1,0,1]
	v_pk_fma_f32 v[110:111], v[144:145], v[126:127], v[110:111] op_sel:[0,1,0] op_sel_hi:[1,1,1]
	s_nop 0
	v_pk_fma_f32 v[96:97], v[50:51], v[128:129], v[96:97] op_sel:[0,0,0] op_sel_hi:[1,0,1]
	v_pk_fma_f32 v[98:99], v[50:51], v[128:129], v[98:99] op_sel:[0,1,0] op_sel_hi:[1,1,1]
	v_pk_fma_f32 v[100:101], v[50:51], v[130:131], v[100:101] op_sel:[0,0,0] op_sel_hi:[1,0,1]
	v_pk_fma_f32 v[102:103], v[50:51], v[130:131], v[102:103] op_sel:[0,1,0] op_sel_hi:[1,1,1]
	v_pk_fma_f32 v[104:105], v[50:51], v[132:133], v[104:105] op_sel:[0,0,0] op_sel_hi:[1,0,1]
	v_pk_fma_f32 v[106:107], v[50:51], v[132:133], v[106:107] op_sel:[0,1,0] op_sel_hi:[1,1,1]
	v_pk_fma_f32 v[108:109], v[50:51], v[134:135], v[108:109] op_sel:[0,0,0] op_sel_hi:[1,0,1]
	v_pk_fma_f32 v[110:111], v[50:51], v[134:135], v[110:111] op_sel:[0,1,0] op_sel_hi:[1,1,1]
	v_pk_mul_f32 v[48:49], v[96:97], v[136:137] op_sel:[0,0] op_sel_hi:[1,0]
	v_pk_mul_f32 v[50:51], v[96:97], v[156:157] op_sel:[0,0] op_sel_hi:[1,0]
	v_pk_fma_f32 v[48:49], v[98:99], v[136:137], v[48:49] op_sel:[0,1,0] op_sel_hi:[1,1,1]
	v_pk_fma_f32 v[50:51], v[98:99], v[156:157], v[50:51] op_sel:[0,1,0] op_sel_hi:[1,1,1]
	v_pk_fma_f32 v[48:49], v[100:101], v[138:139], v[48:49] op_sel:[0,0,0] op_sel_hi:[1,0,1]
	v_pk_fma_f32 v[50:51], v[100:101], v[158:159], v[50:51] op_sel:[0,0,0] op_sel_hi:[1,0,1]
	v_pk_fma_f32 v[48:49], v[102:103], v[138:139], v[48:49] op_sel:[0,1,0] op_sel_hi:[1,1,1]
	v_pk_fma_f32 v[50:51], v[102:103], v[158:159], v[50:51] op_sel:[0,1,0] op_sel_hi:[1,1,1]
	v_pk_fma_f32 v[48:49], v[104:105], v[140:141], v[48:49] op_sel:[0,0,0] op_sel_hi:[1,0,1]
	v_pk_fma_f32 v[50:51], v[104:105], v[160:161], v[50:51] op_sel:[0,0,0] op_sel_hi:[1,0,1]
	v_pk_fma_f32 v[48:49], v[106:107], v[140:141], v[48:49] op_sel:[0,1,0] op_sel_hi:[1,1,1]
	v_pk_fma_f32 v[50:51], v[106:107], v[160:161], v[50:51] op_sel:[0,1,0] op_sel_hi:[1,1,1]
	v_pk_fma_f32 v[48:49], v[108:109], v[142:143], v[48:49] op_sel:[0,0,0] op_sel_hi:[1,0,1]
	v_pk_fma_f32 v[50:51], v[108:109], v[162:163], v[50:51] op_sel:[0,0,0] op_sel_hi:[1,0,1]
	v_pk_fma_f32 v[48:49], v[110:111], v[142:143], v[48:49] op_sel:[0,1,0] op_sel_hi:[1,1,1]
	v_pk_fma_f32 v[50:51], v[110:111], v[162:163], v[50:51] op_sel:[0,1,0] op_sel_hi:[1,1,1]
	s_waitcnt lgkmcnt(9)
; #define LAS __attribute__((address_space(3)))
; __device__ __forceinline__ float red8(float x) { x += dpp_mov<0xB1>(x); x += dpp_mov<0x4E>(x); x += dpp_mov<0x141>(x); return x; }
; __device__ __forceinline__ void scan_phase(const KP& P, LAS unsigned char* lds, const int tid, const int bx, const int G) {
;     ...
;             for (int s = 0; s < 32; ++s) {
;                 const LAS float* p = cb + s * 384;
;                 const f32x4 w0 = *(const LAS f32x4*)(p), w1 = *(const LAS f32x4*)(p + 4);
;                 const f32x4 k0 = *(const LAS f32x4*)(p + 64), k1 = *(const LAS f32x4*)(p + 68);
;                 const f32x4 a0 = *(const LAS f32x4*)(p + 128), a1 = *(const LAS f32x4*)(p + 132);
;                 const f32x4 b0 = *(const LAS f32x4*)(p + 192), b1 = *(const LAS f32x4*)(p + 196);
;                 const f32x4 r0 = *(const LAS f32x4*)(p + 256), r1 = *(const LAS f32x4*)(p + 260);
;                 const float vv = buf[(c & 1) * 12288 + s * 384 + 320 + v];
;                 f32x2 sa2 = S[0] * (f32x2){a0.x, a0.y};
;                 sa2 += S[1] * (f32x2){a0.z, a0.w}; sa2 += S[2] * (f32x2){a1.x, a1.y}; sa2 += S[3] * (f32x2){a1.z, a1.w};
;                 const float sa = red8(sa2.x + sa2.y);
;                 const f32x2 sav = {sa, sa}, vv2 = {vv, vv};
;                 S[0] = S[0] * (f32x2){w0.x, w0.y} + sav * (f32x2){b0.x, b0.y} + vv2 * (f32x2){k0.x, k0.y};
;                 S[1] = S[1] * (f32x2){w0.z, w0.w} + sav * (f32x2){b0.z, b0.w} + vv2 * (f32x2){k0.z, k0.w};
;                 S[2] = S[2] * (f32x2){w1.x, w1.y} + sav * (f32x2){b1.x, b1.y} + vv2 * (f32x2){k1.x, k1.y};
;                 S[3] = S[3] * (f32x2){w1.z, w1.w} + sav * (f32x2){b1.z, b1.w} + vv2 * (f32x2){k1.z, k1.w};
;                 f32x2 y2 = S[0] * (f32x2){r0.x, r0.y};
;                 y2 += S[1] * (f32x2){r0.z, r0.w}; y2 += S[2] * (f32x2){r1.x, r1.y}; y2 += S[3] * (f32x2){r1.z, r1.w};
;                 const float y = red8(y2.x + y2.y);
;                 if (kc == 0) ybuf[s * 64 + v] = y;
	ds_read_b128 v[120:123], v44 offset:4864
	ds_read_b128 v[124:127], v44 offset:4880
	ds_read_b128 v[128:131], v44 offset:5376
	ds_read_b128 v[132:135], v44 offset:5392
	ds_read_b128 v[136:139], v44 offset:5632
	ds_read_b128 v[140:143], v44 offset:5648
	ds_read_b64 v[144:145], v46 offset:4608
	ds_read_b128 v[156:159], v44 offset:6656
	ds_read_b128 v[160:163], v44 offset:6672
	v_add_f32_dpp v48, v48, v48 quad_perm:[1,0,3,2] row_mask:0xf bank_mask:0xf bound_ctrl:1
	v_add_f32_dpp v49, v49, v49 quad_perm:[1,0,3,2] row_mask:0xf bank_mask:0xf bound_ctrl:1
	v_add_f32_dpp v50, v50, v50 quad_perm:[1,0,3,2] row_mask:0xf bank_mask:0xf bound_ctrl:1
	v_add_f32_dpp v51, v51, v51 quad_perm:[1,0,3,2] row_mask:0xf bank_mask:0xf bound_ctrl:1
	v_pk_fma_f32 v[96:97], v[146:147], v[70:71], v[96:97] op_sel:[0,0,0] op_sel_hi:[1,0,1]
	v_pk_fma_f32 v[98:99], v[146:147], v[70:71], v[98:99] op_sel:[0,1,0] op_sel_hi:[1,1,1]
	v_pk_fma_f32 v[100:101], v[146:147], v[72:73], v[100:101] op_sel:[0,0,0] op_sel_hi:[1,0,1]
	v_add_f32_dpp v48, v48, v48 quad_perm:[2,3,0,1] row_mask:0xf bank_mask:0xf bound_ctrl:1
	v_add_f32_dpp v49, v49, v49 quad_perm:[2,3,0,1] row_mask:0xf bank_mask:0xf bound_ctrl:1
	v_add_f32_dpp v50, v50, v50 quad_perm:[2,3,0,1] row_mask:0xf bank_mask:0xf bound_ctrl:1
	v_add_f32_dpp v51, v51, v51 quad_perm:[2,3,0,1] row_mask:0xf bank_mask:0xf bound_ctrl:1
	v_pk_fma_f32 v[102:103], v[146:147], v[72:73], v[102:103] op_sel:[0,1,0] op_sel_hi:[1,1,1]
	v_pk_fma_f32 v[104:105], v[146:147], v[74:75], v[104:105] op_sel:[0,0,0] op_sel_hi:[1,0,1]
	v_pk_fma_f32 v[106:107], v[146:147], v[74:75], v[106:107] op_sel:[0,1,0] op_sel_hi:[1,1,1]
	v_add_f32_dpp v50, v50, v50 row_half_mirror row_mask:0xf bank_mask:0xf bound_ctrl:1
	v_add_f32_dpp v51, v51, v51 row_half_mirror row_mask:0xf bank_mask:0xf bound_ctrl:1
	v_pk_fma_f32 v[108:109], v[146:147], v[76:77], v[108:109] op_sel:[0,0,0] op_sel_hi:[1,0,1]
	s_mov_b64 exec, s[86:87]
	ds_write_b64 v45, v[48:49] offset:0
	s_mov_b64 exec, s[0:1]
	v_pk_fma_f32 v[110:111], v[146:147], v[76:77], v[110:111] op_sel:[0,1,0] op_sel_hi:[1,1,1]
	s_nop 0
	v_pk_fma_f32 v[96:97], v[50:51], v[78:79], v[96:97] op_sel:[0,0,0] op_sel_hi:[1,0,1]
	v_pk_fma_f32 v[98:99], v[50:51], v[78:79], v[98:99] op_sel:[0,1,0] op_sel_hi:[1,1,1]
	v_pk_fma_f32 v[100:101], v[50:51], v[80:81], v[100:101] op_sel:[0,0,0] op_sel_hi:[1,0,1]
	v_pk_fma_f32 v[102:103], v[50:51], v[80:81], v[102:103] op_sel:[0,1,0] op_sel_hi:[1,1,1]
	v_pk_fma_f32 v[104:105], v[50:51], v[82:83], v[104:105] op_sel:[0,0,0] op_sel_hi:[1,0,1]
	v_pk_fma_f32 v[106:107], v[50:51], v[82:83], v[106:107] op_sel:[0,1,0] op_sel_hi:[1,1,1]
	v_pk_fma_f32 v[108:109], v[50:51], v[84:85], v[108:109] op_sel:[0,0,0] op_sel_hi:[1,0,1]
	v_pk_fma_f32 v[110:111], v[50:51], v[84:85], v[110:111] op_sel:[0,1,0] op_sel_hi:[1,1,1]
	v_pk_mul_f32 v[48:49], v[96:97], v[86:87] op_sel:[0,0] op_sel_hi:[1,0]
	v_pk_mul_f32 v[50:51], v[96:97], v[62:63] op_sel:[0,0] op_sel_hi:[1,0]
	v_pk_fma_f32 v[48:49], v[98:99], v[86:87], v[48:49] op_sel:[0,1,0] op_sel_hi:[1,1,1]
	v_pk_fma_f32 v[50:51], v[98:99], v[62:63], v[50:51] op_sel:[0,1,0] op_sel_hi:[1,1,1]
	v_pk_fma_f32 v[48:49], v[100:101], v[88:89], v[48:49] op_sel:[0,0,0] op_sel_hi:[1,0,1]
	v_pk_fma_f32 v[50:51], v[100:101], v[64:65], v[50:51] op_sel:[0,0,0] op_sel_hi:[1,0,1]
	v_pk_fma_f32 v[48:49], v[102:103], v[88:89], v[48:49] op_sel:[0,1,0] op_sel_hi:[1,1,1]
	v_pk_fma_f32 v[50:51], v[102:103], v[64:65], v[50:51] op_sel:[0,1,0] op_sel_hi:[1,1,1]
	v_pk_fma_f32 v[48:49], v[104:105], v[90:91], v[48:49] op_sel:[0,0,0] op_sel_hi:[1,0,1]
	v_pk_fma_f32 v[50:51], v[104:105], v[66:67], v[50:51] op_sel:[0,0,0] op_sel_hi:[1,0,1]
	v_pk_fma_f32 v[48:49], v[106:107], v[90:91], v[48:49] op_sel:[0,1,0] op_sel_hi:[1,1,1]
	v_pk_fma_f32 v[50:51], v[106:107], v[66:67], v[50:51] op_sel:[0,1,0] op_sel_hi:[1,1,1]
	v_pk_fma_f32 v[48:49], v[108:109], v[92:93], v[48:49] op_sel:[0,0,0] op_sel_hi:[1,0,1]
	v_pk_fma_f32 v[50:51], v[108:109], v[68:69], v[50:51] op_sel:[0,0,0] op_sel_hi:[1,0,1]
	v_pk_fma_f32 v[48:49], v[110:111], v[92:93], v[48:49] op_sel:[0,1,0] op_sel_hi:[1,1,1]
	v_pk_fma_f32 v[50:51], v[110:111], v[68:69], v[50:51] op_sel:[0,1,0] op_sel_hi:[1,1,1]
	s_waitcnt lgkmcnt(10)
	ds_read_b128 v[70:73], v44 offset:6400
	ds_read_b128 v[74:77], v44 offset:6416
	ds_read_b128 v[78:81], v44 offset:6912
	ds_read_b128 v[82:85], v44 offset:6928
	ds_read_b128 v[86:89], v44 offset:7168
	ds_read_b128 v[90:93], v44 offset:7184
	ds_read_b64 v[146:147], v46 offset:6144
	ds_read_b128 v[62:65], v44 offset:8192
	ds_read_b128 v[66:69], v44 offset:8208
	v_add_f32_dpp v48, v48, v48 quad_perm:[1,0,3,2] row_mask:0xf bank_mask:0xf bound_ctrl:1
	v_add_f32_dpp v49, v49, v49 quad_perm:[1,0,3,2] row_mask:0xf bank_mask:0xf bound_ctrl:1
	v_add_f32_dpp v50, v50, v50 quad_perm:[1,0,3,2] row_mask:0xf bank_mask:0xf bound_ctrl:1
	v_add_f32_dpp v51, v51, v51 quad_perm:[1,0,3,2] row_mask:0xf bank_mask:0xf bound_ctrl:1
	v_pk_fma_f32 v[96:97], v[192:193], v[168:169], v[96:97] op_sel:[0,0,0] op_sel_hi:[1,0,1]
	v_pk_fma_f32 v[98:99], v[192:193], v[168:169], v[98:99] op_sel:[0,1,0] op_sel_hi:[1,1,1]
	v_pk_fma_f32 v[100:101], v[192:193], v[170:171], v[100:101] op_sel:[0,0,0] op_sel_hi:[1,0,1]
	v_add_f32_dpp v48, v48, v48 quad_perm:[2,3,0,1] row_mask:0xf bank_mask:0xf bound_ctrl:1
	v_add_f32_dpp v49, v49, v49 quad_perm:[2,3,0,1] row_mask:0xf bank_mask:0xf bound_ctrl:1
	v_add_f32_dpp v50, v50, v50 quad_perm:[2,3,0,1] row_mask:0xf bank_mask:0xf bound_ctrl:1
	v_add_f32_dpp v51, v51, v51 quad_perm:[2,3,0,1] row_mask:0xf bank_mask:0xf bound_ctrl:1
	v_pk_fma_f32 v[102:103], v[192:193], v[170:171], v[102:103] op_sel:[0,1,0] op_sel_hi:[1,1,1]
; #define LAS __attribute__((address_space(3)))
; __device__ __forceinline__ float red8(float x) { x += dpp_mov<0xB1>(x); x += dpp_mov<0x4E>(x); x += dpp_mov<0x141>(x); return x; }
; __device__ __forceinline__ void scan_phase(const KP& P, LAS unsigned char* lds, const int tid, const int bx, const int G) {
;     ...
;             for (int s = 0; s < 32; ++s) {
;                 const LAS float* p = cb + s * 384;
;                 const f32x4 w0 = *(const LAS f32x4*)(p), w1 = *(const LAS f32x4*)(p + 4);
;                 const f32x4 k0 = *(const LAS f32x4*)(p + 64), k1 = *(const LAS f32x4*)(p + 68);
;                 const f32x4 a0 = *(const LAS f32x4*)(p + 128), a1 = *(const LAS f32x4*)(p + 132);
;                 const f32x4 b0 = *(const LAS f32x4*)(p + 192), b1 = *(const LAS f32x4*)(p + 196);
;                 const f32x4 r0 = *(const LAS f32x4*)(p + 256), r1 = *(const LAS f32x4*)(p + 260);
;                 const float vv = buf[(c & 1) * 12288 + s * 384 + 320 + v];
;                 f32x2 sa2 = S[0] * (f32x2){a0.x, a0.y};
;                 sa2 += S[1] * (f32x2){a0.z, a0.w}; sa2 += S[2] * (f32x2){a1.x, a1.y}; sa2 += S[3] * (f32x2){a1.z, a1.w};
;                 const float sa = red8(sa2.x + sa2.y);
;                 const f32x2 sav = {sa, sa}, vv2 = {vv, vv};
;                 S[0] = S[0] * (f32x2){w0.x, w0.y} + sav * (f32x2){b0.x, b0.y} + vv2 * (f32x2){k0.x, k0.y};
;                 S[1] = S[1] * (f32x2){w0.z, w0.w} + sav * (f32x2){b0.z, b0.w} + vv2 * (f32x2){k0.z, k0.w};
;                 S[2] = S[2] * (f32x2){w1.x, w1.y} + sav * (f32x2){b1.x, b1.y} + vv2 * (f32x2){k1.x, k1.y};
;                 S[3] = S[3] * (f32x2){w1.z, w1.w} + sav * (f32x2){b1.z, b1.w} + vv2 * (f32x2){k1.z, k1.w};
;                 f32x2 y2 = S[0] * (f32x2){r0.x, r0.y};
;                 y2 += S[1] * (f32x2){r0.z, r0.w}; y2 += S[2] * (f32x2){r1.x, r1.y}; y2 += S[3] * (f32x2){r1.z, r1.w};
;                 const float y = red8(y2.x + y2.y);
;                 if (kc == 0) ybuf[s * 64 + v] = y;
	v_pk_fma_f32 v[104:105], v[192:193], v[172:173], v[104:105] op_sel:[0,0,0] op_sel_hi:[1,0,1]
	v_pk_fma_f32 v[106:107], v[192:193], v[172:173], v[106:107] op_sel:[0,1,0] op_sel_hi:[1,1,1]
	v_add_f32_dpp v50, v50, v50 row_half_mirror row_mask:0xf bank_mask:0xf bound_ctrl:1
	v_add_f32_dpp v51, v51, v51 row_half_mirror row_mask:0xf bank_mask:0xf bound_ctrl:1
	v_pk_fma_f32 v[108:109], v[192:193], v[174:175], v[108:109] op_sel:[0,0,0] op_sel_hi:[1,0,1]
	s_mov_b64 exec, s[86:87]
	ds_write_b64 v45, v[48:49] offset:512
	s_mov_b64 exec, s[0:1]
	v_pk_fma_f32 v[110:111], v[192:193], v[174:175], v[110:111] op_sel:[0,1,0] op_sel_hi:[1,1,1]
	s_nop 0
	v_pk_fma_f32 v[96:97], v[50:51], v[176:177], v[96:97] op_sel:[0,0,0] op_sel_hi:[1,0,1]
	v_pk_fma_f32 v[98:99], v[50:51], v[176:177], v[98:99] op_sel:[0,1,0] op_sel_hi:[1,1,1]
	v_pk_fma_f32 v[100:101], v[50:51], v[178:179], v[100:101] op_sel:[0,0,0] op_sel_hi:[1,0,1]
	v_pk_fma_f32 v[102:103], v[50:51], v[178:179], v[102:103] op_sel:[0,1,0] op_sel_hi:[1,1,1]
	v_pk_fma_f32 v[104:105], v[50:51], v[180:181], v[104:105] op_sel:[0,0,0] op_sel_hi:[1,0,1]
	v_pk_fma_f32 v[106:107], v[50:51], v[180:181], v[106:107] op_sel:[0,1,0] op_sel_hi:[1,1,1]
	v_pk_fma_f32 v[108:109], v[50:51], v[182:183], v[108:109] op_sel:[0,0,0] op_sel_hi:[1,0,1]
	v_pk_fma_f32 v[110:111], v[50:51], v[182:183], v[110:111] op_sel:[0,1,0] op_sel_hi:[1,1,1]
	v_pk_mul_f32 v[48:49], v[96:97], v[184:185] op_sel:[0,0] op_sel_hi:[1,0]
	v_pk_mul_f32 v[50:51], v[96:97], v[148:149] op_sel:[0,0] op_sel_hi:[1,0]
	v_pk_fma_f32 v[48:49], v[98:99], v[184:185], v[48:49] op_sel:[0,1,0] op_sel_hi:[1,1,1]
	v_pk_fma_f32 v[50:51], v[98:99], v[148:149], v[50:51] op_sel:[0,1,0] op_sel_hi:[1,1,1]
	v_pk_fma_f32 v[48:49], v[100:101], v[186:187], v[48:49] op_sel:[0,0,0] op_sel_hi:[1,0,1]
	v_pk_fma_f32 v[50:51], v[100:101], v[150:151], v[50:51] op_sel:[0,0,0] op_sel_hi:[1,0,1]
	v_pk_fma_f32 v[48:49], v[102:103], v[186:187], v[48:49] op_sel:[0,1,0] op_sel_hi:[1,1,1]
	v_pk_fma_f32 v[50:51], v[102:103], v[150:151], v[50:51] op_sel:[0,1,0] op_sel_hi:[1,1,1]
	v_pk_fma_f32 v[48:49], v[104:105], v[188:189], v[48:49] op_sel:[0,0,0] op_sel_hi:[1,0,1]
	v_pk_fma_f32 v[50:51], v[104:105], v[152:153], v[50:51] op_sel:[0,0,0] op_sel_hi:[1,0,1]
	v_pk_fma_f32 v[48:49], v[106:107], v[188:189], v[48:49] op_sel:[0,1,0] op_sel_hi:[1,1,1]
	v_pk_fma_f32 v[50:51], v[106:107], v[152:153], v[50:51] op_sel:[0,1,0] op_sel_hi:[1,1,1]
	v_pk_fma_f32 v[48:49], v[108:109], v[190:191], v[48:49] op_sel:[0,0,0] op_sel_hi:[1,0,1]
	v_pk_fma_f32 v[50:51], v[108:109], v[154:155], v[50:51] op_sel:[0,0,0] op_sel_hi:[1,0,1]
	v_pk_fma_f32 v[48:49], v[110:111], v[190:191], v[48:49] op_sel:[0,1,0] op_sel_hi:[1,1,1]
	v_pk_fma_f32 v[50:51], v[110:111], v[154:155], v[50:51] op_sel:[0,1,0] op_sel_hi:[1,1,1]
	s_waitcnt lgkmcnt(11)
	ds_read_b128 v[168:171], v44 offset:7936
	ds_read_b128 v[172:175], v44 offset:7952
	ds_read_b128 v[176:179], v44 offset:8448
	ds_read_b128 v[180:183], v44 offset:8464
	ds_read_b128 v[184:187], v44 offset:8704
	ds_read_b128 v[188:191], v44 offset:8720
	ds_read_b64 v[192:193], v46 offset:7680
	ds_read_b128 v[148:151], v44 offset:9728
	ds_read_b128 v[152:155], v44 offset:9744
	v_add_f32_dpp v48, v48, v48 quad_perm:[1,0,3,2] row_mask:0xf bank_mask:0xf bound_ctrl:1
	v_add_f32_dpp v49, v49, v49 quad_perm:[1,0,3,2] row_mask:0xf bank_mask:0xf bound_ctrl:1
	v_add_f32_dpp v50, v50, v50 quad_perm:[1,0,3,2] row_mask:0xf bank_mask:0xf bound_ctrl:1
	v_add_f32_dpp v51, v51, v51 quad_perm:[1,0,3,2] row_mask:0xf bank_mask:0xf bound_ctrl:1
	v_pk_fma_f32 v[96:97], v[144:145], v[120:121], v[96:97] op_sel:[0,0,0] op_sel_hi:[1,0,1]
	v_pk_fma_f32 v[98:99], v[144:145], v[120:121], v[98:99] op_sel:[0,1,0] op_sel_hi:[1,1,1]
	v_pk_fma_f32 v[100:101], v[144:145], v[122:123], v[100:101] op_sel:[0,0,0] op_sel_hi:[1,0,1]
	v_add_f32_dpp v48, v48, v48 quad_perm:[2,3,0,1] row_mask:0xf bank_mask:0xf bound_ctrl:1
	v_add_f32_dpp v49, v49, v49 quad_perm:[2,3,0,1] row_mask:0xf bank_mask:0xf bound_ctrl:1
	v_add_f32_dpp v50, v50, v50 quad_perm:[2,3,0,1] row_mask:0xf bank_mask:0xf bound_ctrl:1
	v_add_f32_dpp v51, v51, v51 quad_perm:[2,3,0,1] row_mask:0xf bank_mask:0xf bound_ctrl:1
	v_pk_fma_f32 v[102:103], v[144:145], v[122:123], v[102:103] op_sel:[0,1,0] op_sel_hi:[1,1,1]
	v_pk_fma_f32 v[104:105], v[144:145], v[124:125], v[104:105] op_sel:[0,0,0] op_sel_hi:[1,0,1]
	v_pk_fma_f32 v[106:107], v[144:145], v[124:125], v[106:107] op_sel:[0,1,0] op_sel_hi:[1,1,1]
	v_add_f32_dpp v50, v50, v50 row_half_mirror row_mask:0xf bank_mask:0xf bound_ctrl:1
	v_add_f32_dpp v51, v51, v51 row_half_mirror row_mask:0xf bank_mask:0xf bound_ctrl:1
	v_pk_fma_f32 v[108:109], v[144:145], v[126:127], v[108:109] op_sel:[0,0,0] op_sel_hi:[1,0,1]
	s_mov_b64 exec, s[86:87]
	ds_write_b64 v45, v[48:49] offset:1024
	s_mov_b64 exec, s[0:1]
	v_pk_fma_f32 v[110:111], v[144:145], v[126:127], v[110:111] op_sel:[0,1,0] op_sel_hi:[1,1,1]
	s_nop 0
	v_pk_fma_f32 v[96:97], v[50:51], v[128:129], v[96:97] op_sel:[0,0,0] op_sel_hi:[1,0,1]
	v_pk_fma_f32 v[98:99], v[50:51], v[128:129], v[98:99] op_sel:[0,1,0] op_sel_hi:[1,1,1]
	v_pk_fma_f32 v[100:101], v[50:51], v[130:131], v[100:101] op_sel:[0,0,0] op_sel_hi:[1,0,1]
	v_pk_fma_f32 v[102:103], v[50:51], v[130:131], v[102:103] op_sel:[0,1,0] op_sel_hi:[1,1,1]
	v_pk_fma_f32 v[104:105], v[50:51], v[132:133], v[104:105] op_sel:[0,0,0] op_sel_hi:[1,0,1]
	v_pk_fma_f32 v[106:107], v[50:51], v[132:133], v[106:107] op_sel:[0,1,0] op_sel_hi:[1,1,1]
	v_pk_fma_f32 v[108:109], v[50:51], v[134:135], v[108:109] op_sel:[0,0,0] op_sel_hi:[1,0,1]
	v_pk_fma_f32 v[110:111], v[50:51], v[134:135], v[110:111] op_sel:[0,1,0] op_sel_hi:[1,1,1]
; #define LAS __attribute__((address_space(3)))
; __device__ __forceinline__ float red8(float x) { x += dpp_mov<0xB1>(x); x += dpp_mov<0x4E>(x); x += dpp_mov<0x141>(x); return x; }
; __device__ __forceinline__ void scan_phase(const KP& P, LAS unsigned char* lds, const int tid, const int bx, const int G) {
;     ...
;             for (int s = 0; s < 32; ++s) {
;                 const LAS float* p = cb + s * 384;
;                 const f32x4 w0 = *(const LAS f32x4*)(p), w1 = *(const LAS f32x4*)(p + 4);
;                 const f32x4 k0 = *(const LAS f32x4*)(p + 64), k1 = *(const LAS f32x4*)(p + 68);
;                 const f32x4 a0 = *(const LAS f32x4*)(p + 128), a1 = *(const LAS f32x4*)(p + 132);
;                 const f32x4 b0 = *(const LAS f32x4*)(p + 192), b1 = *(const LAS f32x4*)(p + 196);
;                 const f32x4 r0 = *(const LAS f32x4*)(p + 256), r1 = *(const LAS f32x4*)(p + 260);
;                 const float vv = buf[(c & 1) * 12288 + s * 384 + 320 + v];
;                 f32x2 sa2 = S[0] * (f32x2){a0.x, a0.y};
;                 sa2 += S[1] * (f32x2){a0.z, a0.w}; sa2 += S[2] * (f32x2){a1.x, a1.y}; sa2 += S[3] * (f32x2){a1.z, a1.w};
;                 const float sa = red8(sa2.x + sa2.y);
;                 const f32x2 sav = {sa, sa}, vv2 = {vv, vv};
;                 S[0] = S[0] * (f32x2){w0.x, w0.y} + sav * (f32x2){b0.x, b0.y} + vv2 * (f32x2){k0.x, k0.y};
;                 S[1] = S[1] * (f32x2){w0.z, w0.w} + sav * (f32x2){b0.z, b0.w} + vv2 * (f32x2){k0.z, k0.w};
;                 S[2] = S[2] * (f32x2){w1.x, w1.y} + sav * (f32x2){b1.x, b1.y} + vv2 * (f32x2){k1.x, k1.y};
;                 S[3] = S[3] * (f32x2){w1.z, w1.w} + sav * (f32x2){b1.z, b1.w} + vv2 * (f32x2){k1.z, k1.w};
;                 f32x2 y2 = S[0] * (f32x2){r0.x, r0.y};
;                 y2 += S[1] * (f32x2){r0.z, r0.w}; y2 += S[2] * (f32x2){r1.x, r1.y}; y2 += S[3] * (f32x2){r1.z, r1.w};
;                 const float y = red8(y2.x + y2.y);
;                 if (kc == 0) ybuf[s * 64 + v] = y;
	v_pk_mul_f32 v[48:49], v[96:97], v[136:137] op_sel:[0,0] op_sel_hi:[1,0]
	v_pk_mul_f32 v[50:51], v[96:97], v[156:157] op_sel:[0,0] op_sel_hi:[1,0]
	v_pk_fma_f32 v[48:49], v[98:99], v[136:137], v[48:49] op_sel:[0,1,0] op_sel_hi:[1,1,1]
	v_pk_fma_f32 v[50:51], v[98:99], v[156:157], v[50:51] op_sel:[0,1,0] op_sel_hi:[1,1,1]
	v_pk_fma_f32 v[48:49], v[100:101], v[138:139], v[48:49] op_sel:[0,0,0] op_sel_hi:[1,0,1]
	v_pk_fma_f32 v[50:51], v[100:101], v[158:159], v[50:51] op_sel:[0,0,0] op_sel_hi:[1,0,1]
	v_pk_fma_f32 v[48:49], v[102:103], v[138:139], v[48:49] op_sel:[0,1,0] op_sel_hi:[1,1,1]
	v_pk_fma_f32 v[50:51], v[102:103], v[158:159], v[50:51] op_sel:[0,1,0] op_sel_hi:[1,1,1]
	v_pk_fma_f32 v[48:49], v[104:105], v[140:141], v[48:49] op_sel:[0,0,0] op_sel_hi:[1,0,1]
	v_pk_fma_f32 v[50:51], v[104:105], v[160:161], v[50:51] op_sel:[0,0,0] op_sel_hi:[1,0,1]
	v_pk_fma_f32 v[48:49], v[106:107], v[140:141], v[48:49] op_sel:[0,1,0] op_sel_hi:[1,1,1]
	v_pk_fma_f32 v[50:51], v[106:107], v[160:161], v[50:51] op_sel:[0,1,0] op_sel_hi:[1,1,1]
	v_pk_fma_f32 v[48:49], v[108:109], v[142:143], v[48:49] op_sel:[0,0,0] op_sel_hi:[1,0,1]
	v_pk_fma_f32 v[50:51], v[108:109], v[162:163], v[50:51] op_sel:[0,0,0] op_sel_hi:[1,0,1]
	v_pk_fma_f32 v[48:49], v[110:111], v[142:143], v[48:49] op_sel:[0,1,0] op_sel_hi:[1,1,1]
	v_pk_fma_f32 v[50:51], v[110:111], v[162:163], v[50:51] op_sel:[0,1,0] op_sel_hi:[1,1,1]
	s_waitcnt lgkmcnt(11)
	ds_read_b128 v[120:123], v44 offset:9472
	ds_read_b128 v[124:127], v44 offset:9488
	ds_read_b128 v[128:131], v44 offset:9984
	ds_read_b128 v[132:135], v44 offset:10000
	ds_read_b128 v[136:139], v44 offset:10240
	ds_read_b128 v[140:143], v44 offset:10256
	ds_read_b64 v[144:145], v46 offset:9216
	ds_read_b128 v[156:159], v44 offset:11264
	ds_read_b128 v[160:163], v44 offset:11280
	v_add_f32_dpp v48, v48, v48 quad_perm:[1,0,3,2] row_mask:0xf bank_mask:0xf bound_ctrl:1
	v_add_f32_dpp v49, v49, v49 quad_perm:[1,0,3,2] row_mask:0xf bank_mask:0xf bound_ctrl:1
	v_add_f32_dpp v50, v50, v50 quad_perm:[1,0,3,2] row_mask:0xf bank_mask:0xf bound_ctrl:1
	v_add_f32_dpp v51, v51, v51 quad_perm:[1,0,3,2] row_mask:0xf bank_mask:0xf bound_ctrl:1
	v_pk_fma_f32 v[96:97], v[146:147], v[70:71], v[96:97] op_sel:[0,0,0] op_sel_hi:[1,0,1]
	v_pk_fma_f32 v[98:99], v[146:147], v[70:71], v[98:99] op_sel:[0,1,0] op_sel_hi:[1,1,1]
	v_pk_fma_f32 v[100:101], v[146:147], v[72:73], v[100:101] op_sel:[0,0,0] op_sel_hi:[1,0,1]
	v_add_f32_dpp v48, v48, v48 quad_perm:[2,3,0,1] row_mask:0xf bank_mask:0xf bound_ctrl:1
	v_add_f32_dpp v49, v49, v49 quad_perm:[2,3,0,1] row_mask:0xf bank_mask:0xf bound_ctrl:1
	v_add_f32_dpp v50, v50, v50 quad_perm:[2,3,0,1] row_mask:0xf bank_mask:0xf bound_ctrl:1
	v_add_f32_dpp v51, v51, v51 quad_perm:[2,3,0,1] row_mask:0xf bank_mask:0xf bound_ctrl:1
	v_pk_fma_f32 v[102:103], v[146:147], v[72:73], v[102:103] op_sel:[0,1,0] op_sel_hi:[1,1,1]
	v_pk_fma_f32 v[104:105], v[146:147], v[74:75], v[104:105] op_sel:[0,0,0] op_sel_hi:[1,0,1]
	v_pk_fma_f32 v[106:107], v[146:147], v[74:75], v[106:107] op_sel:[0,1,0] op_sel_hi:[1,1,1]
	v_add_f32_dpp v50, v50, v50 row_half_mirror row_mask:0xf bank_mask:0xf bound_ctrl:1
	v_add_f32_dpp v51, v51, v51 row_half_mirror row_mask:0xf bank_mask:0xf bound_ctrl:1
	v_pk_fma_f32 v[108:109], v[146:147], v[76:77], v[108:109] op_sel:[0,0,0] op_sel_hi:[1,0,1]
	s_mov_b64 exec, s[86:87]
	ds_write_b64 v45, v[48:49] offset:1536
	s_mov_b64 exec, s[0:1]
	v_pk_fma_f32 v[110:111], v[146:147], v[76:77], v[110:111] op_sel:[0,1,0] op_sel_hi:[1,1,1]
	s_nop 0
	v_pk_fma_f32 v[96:97], v[50:51], v[78:79], v[96:97] op_sel:[0,0,0] op_sel_hi:[1,0,1]
	v_pk_fma_f32 v[98:99], v[50:51], v[78:79], v[98:99] op_sel:[0,1,0] op_sel_hi:[1,1,1]
	v_pk_fma_f32 v[100:101], v[50:51], v[80:81], v[100:101] op_sel:[0,0,0] op_sel_hi:[1,0,1]
	v_pk_fma_f32 v[102:103], v[50:51], v[80:81], v[102:103] op_sel:[0,1,0] op_sel_hi:[1,1,1]
	v_pk_fma_f32 v[104:105], v[50:51], v[82:83], v[104:105] op_sel:[0,0,0] op_sel_hi:[1,0,1]
	v_pk_fma_f32 v[106:107], v[50:51], v[82:83], v[106:107] op_sel:[0,1,0] op_sel_hi:[1,1,1]
	v_pk_fma_f32 v[108:109], v[50:51], v[84:85], v[108:109] op_sel:[0,0,0] op_sel_hi:[1,0,1]
	v_pk_fma_f32 v[110:111], v[50:51], v[84:85], v[110:111] op_sel:[0,1,0] op_sel_hi:[1,1,1]
	v_pk_mul_f32 v[48:49], v[96:97], v[86:87] op_sel:[0,0] op_sel_hi:[1,0]
	v_pk_mul_f32 v[50:51], v[96:97], v[62:63] op_sel:[0,0] op_sel_hi:[1,0]
	v_pk_fma_f32 v[48:49], v[98:99], v[86:87], v[48:49] op_sel:[0,1,0] op_sel_hi:[1,1,1]
	v_pk_fma_f32 v[50:51], v[98:99], v[62:63], v[50:51] op_sel:[0,1,0] op_sel_hi:[1,1,1]
	v_pk_fma_f32 v[48:49], v[100:101], v[88:89], v[48:49] op_sel:[0,0,0] op_sel_hi:[1,0,1]
	v_pk_fma_f32 v[50:51], v[100:101], v[64:65], v[50:51] op_sel:[0,0,0] op_sel_hi:[1,0,1]
	v_pk_fma_f32 v[48:49], v[102:103], v[88:89], v[48:49] op_sel:[0,1,0] op_sel_hi:[1,1,1]
	v_pk_fma_f32 v[50:51], v[102:103], v[64:65], v[50:51] op_sel:[0,1,0] op_sel_hi:[1,1,1]
	v_pk_fma_f32 v[48:49], v[104:105], v[90:91], v[48:49] op_sel:[0,0,0] op_sel_hi:[1,0,1]
	v_pk_fma_f32 v[50:51], v[104:105], v[66:67], v[50:51] op_sel:[0,0,0] op_sel_hi:[1,0,1]
	v_pk_fma_f32 v[48:49], v[106:107], v[90:91], v[48:49] op_sel:[0,1,0] op_sel_hi:[1,1,1]
	v_pk_fma_f32 v[50:51], v[106:107], v[66:67], v[50:51] op_sel:[0,1,0] op_sel_hi:[1,1,1]
	v_pk_fma_f32 v[48:49], v[108:109], v[92:93], v[48:49] op_sel:[0,0,0] op_sel_hi:[1,0,1]
	v_pk_fma_f32 v[50:51], v[108:109], v[68:69], v[50:51] op_sel:[0,0,0] op_sel_hi:[1,0,1]
	v_pk_fma_f32 v[48:49], v[110:111], v[92:93], v[48:49] op_sel:[0,1,0] op_sel_hi:[1,1,1]
	v_pk_fma_f32 v[50:51], v[110:111], v[68:69], v[50:51] op_sel:[0,1,0] op_sel_hi:[1,1,1]
	s_waitcnt lgkmcnt(11)
; #define LAS __attribute__((address_space(3)))
; __device__ __forceinline__ float red8(float x) { x += dpp_mov<0xB1>(x); x += dpp_mov<0x4E>(x); x += dpp_mov<0x141>(x); return x; }
; __device__ __forceinline__ void scan_phase(const KP& P, LAS unsigned char* lds, const int tid, const int bx, const int G) {
;     ...
;             for (int s = 0; s < 32; ++s) {
;                 const LAS float* p = cb + s * 384;
;                 const f32x4 w0 = *(const LAS f32x4*)(p), w1 = *(const LAS f32x4*)(p + 4);
;                 const f32x4 k0 = *(const LAS f32x4*)(p + 64), k1 = *(const LAS f32x4*)(p + 68);
;                 const f32x4 a0 = *(const LAS f32x4*)(p + 128), a1 = *(const LAS f32x4*)(p + 132);
;                 const f32x4 b0 = *(const LAS f32x4*)(p + 192), b1 = *(const LAS f32x4*)(p + 196);
;                 const f32x4 r0 = *(const LAS f32x4*)(p + 256), r1 = *(const LAS f32x4*)(p + 260);
;                 const float vv = buf[(c & 1) * 12288 + s * 384 + 320 + v];
;                 f32x2 sa2 = S[0] * (f32x2){a0.x, a0.y};
;                 sa2 += S[1] * (f32x2){a0.z, a0.w}; sa2 += S[2] * (f32x2){a1.x, a1.y}; sa2 += S[3] * (f32x2){a1.z, a1.w};
;                 const float sa = red8(sa2.x + sa2.y);
;                 const f32x2 sav = {sa, sa}, vv2 = {vv, vv};
;                 S[0] = S[0] * (f32x2){w0.x, w0.y} + sav * (f32x2){b0.x, b0.y} + vv2 * (f32x2){k0.x, k0.y};
;                 S[1] = S[1] * (f32x2){w0.z, w0.w} + sav * (f32x2){b0.z, b0.w} + vv2 * (f32x2){k0.z, k0.w};
;                 S[2] = S[2] * (f32x2){w1.x, w1.y} + sav * (f32x2){b1.x, b1.y} + vv2 * (f32x2){k1.x, k1.y};
;                 S[3] = S[3] * (f32x2){w1.z, w1.w} + sav * (f32x2){b1.z, b1.w} + vv2 * (f32x2){k1.z, k1.w};
;                 f32x2 y2 = S[0] * (f32x2){r0.x, r0.y};
;                 y2 += S[1] * (f32x2){r0.z, r0.w}; y2 += S[2] * (f32x2){r1.x, r1.y}; y2 += S[3] * (f32x2){r1.z, r1.w};
;                 const float y = red8(y2.x + y2.y);
;                 if (kc == 0) ybuf[s * 64 + v] = y;
;             }
	ds_read_b128 v[70:73], v44 offset:11008
	ds_read_b128 v[74:77], v44 offset:11024
	ds_read_b128 v[78:81], v44 offset:11520
	ds_read_b128 v[82:85], v44 offset:11536
	ds_read_b128 v[86:89], v44 offset:11776
	ds_read_b128 v[90:93], v44 offset:11792
	ds_read_b64 v[146:147], v46 offset:10752
	ds_read_b128 v[62:65], v44 offset:12800
	ds_read_b128 v[66:69], v44 offset:12816
	v_add_f32_dpp v48, v48, v48 quad_perm:[1,0,3,2] row_mask:0xf bank_mask:0xf bound_ctrl:1
	v_add_f32_dpp v49, v49, v49 quad_perm:[1,0,3,2] row_mask:0xf bank_mask:0xf bound_ctrl:1
	v_add_f32_dpp v50, v50, v50 quad_perm:[1,0,3,2] row_mask:0xf bank_mask:0xf bound_ctrl:1
	v_add_f32_dpp v51, v51, v51 quad_perm:[1,0,3,2] row_mask:0xf bank_mask:0xf bound_ctrl:1
	v_pk_fma_f32 v[96:97], v[192:193], v[168:169], v[96:97] op_sel:[0,0,0] op_sel_hi:[1,0,1]
	v_pk_fma_f32 v[98:99], v[192:193], v[168:169], v[98:99] op_sel:[0,1,0] op_sel_hi:[1,1,1]
	v_pk_fma_f32 v[100:101], v[192:193], v[170:171], v[100:101] op_sel:[0,0,0] op_sel_hi:[1,0,1]
	v_add_f32_dpp v48, v48, v48 quad_perm:[2,3,0,1] row_mask:0xf bank_mask:0xf bound_ctrl:1
	v_add_f32_dpp v49, v49, v49 quad_perm:[2,3,0,1] row_mask:0xf bank_mask:0xf bound_ctrl:1
	v_add_f32_dpp v50, v50, v50 quad_perm:[2,3,0,1] row_mask:0xf bank_mask:0xf bound_ctrl:1
	v_add_f32_dpp v51, v51, v51 quad_perm:[2,3,0,1] row_mask:0xf bank_mask:0xf bound_ctrl:1
	v_pk_fma_f32 v[102:103], v[192:193], v[170:171], v[102:103] op_sel:[0,1,0] op_sel_hi:[1,1,1]
	v_pk_fma_f32 v[104:105], v[192:193], v[172:173], v[104:105] op_sel:[0,0,0] op_sel_hi:[1,0,1]
	v_pk_fma_f32 v[106:107], v[192:193], v[172:173], v[106:107] op_sel:[0,1,0] op_sel_hi:[1,1,1]
	v_add_f32_dpp v50, v50, v50 row_half_mirror row_mask:0xf bank_mask:0xf bound_ctrl:1
	v_add_f32_dpp v51, v51, v51 row_half_mirror row_mask:0xf bank_mask:0xf bound_ctrl:1
	v_pk_fma_f32 v[108:109], v[192:193], v[174:175], v[108:109] op_sel:[0,0,0] op_sel_hi:[1,0,1]
	s_mov_b64 exec, s[86:87]
	ds_write_b64 v45, v[48:49] offset:2048
	s_mov_b64 exec, s[0:1]
	v_pk_fma_f32 v[110:111], v[192:193], v[174:175], v[110:111] op_sel:[0,1,0] op_sel_hi:[1,1,1]
	s_nop 0
	v_pk_fma_f32 v[96:97], v[50:51], v[176:177], v[96:97] op_sel:[0,0,0] op_sel_hi:[1,0,1]
	v_pk_fma_f32 v[98:99], v[50:51], v[176:177], v[98:99] op_sel:[0,1,0] op_sel_hi:[1,1,1]
	v_pk_fma_f32 v[100:101], v[50:51], v[178:179], v[100:101] op_sel:[0,0,0] op_sel_hi:[1,0,1]
	v_pk_fma_f32 v[102:103], v[50:51], v[178:179], v[102:103] op_sel:[0,1,0] op_sel_hi:[1,1,1]
	v_pk_fma_f32 v[104:105], v[50:51], v[180:181], v[104:105] op_sel:[0,0,0] op_sel_hi:[1,0,1]
	v_pk_fma_f32 v[106:107], v[50:51], v[180:181], v[106:107] op_sel:[0,1,0] op_sel_hi:[1,1,1]
	v_pk_fma_f32 v[108:109], v[50:51], v[182:183], v[108:109] op_sel:[0,0,0] op_sel_hi:[1,0,1]
	v_pk_fma_f32 v[110:111], v[50:51], v[182:183], v[110:111] op_sel:[0,1,0] op_sel_hi:[1,1,1]
	v_pk_mul_f32 v[48:49], v[96:97], v[184:185] op_sel:[0,0] op_sel_hi:[1,0]
	v_pk_mul_f32 v[50:51], v[96:97], v[148:149] op_sel:[0,0] op_sel_hi:[1,0]
	v_pk_fma_f32 v[48:49], v[98:99], v[184:185], v[48:49] op_sel:[0,1,0] op_sel_hi:[1,1,1]
	v_pk_fma_f32 v[50:51], v[98:99], v[148:149], v[50:51] op_sel:[0,1,0] op_sel_hi:[1,1,1]
	v_pk_fma_f32 v[48:49], v[100:101], v[186:187], v[48:49] op_sel:[0,0,0] op_sel_hi:[1,0,1]
	v_pk_fma_f32 v[50:51], v[100:101], v[150:151], v[50:51] op_sel:[0,0,0] op_sel_hi:[1,0,1]
	v_pk_fma_f32 v[48:49], v[102:103], v[186:187], v[48:49] op_sel:[0,1,0] op_sel_hi:[1,1,1]
	v_pk_fma_f32 v[50:51], v[102:103], v[150:151], v[50:51] op_sel:[0,1,0] op_sel_hi:[1,1,1]
	v_pk_fma_f32 v[48:49], v[104:105], v[188:189], v[48:49] op_sel:[0,0,0] op_sel_hi:[1,0,1]
	v_pk_fma_f32 v[50:51], v[104:105], v[152:153], v[50:51] op_sel:[0,0,0] op_sel_hi:[1,0,1]
	v_pk_fma_f32 v[48:49], v[106:107], v[188:189], v[48:49] op_sel:[0,1,0] op_sel_hi:[1,1,1]
	v_pk_fma_f32 v[50:51], v[106:107], v[152:153], v[50:51] op_sel:[0,1,0] op_sel_hi:[1,1,1]
	v_pk_fma_f32 v[48:49], v[108:109], v[190:191], v[48:49] op_sel:[0,0,0] op_sel_hi:[1,0,1]
	v_pk_fma_f32 v[50:51], v[108:109], v[154:155], v[50:51] op_sel:[0,0,0] op_sel_hi:[1,0,1]
	v_pk_fma_f32 v[48:49], v[110:111], v[190:191], v[48:49] op_sel:[0,1,0] op_sel_hi:[1,1,1]
	v_pk_fma_f32 v[50:51], v[110:111], v[154:155], v[50:51] op_sel:[0,1,0] op_sel_hi:[1,1,1]
	s_waitcnt lgkmcnt(11)
; #define LAS __attribute__((address_space(3)))
; __device__ __forceinline__ float red8(float x) { x += dpp_mov<0xB1>(x); x += dpp_mov<0x4E>(x); x += dpp_mov<0x141>(x); return x; }
; __device__ __forceinline__ void scan_phase(const KP& P, LAS unsigned char* lds, const int tid, const int bx, const int G) {
;     ...
;             for (int s = 0; s < 32; ++s) {
;                 const LAS float* p = cb + s * 384;
;                 const f32x4 w0 = *(const LAS f32x4*)(p), w1 = *(const LAS f32x4*)(p + 4);
;                 const f32x4 k0 = *(const LAS f32x4*)(p + 64), k1 = *(const LAS f32x4*)(p + 68);
;                 const f32x4 a0 = *(const LAS f32x4*)(p + 128), a1 = *(const LAS f32x4*)(p + 132);
;                 const f32x4 b0 = *(const LAS f32x4*)(p + 192), b1 = *(const LAS f32x4*)(p + 196);
;                 const f32x4 r0 = *(const LAS f32x4*)(p + 256), r1 = *(const LAS f32x4*)(p + 260);
;                 const float vv = buf[(c & 1) * 12288 + s * 384 + 320 + v];
;                 f32x2 sa2 = S[0] * (f32x2){a0.x, a0.y};
;                 sa2 += S[1] * (f32x2){a0.z, a0.w}; sa2 += S[2] * (f32x2){a1.x, a1.y}; sa2 += S[3] * (f32x2){a1.z, a1.w};
;                 const float sa = red8(sa2.x + sa2.y);
;                 const f32x2 sav = {sa, sa}, vv2 = {vv, vv};
;                 S[0] = S[0] * (f32x2){w0.x, w0.y} + sav * (f32x2){b0.x, b0.y} + vv2 * (f32x2){k0.x, k0.y};
;                 S[1] = S[1] * (f32x2){w0.z, w0.w} + sav * (f32x2){b0.z, b0.w} + vv2 * (f32x2){k0.z, k0.w};
;                 S[2] = S[2] * (f32x2){w1.x, w1.y} + sav * (f32x2){b1.x, b1.y} + vv2 * (f32x2){k1.x, k1.y};
;                 S[3] = S[3] * (f32x2){w1.z, w1.w} + sav * (f32x2){b1.z, b1.w} + vv2 * (f32x2){k1.z, k1.w};
;                 f32x2 y2 = S[0] * (f32x2){r0.x, r0.y};
;                 y2 += S[1] * (f32x2){r0.z, r0.w}; y2 += S[2] * (f32x2){r1.x, r1.y}; y2 += S[3] * (f32x2){r1.z, r1.w};
;                 const float y = red8(y2.x + y2.y);
;                 if (kc == 0) ybuf[s * 64 + v] = y;
;             }
	ds_read_b128 v[168:171], v44 offset:12544
	ds_read_b128 v[172:175], v44 offset:12560
	ds_read_b128 v[176:179], v44 offset:13056
	ds_read_b128 v[180:183], v44 offset:13072
	ds_read_b128 v[184:187], v44 offset:13312
	ds_read_b128 v[188:191], v44 offset:13328
	ds_read_b64 v[192:193], v46 offset:12288
	ds_read_b128 v[148:151], v44 offset:14336
	ds_read_b128 v[152:155], v44 offset:14352
	v_add_f32_dpp v48, v48, v48 quad_perm:[1,0,3,2] row_mask:0xf bank_mask:0xf bound_ctrl:1
	v_add_f32_dpp v49, v49, v49 quad_perm:[1,0,3,2] row_mask:0xf bank_mask:0xf bound_ctrl:1
	v_add_f32_dpp v50, v50, v50 quad_perm:[1,0,3,2] row_mask:0xf bank_mask:0xf bound_ctrl:1
	v_add_f32_dpp v51, v51, v51 quad_perm:[1,0,3,2] row_mask:0xf bank_mask:0xf bound_ctrl:1
	v_pk_fma_f32 v[96:97], v[144:145], v[120:121], v[96:97] op_sel:[0,0,0] op_sel_hi:[1,0,1]
	v_pk_fma_f32 v[98:99], v[144:145], v[120:121], v[98:99] op_sel:[0,1,0] op_sel_hi:[1,1,1]
	v_pk_fma_f32 v[100:101], v[144:145], v[122:123], v[100:101] op_sel:[0,0,0] op_sel_hi:[1,0,1]
	v_add_f32_dpp v48, v48, v48 quad_perm:[2,3,0,1] row_mask:0xf bank_mask:0xf bound_ctrl:1
	v_add_f32_dpp v49, v49, v49 quad_perm:[2,3,0,1] row_mask:0xf bank_mask:0xf bound_ctrl:1
	v_add_f32_dpp v50, v50, v50 quad_perm:[2,3,0,1] row_mask:0xf bank_mask:0xf bound_ctrl:1
	v_add_f32_dpp v51, v51, v51 quad_perm:[2,3,0,1] row_mask:0xf bank_mask:0xf bound_ctrl:1
	v_pk_fma_f32 v[102:103], v[144:145], v[122:123], v[102:103] op_sel:[0,1,0] op_sel_hi:[1,1,1]
	v_pk_fma_f32 v[104:105], v[144:145], v[124:125], v[104:105] op_sel:[0,0,0] op_sel_hi:[1,0,1]
	v_pk_fma_f32 v[106:107], v[144:145], v[124:125], v[106:107] op_sel:[0,1,0] op_sel_hi:[1,1,1]
	v_add_f32_dpp v50, v50, v50 row_half_mirror row_mask:0xf bank_mask:0xf bound_ctrl:1
	v_add_f32_dpp v51, v51, v51 row_half_mirror row_mask:0xf bank_mask:0xf bound_ctrl:1
	v_pk_fma_f32 v[108:109], v[144:145], v[126:127], v[108:109] op_sel:[0,0,0] op_sel_hi:[1,0,1]
	s_mov_b64 exec, s[86:87]
	ds_write_b64 v45, v[48:49] offset:2560
	s_mov_b64 exec, s[0:1]
	v_pk_fma_f32 v[110:111], v[144:145], v[126:127], v[110:111] op_sel:[0,1,0] op_sel_hi:[1,1,1]
	s_nop 0
	v_pk_fma_f32 v[96:97], v[50:51], v[128:129], v[96:97] op_sel:[0,0,0] op_sel_hi:[1,0,1]
	v_pk_fma_f32 v[98:99], v[50:51], v[128:129], v[98:99] op_sel:[0,1,0] op_sel_hi:[1,1,1]
	v_pk_fma_f32 v[100:101], v[50:51], v[130:131], v[100:101] op_sel:[0,0,0] op_sel_hi:[1,0,1]
	v_pk_fma_f32 v[102:103], v[50:51], v[130:131], v[102:103] op_sel:[0,1,0] op_sel_hi:[1,1,1]
	v_pk_fma_f32 v[104:105], v[50:51], v[132:133], v[104:105] op_sel:[0,0,0] op_sel_hi:[1,0,1]
	v_pk_fma_f32 v[106:107], v[50:51], v[132:133], v[106:107] op_sel:[0,1,0] op_sel_hi:[1,1,1]
	v_pk_fma_f32 v[108:109], v[50:51], v[134:135], v[108:109] op_sel:[0,0,0] op_sel_hi:[1,0,1]
	v_pk_fma_f32 v[110:111], v[50:51], v[134:135], v[110:111] op_sel:[0,1,0] op_sel_hi:[1,1,1]
	v_pk_mul_f32 v[48:49], v[96:97], v[136:137] op_sel:[0,0] op_sel_hi:[1,0]
	v_pk_mul_f32 v[50:51], v[96:97], v[156:157] op_sel:[0,0] op_sel_hi:[1,0]
	v_pk_fma_f32 v[48:49], v[98:99], v[136:137], v[48:49] op_sel:[0,1,0] op_sel_hi:[1,1,1]
	v_pk_fma_f32 v[50:51], v[98:99], v[156:157], v[50:51] op_sel:[0,1,0] op_sel_hi:[1,1,1]
	v_pk_fma_f32 v[48:49], v[100:101], v[138:139], v[48:49] op_sel:[0,0,0] op_sel_hi:[1,0,1]
	v_pk_fma_f32 v[50:51], v[100:101], v[158:159], v[50:51] op_sel:[0,0,0] op_sel_hi:[1,0,1]
	v_pk_fma_f32 v[48:49], v[102:103], v[138:139], v[48:49] op_sel:[0,1,0] op_sel_hi:[1,1,1]
	v_pk_fma_f32 v[50:51], v[102:103], v[158:159], v[50:51] op_sel:[0,1,0] op_sel_hi:[1,1,1]
	v_pk_fma_f32 v[48:49], v[104:105], v[140:141], v[48:49] op_sel:[0,0,0] op_sel_hi:[1,0,1]
	v_pk_fma_f32 v[50:51], v[104:105], v[160:161], v[50:51] op_sel:[0,0,0] op_sel_hi:[1,0,1]
	v_pk_fma_f32 v[48:49], v[106:107], v[140:141], v[48:49] op_sel:[0,1,0] op_sel_hi:[1,1,1]
	v_pk_fma_f32 v[50:51], v[106:107], v[160:161], v[50:51] op_sel:[0,1,0] op_sel_hi:[1,1,1]
	v_pk_fma_f32 v[48:49], v[108:109], v[142:143], v[48:49] op_sel:[0,0,0] op_sel_hi:[1,0,1]
	v_pk_fma_f32 v[50:51], v[108:109], v[162:163], v[50:51] op_sel:[0,0,0] op_sel_hi:[1,0,1]
	v_pk_fma_f32 v[48:49], v[110:111], v[142:143], v[48:49] op_sel:[0,1,0] op_sel_hi:[1,1,1]
	v_pk_fma_f32 v[50:51], v[110:111], v[162:163], v[50:51] op_sel:[0,1,0] op_sel_hi:[1,1,1]
	s_waitcnt lgkmcnt(11)
; #define LAS __attribute__((address_space(3)))
; __device__ __forceinline__ float red8(float x) { x += dpp_mov<0xB1>(x); x += dpp_mov<0x4E>(x); x += dpp_mov<0x141>(x); return x; }
; __device__ __forceinline__ void scan_phase(const KP& P, LAS unsigned char* lds, const int tid, const int bx, const int G) {
;     ...
;             for (int s = 0; s < 32; ++s) {
;                 const LAS float* p = cb + s * 384;
;                 const f32x4 w0 = *(const LAS f32x4*)(p), w1 = *(const LAS f32x4*)(p + 4);
;                 const f32x4 k0 = *(const LAS f32x4*)(p + 64), k1 = *(const LAS f32x4*)(p + 68);
;                 const f32x4 a0 = *(const LAS f32x4*)(p + 128), a1 = *(const LAS f32x4*)(p + 132);
;                 const f32x4 b0 = *(const LAS f32x4*)(p + 192), b1 = *(const LAS f32x4*)(p + 196);
;                 const f32x4 r0 = *(const LAS f32x4*)(p + 256), r1 = *(const LAS f32x4*)(p + 260);
;                 const float vv = buf[(c & 1) * 12288 + s * 384 + 320 + v];
;                 f32x2 sa2 = S[0] * (f32x2){a0.x, a0.y};
;                 sa2 += S[1] * (f32x2){a0.z, a0.w}; sa2 += S[2] * (f32x2){a1.x, a1.y}; sa2 += S[3] * (f32x2){a1.z, a1.w};
;                 const float sa = red8(sa2.x + sa2.y);
;                 const f32x2 sav = {sa, sa}, vv2 = {vv, vv};
;                 S[0] = S[0] * (f32x2){w0.x, w0.y} + sav * (f32x2){b0.x, b0.y} + vv2 * (f32x2){k0.x, k0.y};
;                 S[1] = S[1] * (f32x2){w0.z, w0.w} + sav * (f32x2){b0.z, b0.w} + vv2 * (f32x2){k0.z, k0.w};
;                 S[2] = S[2] * (f32x2){w1.x, w1.y} + sav * (f32x2){b1.x, b1.y} + vv2 * (f32x2){k1.x, k1.y};
;                 S[3] = S[3] * (f32x2){w1.z, w1.w} + sav * (f32x2){b1.z, b1.w} + vv2 * (f32x2){k1.z, k1.w};
;                 f32x2 y2 = S[0] * (f32x2){r0.x, r0.y};
;                 y2 += S[1] * (f32x2){r0.z, r0.w}; y2 += S[2] * (f32x2){r1.x, r1.y}; y2 += S[3] * (f32x2){r1.z, r1.w};
;                 const float y = red8(y2.x + y2.y);
;                 if (kc == 0) ybuf[s * 64 + v] = y;
;             }
	ds_read_b128 v[120:123], v44 offset:14080
	ds_read_b128 v[124:127], v44 offset:14096
	ds_read_b128 v[128:131], v44 offset:14592
	ds_read_b128 v[132:135], v44 offset:14608
	ds_read_b128 v[136:139], v44 offset:14848
	ds_read_b128 v[140:143], v44 offset:14864
	ds_read_b64 v[144:145], v46 offset:13824
	ds_read_b128 v[156:159], v44 offset:15872
	ds_read_b128 v[160:163], v44 offset:15888
	v_add_f32_dpp v48, v48, v48 quad_perm:[1,0,3,2] row_mask:0xf bank_mask:0xf bound_ctrl:1
	v_add_f32_dpp v49, v49, v49 quad_perm:[1,0,3,2] row_mask:0xf bank_mask:0xf bound_ctrl:1
	v_add_f32_dpp v50, v50, v50 quad_perm:[1,0,3,2] row_mask:0xf bank_mask:0xf bound_ctrl:1
	v_add_f32_dpp v51, v51, v51 quad_perm:[1,0,3,2] row_mask:0xf bank_mask:0xf bound_ctrl:1
	v_pk_fma_f32 v[96:97], v[146:147], v[70:71], v[96:97] op_sel:[0,0,0] op_sel_hi:[1,0,1]
	v_pk_fma_f32 v[98:99], v[146:147], v[70:71], v[98:99] op_sel:[0,1,0] op_sel_hi:[1,1,1]
	v_pk_fma_f32 v[100:101], v[146:147], v[72:73], v[100:101] op_sel:[0,0,0] op_sel_hi:[1,0,1]
	v_add_f32_dpp v48, v48, v48 quad_perm:[2,3,0,1] row_mask:0xf bank_mask:0xf bound_ctrl:1
	v_add_f32_dpp v49, v49, v49 quad_perm:[2,3,0,1] row_mask:0xf bank_mask:0xf bound_ctrl:1
	v_add_f32_dpp v50, v50, v50 quad_perm:[2,3,0,1] row_mask:0xf bank_mask:0xf bound_ctrl:1
	v_add_f32_dpp v51, v51, v51 quad_perm:[2,3,0,1] row_mask:0xf bank_mask:0xf bound_ctrl:1
	v_pk_fma_f32 v[102:103], v[146:147], v[72:73], v[102:103] op_sel:[0,1,0] op_sel_hi:[1,1,1]
	v_pk_fma_f32 v[104:105], v[146:147], v[74:75], v[104:105] op_sel:[0,0,0] op_sel_hi:[1,0,1]
	v_pk_fma_f32 v[106:107], v[146:147], v[74:75], v[106:107] op_sel:[0,1,0] op_sel_hi:[1,1,1]
	v_add_f32_dpp v50, v50, v50 row_half_mirror row_mask:0xf bank_mask:0xf bound_ctrl:1
	v_add_f32_dpp v51, v51, v51 row_half_mirror row_mask:0xf bank_mask:0xf bound_ctrl:1
	v_pk_fma_f32 v[108:109], v[146:147], v[76:77], v[108:109] op_sel:[0,0,0] op_sel_hi:[1,0,1]
	s_mov_b64 exec, s[86:87]
	ds_write_b64 v45, v[48:49] offset:3072
	s_mov_b64 exec, s[0:1]
	v_pk_fma_f32 v[110:111], v[146:147], v[76:77], v[110:111] op_sel:[0,1,0] op_sel_hi:[1,1,1]
	s_nop 0
	v_pk_fma_f32 v[96:97], v[50:51], v[78:79], v[96:97] op_sel:[0,0,0] op_sel_hi:[1,0,1]
	v_pk_fma_f32 v[98:99], v[50:51], v[78:79], v[98:99] op_sel:[0,1,0] op_sel_hi:[1,1,1]
	v_pk_fma_f32 v[100:101], v[50:51], v[80:81], v[100:101] op_sel:[0,0,0] op_sel_hi:[1,0,1]
	v_pk_fma_f32 v[102:103], v[50:51], v[80:81], v[102:103] op_sel:[0,1,0] op_sel_hi:[1,1,1]
	v_pk_fma_f32 v[104:105], v[50:51], v[82:83], v[104:105] op_sel:[0,0,0] op_sel_hi:[1,0,1]
	v_pk_fma_f32 v[106:107], v[50:51], v[82:83], v[106:107] op_sel:[0,1,0] op_sel_hi:[1,1,1]
	v_pk_fma_f32 v[108:109], v[50:51], v[84:85], v[108:109] op_sel:[0,0,0] op_sel_hi:[1,0,1]
	v_pk_fma_f32 v[110:111], v[50:51], v[84:85], v[110:111] op_sel:[0,1,0] op_sel_hi:[1,1,1]
	v_pk_mul_f32 v[48:49], v[96:97], v[86:87] op_sel:[0,0] op_sel_hi:[1,0]
	v_pk_mul_f32 v[50:51], v[96:97], v[62:63] op_sel:[0,0] op_sel_hi:[1,0]
	v_pk_fma_f32 v[48:49], v[98:99], v[86:87], v[48:49] op_sel:[0,1,0] op_sel_hi:[1,1,1]
	v_pk_fma_f32 v[50:51], v[98:99], v[62:63], v[50:51] op_sel:[0,1,0] op_sel_hi:[1,1,1]
	v_pk_fma_f32 v[48:49], v[100:101], v[88:89], v[48:49] op_sel:[0,0,0] op_sel_hi:[1,0,1]
	v_pk_fma_f32 v[50:51], v[100:101], v[64:65], v[50:51] op_sel:[0,0,0] op_sel_hi:[1,0,1]
	v_pk_fma_f32 v[48:49], v[102:103], v[88:89], v[48:49] op_sel:[0,1,0] op_sel_hi:[1,1,1]
	v_pk_fma_f32 v[50:51], v[102:103], v[64:65], v[50:51] op_sel:[0,1,0] op_sel_hi:[1,1,1]
	v_pk_fma_f32 v[48:49], v[104:105], v[90:91], v[48:49] op_sel:[0,0,0] op_sel_hi:[1,0,1]
	v_pk_fma_f32 v[50:51], v[104:105], v[66:67], v[50:51] op_sel:[0,0,0] op_sel_hi:[1,0,1]
	v_pk_fma_f32 v[48:49], v[106:107], v[90:91], v[48:49] op_sel:[0,1,0] op_sel_hi:[1,1,1]
	v_pk_fma_f32 v[50:51], v[106:107], v[66:67], v[50:51] op_sel:[0,1,0] op_sel_hi:[1,1,1]
	v_pk_fma_f32 v[48:49], v[108:109], v[92:93], v[48:49] op_sel:[0,0,0] op_sel_hi:[1,0,1]
	v_pk_fma_f32 v[50:51], v[108:109], v[68:69], v[50:51] op_sel:[0,0,0] op_sel_hi:[1,0,1]
	v_pk_fma_f32 v[48:49], v[110:111], v[92:93], v[48:49] op_sel:[0,1,0] op_sel_hi:[1,1,1]
	v_pk_fma_f32 v[50:51], v[110:111], v[68:69], v[50:51] op_sel:[0,1,0] op_sel_hi:[1,1,1]
	s_waitcnt lgkmcnt(11)
	ds_read_b128 v[70:73], v44 offset:15616
	ds_read_b128 v[74:77], v44 offset:15632
	ds_read_b128 v[78:81], v44 offset:16128
	ds_read_b128 v[82:85], v44 offset:16144
	ds_read_b128 v[86:89], v44 offset:16384
	ds_read_b128 v[90:93], v44 offset:16400
	ds_read_b64 v[146:147], v46 offset:15360
	ds_read_b128 v[62:65], v44 offset:17408
	ds_read_b128 v[66:69], v44 offset:17424
	v_add_f32_dpp v48, v48, v48 quad_perm:[1,0,3,2] row_mask:0xf bank_mask:0xf bound_ctrl:1
	v_add_f32_dpp v49, v49, v49 quad_perm:[1,0,3,2] row_mask:0xf bank_mask:0xf bound_ctrl:1
	v_add_f32_dpp v50, v50, v50 quad_perm:[1,0,3,2] row_mask:0xf bank_mask:0xf bound_ctrl:1
	v_add_f32_dpp v51, v51, v51 quad_perm:[1,0,3,2] row_mask:0xf bank_mask:0xf bound_ctrl:1
	v_pk_fma_f32 v[96:97], v[192:193], v[168:169], v[96:97] op_sel:[0,0,0] op_sel_hi:[1,0,1]
	v_pk_fma_f32 v[98:99], v[192:193], v[168:169], v[98:99] op_sel:[0,1,0] op_sel_hi:[1,1,1]
	v_pk_fma_f32 v[100:101], v[192:193], v[170:171], v[100:101] op_sel:[0,0,0] op_sel_hi:[1,0,1]
	v_add_f32_dpp v48, v48, v48 quad_perm:[2,3,0,1] row_mask:0xf bank_mask:0xf bound_ctrl:1
	v_add_f32_dpp v49, v49, v49 quad_perm:[2,3,0,1] row_mask:0xf bank_mask:0xf bound_ctrl:1
	v_add_f32_dpp v50, v50, v50 quad_perm:[2,3,0,1] row_mask:0xf bank_mask:0xf bound_ctrl:1
	v_add_f32_dpp v51, v51, v51 quad_perm:[2,3,0,1] row_mask:0xf bank_mask:0xf bound_ctrl:1
	v_pk_fma_f32 v[102:103], v[192:193], v[170:171], v[102:103] op_sel:[0,1,0] op_sel_hi:[1,1,1]
; #define LAS __attribute__((address_space(3)))
; __device__ __forceinline__ float red8(float x) { x += dpp_mov<0xB1>(x); x += dpp_mov<0x4E>(x); x += dpp_mov<0x141>(x); return x; }
; __device__ __forceinline__ void scan_phase(const KP& P, LAS unsigned char* lds, const int tid, const int bx, const int G) {
;     ...
;             for (int s = 0; s < 32; ++s) {
;                 const LAS float* p = cb + s * 384;
;                 const f32x4 w0 = *(const LAS f32x4*)(p), w1 = *(const LAS f32x4*)(p + 4);
;                 const f32x4 k0 = *(const LAS f32x4*)(p + 64), k1 = *(const LAS f32x4*)(p + 68);
;                 const f32x4 a0 = *(const LAS f32x4*)(p + 128), a1 = *(const LAS f32x4*)(p + 132);
;                 const f32x4 b0 = *(const LAS f32x4*)(p + 192), b1 = *(const LAS f32x4*)(p + 196);
;                 const f32x4 r0 = *(const LAS f32x4*)(p + 256), r1 = *(const LAS f32x4*)(p + 260);
;                 const float vv = buf[(c & 1) * 12288 + s * 384 + 320 + v];
;                 f32x2 sa2 = S[0] * (f32x2){a0.x, a0.y};
;                 sa2 += S[1] * (f32x2){a0.z, a0.w}; sa2 += S[2] * (f32x2){a1.x, a1.y}; sa2 += S[3] * (f32x2){a1.z, a1.w};
;                 const float sa = red8(sa2.x + sa2.y);
;                 const f32x2 sav = {sa, sa}, vv2 = {vv, vv};
;                 S[0] = S[0] * (f32x2){w0.x, w0.y} + sav * (f32x2){b0.x, b0.y} + vv2 * (f32x2){k0.x, k0.y};
;                 S[1] = S[1] * (f32x2){w0.z, w0.w} + sav * (f32x2){b0.z, b0.w} + vv2 * (f32x2){k0.z, k0.w};
;                 S[2] = S[2] * (f32x2){w1.x, w1.y} + sav * (f32x2){b1.x, b1.y} + vv2 * (f32x2){k1.x, k1.y};
;                 S[3] = S[3] * (f32x2){w1.z, w1.w} + sav * (f32x2){b1.z, b1.w} + vv2 * (f32x2){k1.z, k1.w};
;                 f32x2 y2 = S[0] * (f32x2){r0.x, r0.y};
;                 y2 += S[1] * (f32x2){r0.z, r0.w}; y2 += S[2] * (f32x2){r1.x, r1.y}; y2 += S[3] * (f32x2){r1.z, r1.w};
;                 const float y = red8(y2.x + y2.y);
;                 if (kc == 0) ybuf[s * 64 + v] = y;
;             }
	v_pk_fma_f32 v[104:105], v[192:193], v[172:173], v[104:105] op_sel:[0,0,0] op_sel_hi:[1,0,1]
	v_pk_fma_f32 v[106:107], v[192:193], v[172:173], v[106:107] op_sel:[0,1,0] op_sel_hi:[1,1,1]
	v_add_f32_dpp v50, v50, v50 row_half_mirror row_mask:0xf bank_mask:0xf bound_ctrl:1
	v_add_f32_dpp v51, v51, v51 row_half_mirror row_mask:0xf bank_mask:0xf bound_ctrl:1
	v_pk_fma_f32 v[108:109], v[192:193], v[174:175], v[108:109] op_sel:[0,0,0] op_sel_hi:[1,0,1]
	s_mov_b64 exec, s[86:87]
	ds_write_b64 v45, v[48:49] offset:3584
	s_mov_b64 exec, s[0:1]
	v_pk_fma_f32 v[110:111], v[192:193], v[174:175], v[110:111] op_sel:[0,1,0] op_sel_hi:[1,1,1]
	s_nop 0
	v_pk_fma_f32 v[96:97], v[50:51], v[176:177], v[96:97] op_sel:[0,0,0] op_sel_hi:[1,0,1]
	v_pk_fma_f32 v[98:99], v[50:51], v[176:177], v[98:99] op_sel:[0,1,0] op_sel_hi:[1,1,1]
	v_pk_fma_f32 v[100:101], v[50:51], v[178:179], v[100:101] op_sel:[0,0,0] op_sel_hi:[1,0,1]
	v_pk_fma_f32 v[102:103], v[50:51], v[178:179], v[102:103] op_sel:[0,1,0] op_sel_hi:[1,1,1]
	v_pk_fma_f32 v[104:105], v[50:51], v[180:181], v[104:105] op_sel:[0,0,0] op_sel_hi:[1,0,1]
	v_pk_fma_f32 v[106:107], v[50:51], v[180:181], v[106:107] op_sel:[0,1,0] op_sel_hi:[1,1,1]
	v_pk_fma_f32 v[108:109], v[50:51], v[182:183], v[108:109] op_sel:[0,0,0] op_sel_hi:[1,0,1]
	v_pk_fma_f32 v[110:111], v[50:51], v[182:183], v[110:111] op_sel:[0,1,0] op_sel_hi:[1,1,1]
	v_pk_mul_f32 v[48:49], v[96:97], v[184:185] op_sel:[0,0] op_sel_hi:[1,0]
	v_pk_mul_f32 v[50:51], v[96:97], v[148:149] op_sel:[0,0] op_sel_hi:[1,0]
	v_pk_fma_f32 v[48:49], v[98:99], v[184:185], v[48:49] op_sel:[0,1,0] op_sel_hi:[1,1,1]
	v_pk_fma_f32 v[50:51], v[98:99], v[148:149], v[50:51] op_sel:[0,1,0] op_sel_hi:[1,1,1]
	v_pk_fma_f32 v[48:49], v[100:101], v[186:187], v[48:49] op_sel:[0,0,0] op_sel_hi:[1,0,1]
	v_pk_fma_f32 v[50:51], v[100:101], v[150:151], v[50:51] op_sel:[0,0,0] op_sel_hi:[1,0,1]
	v_pk_fma_f32 v[48:49], v[102:103], v[186:187], v[48:49] op_sel:[0,1,0] op_sel_hi:[1,1,1]
	v_pk_fma_f32 v[50:51], v[102:103], v[150:151], v[50:51] op_sel:[0,1,0] op_sel_hi:[1,1,1]
	v_pk_fma_f32 v[48:49], v[104:105], v[188:189], v[48:49] op_sel:[0,0,0] op_sel_hi:[1,0,1]
	v_pk_fma_f32 v[50:51], v[104:105], v[152:153], v[50:51] op_sel:[0,0,0] op_sel_hi:[1,0,1]
	v_pk_fma_f32 v[48:49], v[106:107], v[188:189], v[48:49] op_sel:[0,1,0] op_sel_hi:[1,1,1]
	v_pk_fma_f32 v[50:51], v[106:107], v[152:153], v[50:51] op_sel:[0,1,0] op_sel_hi:[1,1,1]
	v_pk_fma_f32 v[48:49], v[108:109], v[190:191], v[48:49] op_sel:[0,0,0] op_sel_hi:[1,0,1]
	v_pk_fma_f32 v[50:51], v[108:109], v[154:155], v[50:51] op_sel:[0,0,0] op_sel_hi:[1,0,1]
	v_pk_fma_f32 v[48:49], v[110:111], v[190:191], v[48:49] op_sel:[0,1,0] op_sel_hi:[1,1,1]
	v_pk_fma_f32 v[50:51], v[110:111], v[154:155], v[50:51] op_sel:[0,1,0] op_sel_hi:[1,1,1]
	s_waitcnt lgkmcnt(11)
	ds_read_b128 v[168:171], v44 offset:17152
	ds_read_b128 v[172:175], v44 offset:17168
	ds_read_b128 v[176:179], v44 offset:17664
	ds_read_b128 v[180:183], v44 offset:17680
	ds_read_b128 v[184:187], v44 offset:17920
	ds_read_b128 v[188:191], v44 offset:17936
	ds_read_b64 v[192:193], v46 offset:16896
	ds_read_b128 v[148:151], v44 offset:18944
	ds_read_b128 v[152:155], v44 offset:18960
	v_add_f32_dpp v48, v48, v48 quad_perm:[1,0,3,2] row_mask:0xf bank_mask:0xf bound_ctrl:1
	v_add_f32_dpp v49, v49, v49 quad_perm:[1,0,3,2] row_mask:0xf bank_mask:0xf bound_ctrl:1
	v_add_f32_dpp v50, v50, v50 quad_perm:[1,0,3,2] row_mask:0xf bank_mask:0xf bound_ctrl:1
	v_add_f32_dpp v51, v51, v51 quad_perm:[1,0,3,2] row_mask:0xf bank_mask:0xf bound_ctrl:1
	v_pk_fma_f32 v[96:97], v[144:145], v[120:121], v[96:97] op_sel:[0,0,0] op_sel_hi:[1,0,1]
	v_pk_fma_f32 v[98:99], v[144:145], v[120:121], v[98:99] op_sel:[0,1,0] op_sel_hi:[1,1,1]
	v_pk_fma_f32 v[100:101], v[144:145], v[122:123], v[100:101] op_sel:[0,0,0] op_sel_hi:[1,0,1]
	v_add_f32_dpp v48, v48, v48 quad_perm:[2,3,0,1] row_mask:0xf bank_mask:0xf bound_ctrl:1
	v_add_f32_dpp v49, v49, v49 quad_perm:[2,3,0,1] row_mask:0xf bank_mask:0xf bound_ctrl:1
	v_add_f32_dpp v50, v50, v50 quad_perm:[2,3,0,1] row_mask:0xf bank_mask:0xf bound_ctrl:1
	v_add_f32_dpp v51, v51, v51 quad_perm:[2,3,0,1] row_mask:0xf bank_mask:0xf bound_ctrl:1
	v_pk_fma_f32 v[102:103], v[144:145], v[122:123], v[102:103] op_sel:[0,1,0] op_sel_hi:[1,1,1]
	v_pk_fma_f32 v[104:105], v[144:145], v[124:125], v[104:105] op_sel:[0,0,0] op_sel_hi:[1,0,1]
	v_pk_fma_f32 v[106:107], v[144:145], v[124:125], v[106:107] op_sel:[0,1,0] op_sel_hi:[1,1,1]
	v_add_f32_dpp v50, v50, v50 row_half_mirror row_mask:0xf bank_mask:0xf bound_ctrl:1
	v_add_f32_dpp v51, v51, v51 row_half_mirror row_mask:0xf bank_mask:0xf bound_ctrl:1
	v_pk_fma_f32 v[108:109], v[144:145], v[126:127], v[108:109] op_sel:[0,0,0] op_sel_hi:[1,0,1]
	s_mov_b64 exec, s[86:87]
	ds_write_b64 v45, v[48:49] offset:4096
	s_mov_b64 exec, s[0:1]
	v_pk_fma_f32 v[110:111], v[144:145], v[126:127], v[110:111] op_sel:[0,1,0] op_sel_hi:[1,1,1]
	s_nop 0
	v_pk_fma_f32 v[96:97], v[50:51], v[128:129], v[96:97] op_sel:[0,0,0] op_sel_hi:[1,0,1]
	v_pk_fma_f32 v[98:99], v[50:51], v[128:129], v[98:99] op_sel:[0,1,0] op_sel_hi:[1,1,1]
	v_pk_fma_f32 v[100:101], v[50:51], v[130:131], v[100:101] op_sel:[0,0,0] op_sel_hi:[1,0,1]
	v_pk_fma_f32 v[102:103], v[50:51], v[130:131], v[102:103] op_sel:[0,1,0] op_sel_hi:[1,1,1]
	v_pk_fma_f32 v[104:105], v[50:51], v[132:133], v[104:105] op_sel:[0,0,0] op_sel_hi:[1,0,1]
	v_pk_fma_f32 v[106:107], v[50:51], v[132:133], v[106:107] op_sel:[0,1,0] op_sel_hi:[1,1,1]
	v_pk_fma_f32 v[108:109], v[50:51], v[134:135], v[108:109] op_sel:[0,0,0] op_sel_hi:[1,0,1]
	v_pk_fma_f32 v[110:111], v[50:51], v[134:135], v[110:111] op_sel:[0,1,0] op_sel_hi:[1,1,1]
; #define LAS __attribute__((address_space(3)))
; __device__ __forceinline__ float red8(float x) { x += dpp_mov<0xB1>(x); x += dpp_mov<0x4E>(x); x += dpp_mov<0x141>(x); return x; }
; __device__ __forceinline__ void scan_phase(const KP& P, LAS unsigned char* lds, const int tid, const int bx, const int G) {
;     ...
;             for (int s = 0; s < 32; ++s) {
;                 const LAS float* p = cb + s * 384;
;                 const f32x4 w0 = *(const LAS f32x4*)(p), w1 = *(const LAS f32x4*)(p + 4);
;                 const f32x4 k0 = *(const LAS f32x4*)(p + 64), k1 = *(const LAS f32x4*)(p + 68);
;                 const f32x4 a0 = *(const LAS f32x4*)(p + 128), a1 = *(const LAS f32x4*)(p + 132);
;                 const f32x4 b0 = *(const LAS f32x4*)(p + 192), b1 = *(const LAS f32x4*)(p + 196);
;                 const f32x4 r0 = *(const LAS f32x4*)(p + 256), r1 = *(const LAS f32x4*)(p + 260);
;                 const float vv = buf[(c & 1) * 12288 + s * 384 + 320 + v];
;                 f32x2 sa2 = S[0] * (f32x2){a0.x, a0.y};
;                 sa2 += S[1] * (f32x2){a0.z, a0.w}; sa2 += S[2] * (f32x2){a1.x, a1.y}; sa2 += S[3] * (f32x2){a1.z, a1.w};
;                 const float sa = red8(sa2.x + sa2.y);
;                 const f32x2 sav = {sa, sa}, vv2 = {vv, vv};
;                 S[0] = S[0] * (f32x2){w0.x, w0.y} + sav * (f32x2){b0.x, b0.y} + vv2 * (f32x2){k0.x, k0.y};
;                 S[1] = S[1] * (f32x2){w0.z, w0.w} + sav * (f32x2){b0.z, b0.w} + vv2 * (f32x2){k0.z, k0.w};
;                 S[2] = S[2] * (f32x2){w1.x, w1.y} + sav * (f32x2){b1.x, b1.y} + vv2 * (f32x2){k1.x, k1.y};
;                 S[3] = S[3] * (f32x2){w1.z, w1.w} + sav * (f32x2){b1.z, b1.w} + vv2 * (f32x2){k1.z, k1.w};
;                 f32x2 y2 = S[0] * (f32x2){r0.x, r0.y};
;                 y2 += S[1] * (f32x2){r0.z, r0.w}; y2 += S[2] * (f32x2){r1.x, r1.y}; y2 += S[3] * (f32x2){r1.z, r1.w};
;                 const float y = red8(y2.x + y2.y);
;                 if (kc == 0) ybuf[s * 64 + v] = y;
;             }
	v_pk_mul_f32 v[48:49], v[96:97], v[136:137] op_sel:[0,0] op_sel_hi:[1,0]
	v_pk_mul_f32 v[50:51], v[96:97], v[156:157] op_sel:[0,0] op_sel_hi:[1,0]
	v_pk_fma_f32 v[48:49], v[98:99], v[136:137], v[48:49] op_sel:[0,1,0] op_sel_hi:[1,1,1]
	v_pk_fma_f32 v[50:51], v[98:99], v[156:157], v[50:51] op_sel:[0,1,0] op_sel_hi:[1,1,1]
	v_pk_fma_f32 v[48:49], v[100:101], v[138:139], v[48:49] op_sel:[0,0,0] op_sel_hi:[1,0,1]
	v_pk_fma_f32 v[50:51], v[100:101], v[158:159], v[50:51] op_sel:[0,0,0] op_sel_hi:[1,0,1]
	v_pk_fma_f32 v[48:49], v[102:103], v[138:139], v[48:49] op_sel:[0,1,0] op_sel_hi:[1,1,1]
	v_pk_fma_f32 v[50:51], v[102:103], v[158:159], v[50:51] op_sel:[0,1,0] op_sel_hi:[1,1,1]
	v_pk_fma_f32 v[48:49], v[104:105], v[140:141], v[48:49] op_sel:[0,0,0] op_sel_hi:[1,0,1]
	v_pk_fma_f32 v[50:51], v[104:105], v[160:161], v[50:51] op_sel:[0,0,0] op_sel_hi:[1,0,1]
	v_pk_fma_f32 v[48:49], v[106:107], v[140:141], v[48:49] op_sel:[0,1,0] op_sel_hi:[1,1,1]
	v_pk_fma_f32 v[50:51], v[106:107], v[160:161], v[50:51] op_sel:[0,1,0] op_sel_hi:[1,1,1]
	v_pk_fma_f32 v[48:49], v[108:109], v[142:143], v[48:49] op_sel:[0,0,0] op_sel_hi:[1,0,1]
	v_pk_fma_f32 v[50:51], v[108:109], v[162:163], v[50:51] op_sel:[0,0,0] op_sel_hi:[1,0,1]
	v_pk_fma_f32 v[48:49], v[110:111], v[142:143], v[48:49] op_sel:[0,1,0] op_sel_hi:[1,1,1]
	v_pk_fma_f32 v[50:51], v[110:111], v[162:163], v[50:51] op_sel:[0,1,0] op_sel_hi:[1,1,1]
	s_waitcnt lgkmcnt(11)
	ds_read_b128 v[120:123], v44 offset:18688
	ds_read_b128 v[124:127], v44 offset:18704
	ds_read_b128 v[128:131], v44 offset:19200
	ds_read_b128 v[132:135], v44 offset:19216
	ds_read_b128 v[136:139], v44 offset:19456
	ds_read_b128 v[140:143], v44 offset:19472
	ds_read_b64 v[144:145], v46 offset:18432
	ds_read_b128 v[156:159], v44 offset:20480
	ds_read_b128 v[160:163], v44 offset:20496
	v_add_f32_dpp v48, v48, v48 quad_perm:[1,0,3,2] row_mask:0xf bank_mask:0xf bound_ctrl:1
	v_add_f32_dpp v49, v49, v49 quad_perm:[1,0,3,2] row_mask:0xf bank_mask:0xf bound_ctrl:1
	v_add_f32_dpp v50, v50, v50 quad_perm:[1,0,3,2] row_mask:0xf bank_mask:0xf bound_ctrl:1
	v_add_f32_dpp v51, v51, v51 quad_perm:[1,0,3,2] row_mask:0xf bank_mask:0xf bound_ctrl:1
	v_pk_fma_f32 v[96:97], v[146:147], v[70:71], v[96:97] op_sel:[0,0,0] op_sel_hi:[1,0,1]
	v_pk_fma_f32 v[98:99], v[146:147], v[70:71], v[98:99] op_sel:[0,1,0] op_sel_hi:[1,1,1]
	v_pk_fma_f32 v[100:101], v[146:147], v[72:73], v[100:101] op_sel:[0,0,0] op_sel_hi:[1,0,1]
	v_add_f32_dpp v48, v48, v48 quad_perm:[2,3,0,1] row_mask:0xf bank_mask:0xf bound_ctrl:1
	v_add_f32_dpp v49, v49, v49 quad_perm:[2,3,0,1] row_mask:0xf bank_mask:0xf bound_ctrl:1
	v_add_f32_dpp v50, v50, v50 quad_perm:[2,3,0,1] row_mask:0xf bank_mask:0xf bound_ctrl:1
	v_add_f32_dpp v51, v51, v51 quad_perm:[2,3,0,1] row_mask:0xf bank_mask:0xf bound_ctrl:1
	v_pk_fma_f32 v[102:103], v[146:147], v[72:73], v[102:103] op_sel:[0,1,0] op_sel_hi:[1,1,1]
	v_pk_fma_f32 v[104:105], v[146:147], v[74:75], v[104:105] op_sel:[0,0,0] op_sel_hi:[1,0,1]
	v_pk_fma_f32 v[106:107], v[146:147], v[74:75], v[106:107] op_sel:[0,1,0] op_sel_hi:[1,1,1]
	v_add_f32_dpp v50, v50, v50 row_half_mirror row_mask:0xf bank_mask:0xf bound_ctrl:1
	v_add_f32_dpp v51, v51, v51 row_half_mirror row_mask:0xf bank_mask:0xf bound_ctrl:1
	v_pk_fma_f32 v[108:109], v[146:147], v[76:77], v[108:109] op_sel:[0,0,0] op_sel_hi:[1,0,1]
	s_mov_b64 exec, s[86:87]
	ds_write_b64 v45, v[48:49] offset:4608
	s_mov_b64 exec, s[0:1]
	v_pk_fma_f32 v[110:111], v[146:147], v[76:77], v[110:111] op_sel:[0,1,0] op_sel_hi:[1,1,1]
	s_nop 0
	v_pk_fma_f32 v[96:97], v[50:51], v[78:79], v[96:97] op_sel:[0,0,0] op_sel_hi:[1,0,1]
	v_pk_fma_f32 v[98:99], v[50:51], v[78:79], v[98:99] op_sel:[0,1,0] op_sel_hi:[1,1,1]
	v_pk_fma_f32 v[100:101], v[50:51], v[80:81], v[100:101] op_sel:[0,0,0] op_sel_hi:[1,0,1]
	v_pk_fma_f32 v[102:103], v[50:51], v[80:81], v[102:103] op_sel:[0,1,0] op_sel_hi:[1,1,1]
	v_pk_fma_f32 v[104:105], v[50:51], v[82:83], v[104:105] op_sel:[0,0,0] op_sel_hi:[1,0,1]
	v_pk_fma_f32 v[106:107], v[50:51], v[82:83], v[106:107] op_sel:[0,1,0] op_sel_hi:[1,1,1]
	v_pk_fma_f32 v[108:109], v[50:51], v[84:85], v[108:109] op_sel:[0,0,0] op_sel_hi:[1,0,1]
	v_pk_fma_f32 v[110:111], v[50:51], v[84:85], v[110:111] op_sel:[0,1,0] op_sel_hi:[1,1,1]
	v_pk_mul_f32 v[48:49], v[96:97], v[86:87] op_sel:[0,0] op_sel_hi:[1,0]
	v_pk_mul_f32 v[50:51], v[96:97], v[62:63] op_sel:[0,0] op_sel_hi:[1,0]
	v_pk_fma_f32 v[48:49], v[98:99], v[86:87], v[48:49] op_sel:[0,1,0] op_sel_hi:[1,1,1]
	v_pk_fma_f32 v[50:51], v[98:99], v[62:63], v[50:51] op_sel:[0,1,0] op_sel_hi:[1,1,1]
	v_pk_fma_f32 v[48:49], v[100:101], v[88:89], v[48:49] op_sel:[0,0,0] op_sel_hi:[1,0,1]
	v_pk_fma_f32 v[50:51], v[100:101], v[64:65], v[50:51] op_sel:[0,0,0] op_sel_hi:[1,0,1]
	v_pk_fma_f32 v[48:49], v[102:103], v[88:89], v[48:49] op_sel:[0,1,0] op_sel_hi:[1,1,1]
	v_pk_fma_f32 v[50:51], v[102:103], v[64:65], v[50:51] op_sel:[0,1,0] op_sel_hi:[1,1,1]
	v_pk_fma_f32 v[48:49], v[104:105], v[90:91], v[48:49] op_sel:[0,0,0] op_sel_hi:[1,0,1]
	v_pk_fma_f32 v[50:51], v[104:105], v[66:67], v[50:51] op_sel:[0,0,0] op_sel_hi:[1,0,1]
	v_pk_fma_f32 v[48:49], v[106:107], v[90:91], v[48:49] op_sel:[0,1,0] op_sel_hi:[1,1,1]
	v_pk_fma_f32 v[50:51], v[106:107], v[66:67], v[50:51] op_sel:[0,1,0] op_sel_hi:[1,1,1]
	v_pk_fma_f32 v[48:49], v[108:109], v[92:93], v[48:49] op_sel:[0,0,0] op_sel_hi:[1,0,1]
	v_pk_fma_f32 v[50:51], v[108:109], v[68:69], v[50:51] op_sel:[0,0,0] op_sel_hi:[1,0,1]
	v_pk_fma_f32 v[48:49], v[110:111], v[92:93], v[48:49] op_sel:[0,1,0] op_sel_hi:[1,1,1]
	v_pk_fma_f32 v[50:51], v[110:111], v[68:69], v[50:51] op_sel:[0,1,0] op_sel_hi:[1,1,1]
	s_waitcnt lgkmcnt(11)
; #define LAS __attribute__((address_space(3)))
; __device__ __forceinline__ float red8(float x) { x += dpp_mov<0xB1>(x); x += dpp_mov<0x4E>(x); x += dpp_mov<0x141>(x); return x; }
; __device__ __forceinline__ void scan_phase(const KP& P, LAS unsigned char* lds, const int tid, const int bx, const int G) {
;     ...
;             for (int s = 0; s < 32; ++s) {
;                 const LAS float* p = cb + s * 384;
;                 const f32x4 w0 = *(const LAS f32x4*)(p), w1 = *(const LAS f32x4*)(p + 4);
;                 const f32x4 k0 = *(const LAS f32x4*)(p + 64), k1 = *(const LAS f32x4*)(p + 68);
;                 const f32x4 a0 = *(const LAS f32x4*)(p + 128), a1 = *(const LAS f32x4*)(p + 132);
;                 const f32x4 b0 = *(const LAS f32x4*)(p + 192), b1 = *(const LAS f32x4*)(p + 196);
;                 const f32x4 r0 = *(const LAS f32x4*)(p + 256), r1 = *(const LAS f32x4*)(p + 260);
;                 const float vv = buf[(c & 1) * 12288 + s * 384 + 320 + v];
;                 f32x2 sa2 = S[0] * (f32x2){a0.x, a0.y};
;                 sa2 += S[1] * (f32x2){a0.z, a0.w}; sa2 += S[2] * (f32x2){a1.x, a1.y}; sa2 += S[3] * (f32x2){a1.z, a1.w};
;                 const float sa = red8(sa2.x + sa2.y);
;                 const f32x2 sav = {sa, sa}, vv2 = {vv, vv};
;                 S[0] = S[0] * (f32x2){w0.x, w0.y} + sav * (f32x2){b0.x, b0.y} + vv2 * (f32x2){k0.x, k0.y};
;                 S[1] = S[1] * (f32x2){w0.z, w0.w} + sav * (f32x2){b0.z, b0.w} + vv2 * (f32x2){k0.z, k0.w};
;                 S[2] = S[2] * (f32x2){w1.x, w1.y} + sav * (f32x2){b1.x, b1.y} + vv2 * (f32x2){k1.x, k1.y};
;                 S[3] = S[3] * (f32x2){w1.z, w1.w} + sav * (f32x2){b1.z, b1.w} + vv2 * (f32x2){k1.z, k1.w};
;                 f32x2 y2 = S[0] * (f32x2){r0.x, r0.y};
;                 y2 += S[1] * (f32x2){r0.z, r0.w}; y2 += S[2] * (f32x2){r1.x, r1.y}; y2 += S[3] * (f32x2){r1.z, r1.w};
;                 const float y = red8(y2.x + y2.y);
;                 if (kc == 0) ybuf[s * 64 + v] = y;
;             }
	ds_read_b128 v[70:73], v44 offset:20224
	ds_read_b128 v[74:77], v44 offset:20240
	ds_read_b128 v[78:81], v44 offset:20736
	ds_read_b128 v[82:85], v44 offset:20752
	ds_read_b128 v[86:89], v44 offset:20992
	ds_read_b128 v[90:93], v44 offset:21008
	ds_read_b64 v[146:147], v46 offset:19968
	ds_read_b128 v[62:65], v44 offset:22016
	ds_read_b128 v[66:69], v44 offset:22032
	v_add_f32_dpp v48, v48, v48 quad_perm:[1,0,3,2] row_mask:0xf bank_mask:0xf bound_ctrl:1
	v_add_f32_dpp v49, v49, v49 quad_perm:[1,0,3,2] row_mask:0xf bank_mask:0xf bound_ctrl:1
	v_add_f32_dpp v50, v50, v50 quad_perm:[1,0,3,2] row_mask:0xf bank_mask:0xf bound_ctrl:1
	v_add_f32_dpp v51, v51, v51 quad_perm:[1,0,3,2] row_mask:0xf bank_mask:0xf bound_ctrl:1
	v_pk_fma_f32 v[96:97], v[192:193], v[168:169], v[96:97] op_sel:[0,0,0] op_sel_hi:[1,0,1]
	v_pk_fma_f32 v[98:99], v[192:193], v[168:169], v[98:99] op_sel:[0,1,0] op_sel_hi:[1,1,1]
	v_pk_fma_f32 v[100:101], v[192:193], v[170:171], v[100:101] op_sel:[0,0,0] op_sel_hi:[1,0,1]
	v_add_f32_dpp v48, v48, v48 quad_perm:[2,3,0,1] row_mask:0xf bank_mask:0xf bound_ctrl:1
	v_add_f32_dpp v49, v49, v49 quad_perm:[2,3,0,1] row_mask:0xf bank_mask:0xf bound_ctrl:1
	v_add_f32_dpp v50, v50, v50 quad_perm:[2,3,0,1] row_mask:0xf bank_mask:0xf bound_ctrl:1
	v_add_f32_dpp v51, v51, v51 quad_perm:[2,3,0,1] row_mask:0xf bank_mask:0xf bound_ctrl:1
	v_pk_fma_f32 v[102:103], v[192:193], v[170:171], v[102:103] op_sel:[0,1,0] op_sel_hi:[1,1,1]
	v_pk_fma_f32 v[104:105], v[192:193], v[172:173], v[104:105] op_sel:[0,0,0] op_sel_hi:[1,0,1]
	v_pk_fma_f32 v[106:107], v[192:193], v[172:173], v[106:107] op_sel:[0,1,0] op_sel_hi:[1,1,1]
	v_add_f32_dpp v50, v50, v50 row_half_mirror row_mask:0xf bank_mask:0xf bound_ctrl:1
	v_add_f32_dpp v51, v51, v51 row_half_mirror row_mask:0xf bank_mask:0xf bound_ctrl:1
	v_pk_fma_f32 v[108:109], v[192:193], v[174:175], v[108:109] op_sel:[0,0,0] op_sel_hi:[1,0,1]
	s_mov_b64 exec, s[86:87]
	ds_write_b64 v45, v[48:49] offset:5120
	s_mov_b64 exec, s[0:1]
	v_pk_fma_f32 v[110:111], v[192:193], v[174:175], v[110:111] op_sel:[0,1,0] op_sel_hi:[1,1,1]
	s_nop 0
	v_pk_fma_f32 v[96:97], v[50:51], v[176:177], v[96:97] op_sel:[0,0,0] op_sel_hi:[1,0,1]
	v_pk_fma_f32 v[98:99], v[50:51], v[176:177], v[98:99] op_sel:[0,1,0] op_sel_hi:[1,1,1]
	v_pk_fma_f32 v[100:101], v[50:51], v[178:179], v[100:101] op_sel:[0,0,0] op_sel_hi:[1,0,1]
	v_pk_fma_f32 v[102:103], v[50:51], v[178:179], v[102:103] op_sel:[0,1,0] op_sel_hi:[1,1,1]
	v_pk_fma_f32 v[104:105], v[50:51], v[180:181], v[104:105] op_sel:[0,0,0] op_sel_hi:[1,0,1]
	v_pk_fma_f32 v[106:107], v[50:51], v[180:181], v[106:107] op_sel:[0,1,0] op_sel_hi:[1,1,1]
	v_pk_fma_f32 v[108:109], v[50:51], v[182:183], v[108:109] op_sel:[0,0,0] op_sel_hi:[1,0,1]
	v_pk_fma_f32 v[110:111], v[50:51], v[182:183], v[110:111] op_sel:[0,1,0] op_sel_hi:[1,1,1]
	v_pk_mul_f32 v[48:49], v[96:97], v[184:185] op_sel:[0,0] op_sel_hi:[1,0]
	v_pk_mul_f32 v[50:51], v[96:97], v[148:149] op_sel:[0,0] op_sel_hi:[1,0]
	v_pk_fma_f32 v[48:49], v[98:99], v[184:185], v[48:49] op_sel:[0,1,0] op_sel_hi:[1,1,1]
	v_pk_fma_f32 v[50:51], v[98:99], v[148:149], v[50:51] op_sel:[0,1,0] op_sel_hi:[1,1,1]
	v_pk_fma_f32 v[48:49], v[100:101], v[186:187], v[48:49] op_sel:[0,0,0] op_sel_hi:[1,0,1]
	v_pk_fma_f32 v[50:51], v[100:101], v[150:151], v[50:51] op_sel:[0,0,0] op_sel_hi:[1,0,1]
	v_pk_fma_f32 v[48:49], v[102:103], v[186:187], v[48:49] op_sel:[0,1,0] op_sel_hi:[1,1,1]
	v_pk_fma_f32 v[50:51], v[102:103], v[150:151], v[50:51] op_sel:[0,1,0] op_sel_hi:[1,1,1]
	v_pk_fma_f32 v[48:49], v[104:105], v[188:189], v[48:49] op_sel:[0,0,0] op_sel_hi:[1,0,1]
	v_pk_fma_f32 v[50:51], v[104:105], v[152:153], v[50:51] op_sel:[0,0,0] op_sel_hi:[1,0,1]
	v_pk_fma_f32 v[48:49], v[106:107], v[188:189], v[48:49] op_sel:[0,1,0] op_sel_hi:[1,1,1]
	v_pk_fma_f32 v[50:51], v[106:107], v[152:153], v[50:51] op_sel:[0,1,0] op_sel_hi:[1,1,1]
	v_pk_fma_f32 v[48:49], v[108:109], v[190:191], v[48:49] op_sel:[0,0,0] op_sel_hi:[1,0,1]
	v_pk_fma_f32 v[50:51], v[108:109], v[154:155], v[50:51] op_sel:[0,0,0] op_sel_hi:[1,0,1]
	v_pk_fma_f32 v[48:49], v[110:111], v[190:191], v[48:49] op_sel:[0,1,0] op_sel_hi:[1,1,1]
	v_pk_fma_f32 v[50:51], v[110:111], v[154:155], v[50:51] op_sel:[0,1,0] op_sel_hi:[1,1,1]
	s_waitcnt lgkmcnt(11)
; #define LAS __attribute__((address_space(3)))
; __device__ __forceinline__ float red8(float x) { x += dpp_mov<0xB1>(x); x += dpp_mov<0x4E>(x); x += dpp_mov<0x141>(x); return x; }
; __device__ __forceinline__ void scan_phase(const KP& P, LAS unsigned char* lds, const int tid, const int bx, const int G) {
;     ...
;             for (int s = 0; s < 32; ++s) {
;                 const LAS float* p = cb + s * 384;
;                 const f32x4 w0 = *(const LAS f32x4*)(p), w1 = *(const LAS f32x4*)(p + 4);
;                 const f32x4 k0 = *(const LAS f32x4*)(p + 64), k1 = *(const LAS f32x4*)(p + 68);
;                 const f32x4 a0 = *(const LAS f32x4*)(p + 128), a1 = *(const LAS f32x4*)(p + 132);
;                 const f32x4 b0 = *(const LAS f32x4*)(p + 192), b1 = *(const LAS f32x4*)(p + 196);
;                 const f32x4 r0 = *(const LAS f32x4*)(p + 256), r1 = *(const LAS f32x4*)(p + 260);
;                 const float vv = buf[(c & 1) * 12288 + s * 384 + 320 + v];
;                 f32x2 sa2 = S[0] * (f32x2){a0.x, a0.y};
;                 sa2 += S[1] * (f32x2){a0.z, a0.w}; sa2 += S[2] * (f32x2){a1.x, a1.y}; sa2 += S[3] * (f32x2){a1.z, a1.w};
;                 const float sa = red8(sa2.x + sa2.y);
;                 const f32x2 sav = {sa, sa}, vv2 = {vv, vv};
;                 S[0] = S[0] * (f32x2){w0.x, w0.y} + sav * (f32x2){b0.x, b0.y} + vv2 * (f32x2){k0.x, k0.y};
;                 S[1] = S[1] * (f32x2){w0.z, w0.w} + sav * (f32x2){b0.z, b0.w} + vv2 * (f32x2){k0.z, k0.w};
;                 S[2] = S[2] * (f32x2){w1.x, w1.y} + sav * (f32x2){b1.x, b1.y} + vv2 * (f32x2){k1.x, k1.y};
;                 S[3] = S[3] * (f32x2){w1.z, w1.w} + sav * (f32x2){b1.z, b1.w} + vv2 * (f32x2){k1.z, k1.w};
;                 f32x2 y2 = S[0] * (f32x2){r0.x, r0.y};
;                 y2 += S[1] * (f32x2){r0.z, r0.w}; y2 += S[2] * (f32x2){r1.x, r1.y}; y2 += S[3] * (f32x2){r1.z, r1.w};
;                 const float y = red8(y2.x + y2.y);
;                 if (kc == 0) ybuf[s * 64 + v] = y;
;             }
	ds_read_b128 v[168:171], v44 offset:21760
	ds_read_b128 v[172:175], v44 offset:21776
	ds_read_b128 v[176:179], v44 offset:22272
	ds_read_b128 v[180:183], v44 offset:22288
	ds_read_b128 v[184:187], v44 offset:22528
	ds_read_b128 v[188:191], v44 offset:22544
	ds_read_b64 v[192:193], v46 offset:21504
	ds_read_b128 v[148:151], v44 offset:23552
	ds_read_b128 v[152:155], v44 offset:23568
	v_add_f32_dpp v48, v48, v48 quad_perm:[1,0,3,2] row_mask:0xf bank_mask:0xf bound_ctrl:1
	v_add_f32_dpp v49, v49, v49 quad_perm:[1,0,3,2] row_mask:0xf bank_mask:0xf bound_ctrl:1
	v_add_f32_dpp v50, v50, v50 quad_perm:[1,0,3,2] row_mask:0xf bank_mask:0xf bound_ctrl:1
	v_add_f32_dpp v51, v51, v51 quad_perm:[1,0,3,2] row_mask:0xf bank_mask:0xf bound_ctrl:1
	v_pk_fma_f32 v[96:97], v[144:145], v[120:121], v[96:97] op_sel:[0,0,0] op_sel_hi:[1,0,1]
	v_pk_fma_f32 v[98:99], v[144:145], v[120:121], v[98:99] op_sel:[0,1,0] op_sel_hi:[1,1,1]
	v_pk_fma_f32 v[100:101], v[144:145], v[122:123], v[100:101] op_sel:[0,0,0] op_sel_hi:[1,0,1]
	v_add_f32_dpp v48, v48, v48 quad_perm:[2,3,0,1] row_mask:0xf bank_mask:0xf bound_ctrl:1
	v_add_f32_dpp v49, v49, v49 quad_perm:[2,3,0,1] row_mask:0xf bank_mask:0xf bound_ctrl:1
	v_add_f32_dpp v50, v50, v50 quad_perm:[2,3,0,1] row_mask:0xf bank_mask:0xf bound_ctrl:1
	v_add_f32_dpp v51, v51, v51 quad_perm:[2,3,0,1] row_mask:0xf bank_mask:0xf bound_ctrl:1
	v_pk_fma_f32 v[102:103], v[144:145], v[122:123], v[102:103] op_sel:[0,1,0] op_sel_hi:[1,1,1]
	v_pk_fma_f32 v[104:105], v[144:145], v[124:125], v[104:105] op_sel:[0,0,0] op_sel_hi:[1,0,1]
	v_pk_fma_f32 v[106:107], v[144:145], v[124:125], v[106:107] op_sel:[0,1,0] op_sel_hi:[1,1,1]
	v_add_f32_dpp v50, v50, v50 row_half_mirror row_mask:0xf bank_mask:0xf bound_ctrl:1
	v_add_f32_dpp v51, v51, v51 row_half_mirror row_mask:0xf bank_mask:0xf bound_ctrl:1
	v_pk_fma_f32 v[108:109], v[144:145], v[126:127], v[108:109] op_sel:[0,0,0] op_sel_hi:[1,0,1]
	s_mov_b64 exec, s[86:87]
	ds_write_b64 v45, v[48:49] offset:5632
	s_mov_b64 exec, s[0:1]
	v_pk_fma_f32 v[110:111], v[144:145], v[126:127], v[110:111] op_sel:[0,1,0] op_sel_hi:[1,1,1]
	s_nop 0
	v_pk_fma_f32 v[96:97], v[50:51], v[128:129], v[96:97] op_sel:[0,0,0] op_sel_hi:[1,0,1]
	v_pk_fma_f32 v[98:99], v[50:51], v[128:129], v[98:99] op_sel:[0,1,0] op_sel_hi:[1,1,1]
	v_pk_fma_f32 v[100:101], v[50:51], v[130:131], v[100:101] op_sel:[0,0,0] op_sel_hi:[1,0,1]
	v_pk_fma_f32 v[102:103], v[50:51], v[130:131], v[102:103] op_sel:[0,1,0] op_sel_hi:[1,1,1]
	v_pk_fma_f32 v[104:105], v[50:51], v[132:133], v[104:105] op_sel:[0,0,0] op_sel_hi:[1,0,1]
	v_pk_fma_f32 v[106:107], v[50:51], v[132:133], v[106:107] op_sel:[0,1,0] op_sel_hi:[1,1,1]
	v_pk_fma_f32 v[108:109], v[50:51], v[134:135], v[108:109] op_sel:[0,0,0] op_sel_hi:[1,0,1]
	v_pk_fma_f32 v[110:111], v[50:51], v[134:135], v[110:111] op_sel:[0,1,0] op_sel_hi:[1,1,1]
	v_pk_mul_f32 v[48:49], v[96:97], v[136:137] op_sel:[0,0] op_sel_hi:[1,0]
	v_pk_mul_f32 v[50:51], v[96:97], v[156:157] op_sel:[0,0] op_sel_hi:[1,0]
	v_pk_fma_f32 v[48:49], v[98:99], v[136:137], v[48:49] op_sel:[0,1,0] op_sel_hi:[1,1,1]
	v_pk_fma_f32 v[50:51], v[98:99], v[156:157], v[50:51] op_sel:[0,1,0] op_sel_hi:[1,1,1]
	v_pk_fma_f32 v[48:49], v[100:101], v[138:139], v[48:49] op_sel:[0,0,0] op_sel_hi:[1,0,1]
	v_pk_fma_f32 v[50:51], v[100:101], v[158:159], v[50:51] op_sel:[0,0,0] op_sel_hi:[1,0,1]
	v_pk_fma_f32 v[48:49], v[102:103], v[138:139], v[48:49] op_sel:[0,1,0] op_sel_hi:[1,1,1]
	v_pk_fma_f32 v[50:51], v[102:103], v[158:159], v[50:51] op_sel:[0,1,0] op_sel_hi:[1,1,1]
	v_pk_fma_f32 v[48:49], v[104:105], v[140:141], v[48:49] op_sel:[0,0,0] op_sel_hi:[1,0,1]
	v_pk_fma_f32 v[50:51], v[104:105], v[160:161], v[50:51] op_sel:[0,0,0] op_sel_hi:[1,0,1]
	v_pk_fma_f32 v[48:49], v[106:107], v[140:141], v[48:49] op_sel:[0,1,0] op_sel_hi:[1,1,1]
	v_pk_fma_f32 v[50:51], v[106:107], v[160:161], v[50:51] op_sel:[0,1,0] op_sel_hi:[1,1,1]
	v_pk_fma_f32 v[48:49], v[108:109], v[142:143], v[48:49] op_sel:[0,0,0] op_sel_hi:[1,0,1]
	v_pk_fma_f32 v[50:51], v[108:109], v[162:163], v[50:51] op_sel:[0,0,0] op_sel_hi:[1,0,1]
	v_pk_fma_f32 v[48:49], v[110:111], v[142:143], v[48:49] op_sel:[0,1,0] op_sel_hi:[1,1,1]
	v_pk_fma_f32 v[50:51], v[110:111], v[162:163], v[50:51] op_sel:[0,1,0] op_sel_hi:[1,1,1]
	s_waitcnt lgkmcnt(11)
; #define LAS __attribute__((address_space(3)))
; __device__ __forceinline__ float red8(float x) { x += dpp_mov<0xB1>(x); x += dpp_mov<0x4E>(x); x += dpp_mov<0x141>(x); return x; }
; __device__ __forceinline__ void scan_phase(const KP& P, LAS unsigned char* lds, const int tid, const int bx, const int G) {
;     ...
;             for (int s = 0; s < 32; ++s) {
;                 const LAS float* p = cb + s * 384;
;                 const f32x4 w0 = *(const LAS f32x4*)(p), w1 = *(const LAS f32x4*)(p + 4);
;                 const f32x4 k0 = *(const LAS f32x4*)(p + 64), k1 = *(const LAS f32x4*)(p + 68);
;                 const f32x4 a0 = *(const LAS f32x4*)(p + 128), a1 = *(const LAS f32x4*)(p + 132);
;                 const f32x4 b0 = *(const LAS f32x4*)(p + 192), b1 = *(const LAS f32x4*)(p + 196);
;                 const f32x4 r0 = *(const LAS f32x4*)(p + 256), r1 = *(const LAS f32x4*)(p + 260);
;                 const float vv = buf[(c & 1) * 12288 + s * 384 + 320 + v];
;                 f32x2 sa2 = S[0] * (f32x2){a0.x, a0.y};
;                 sa2 += S[1] * (f32x2){a0.z, a0.w}; sa2 += S[2] * (f32x2){a1.x, a1.y}; sa2 += S[3] * (f32x2){a1.z, a1.w};
;                 const float sa = red8(sa2.x + sa2.y);
;                 const f32x2 sav = {sa, sa}, vv2 = {vv, vv};
;                 S[0] = S[0] * (f32x2){w0.x, w0.y} + sav * (f32x2){b0.x, b0.y} + vv2 * (f32x2){k0.x, k0.y};
;                 S[1] = S[1] * (f32x2){w0.z, w0.w} + sav * (f32x2){b0.z, b0.w} + vv2 * (f32x2){k0.z, k0.w};
;                 S[2] = S[2] * (f32x2){w1.x, w1.y} + sav * (f32x2){b1.x, b1.y} + vv2 * (f32x2){k1.x, k1.y};
;                 S[3] = S[3] * (f32x2){w1.z, w1.w} + sav * (f32x2){b1.z, b1.w} + vv2 * (f32x2){k1.z, k1.w};
;                 f32x2 y2 = S[0] * (f32x2){r0.x, r0.y};
;                 y2 += S[1] * (f32x2){r0.z, r0.w}; y2 += S[2] * (f32x2){r1.x, r1.y}; y2 += S[3] * (f32x2){r1.z, r1.w};
;                 const float y = red8(y2.x + y2.y);
;                 if (kc == 0) ybuf[s * 64 + v] = y;
;             }
	ds_read_b128 v[120:123], v44 offset:23296
	ds_read_b128 v[124:127], v44 offset:23312
	ds_read_b128 v[128:131], v44 offset:23808
	ds_read_b128 v[132:135], v44 offset:23824
	ds_read_b128 v[136:139], v44 offset:24064
	ds_read_b128 v[140:143], v44 offset:24080
	ds_read_b64 v[144:145], v46 offset:23040
	ds_read_b128 v[156:159], v44 offset:25088
	ds_read_b128 v[160:163], v44 offset:25104
	v_add_f32_dpp v48, v48, v48 quad_perm:[1,0,3,2] row_mask:0xf bank_mask:0xf bound_ctrl:1
	v_add_f32_dpp v49, v49, v49 quad_perm:[1,0,3,2] row_mask:0xf bank_mask:0xf bound_ctrl:1
	v_add_f32_dpp v50, v50, v50 quad_perm:[1,0,3,2] row_mask:0xf bank_mask:0xf bound_ctrl:1
	v_add_f32_dpp v51, v51, v51 quad_perm:[1,0,3,2] row_mask:0xf bank_mask:0xf bound_ctrl:1
	v_pk_fma_f32 v[96:97], v[146:147], v[70:71], v[96:97] op_sel:[0,0,0] op_sel_hi:[1,0,1]
	v_pk_fma_f32 v[98:99], v[146:147], v[70:71], v[98:99] op_sel:[0,1,0] op_sel_hi:[1,1,1]
	v_pk_fma_f32 v[100:101], v[146:147], v[72:73], v[100:101] op_sel:[0,0,0] op_sel_hi:[1,0,1]
	v_add_f32_dpp v48, v48, v48 quad_perm:[2,3,0,1] row_mask:0xf bank_mask:0xf bound_ctrl:1
	v_add_f32_dpp v49, v49, v49 quad_perm:[2,3,0,1] row_mask:0xf bank_mask:0xf bound_ctrl:1
	v_add_f32_dpp v50, v50, v50 quad_perm:[2,3,0,1] row_mask:0xf bank_mask:0xf bound_ctrl:1
	v_add_f32_dpp v51, v51, v51 quad_perm:[2,3,0,1] row_mask:0xf bank_mask:0xf bound_ctrl:1
	v_pk_fma_f32 v[102:103], v[146:147], v[72:73], v[102:103] op_sel:[0,1,0] op_sel_hi:[1,1,1]
	v_pk_fma_f32 v[104:105], v[146:147], v[74:75], v[104:105] op_sel:[0,0,0] op_sel_hi:[1,0,1]
	v_pk_fma_f32 v[106:107], v[146:147], v[74:75], v[106:107] op_sel:[0,1,0] op_sel_hi:[1,1,1]
	v_add_f32_dpp v50, v50, v50 row_half_mirror row_mask:0xf bank_mask:0xf bound_ctrl:1
	v_add_f32_dpp v51, v51, v51 row_half_mirror row_mask:0xf bank_mask:0xf bound_ctrl:1
	v_pk_fma_f32 v[108:109], v[146:147], v[76:77], v[108:109] op_sel:[0,0,0] op_sel_hi:[1,0,1]
	s_mov_b64 exec, s[86:87]
	ds_write_b64 v45, v[48:49] offset:6144
	s_mov_b64 exec, s[0:1]
	v_pk_fma_f32 v[110:111], v[146:147], v[76:77], v[110:111] op_sel:[0,1,0] op_sel_hi:[1,1,1]
	s_nop 0
	v_pk_fma_f32 v[96:97], v[50:51], v[78:79], v[96:97] op_sel:[0,0,0] op_sel_hi:[1,0,1]
	v_pk_fma_f32 v[98:99], v[50:51], v[78:79], v[98:99] op_sel:[0,1,0] op_sel_hi:[1,1,1]
	v_pk_fma_f32 v[100:101], v[50:51], v[80:81], v[100:101] op_sel:[0,0,0] op_sel_hi:[1,0,1]
	v_pk_fma_f32 v[102:103], v[50:51], v[80:81], v[102:103] op_sel:[0,1,0] op_sel_hi:[1,1,1]
	v_pk_fma_f32 v[104:105], v[50:51], v[82:83], v[104:105] op_sel:[0,0,0] op_sel_hi:[1,0,1]
	v_pk_fma_f32 v[106:107], v[50:51], v[82:83], v[106:107] op_sel:[0,1,0] op_sel_hi:[1,1,1]
	v_pk_fma_f32 v[108:109], v[50:51], v[84:85], v[108:109] op_sel:[0,0,0] op_sel_hi:[1,0,1]
	v_pk_fma_f32 v[110:111], v[50:51], v[84:85], v[110:111] op_sel:[0,1,0] op_sel_hi:[1,1,1]
	v_pk_mul_f32 v[48:49], v[96:97], v[86:87] op_sel:[0,0] op_sel_hi:[1,0]
	v_pk_mul_f32 v[50:51], v[96:97], v[62:63] op_sel:[0,0] op_sel_hi:[1,0]
	v_pk_fma_f32 v[48:49], v[98:99], v[86:87], v[48:49] op_sel:[0,1,0] op_sel_hi:[1,1,1]
	v_pk_fma_f32 v[50:51], v[98:99], v[62:63], v[50:51] op_sel:[0,1,0] op_sel_hi:[1,1,1]
	v_pk_fma_f32 v[48:49], v[100:101], v[88:89], v[48:49] op_sel:[0,0,0] op_sel_hi:[1,0,1]
	v_pk_fma_f32 v[50:51], v[100:101], v[64:65], v[50:51] op_sel:[0,0,0] op_sel_hi:[1,0,1]
	v_pk_fma_f32 v[48:49], v[102:103], v[88:89], v[48:49] op_sel:[0,1,0] op_sel_hi:[1,1,1]
	v_pk_fma_f32 v[50:51], v[102:103], v[64:65], v[50:51] op_sel:[0,1,0] op_sel_hi:[1,1,1]
	v_pk_fma_f32 v[48:49], v[104:105], v[90:91], v[48:49] op_sel:[0,0,0] op_sel_hi:[1,0,1]
	v_pk_fma_f32 v[50:51], v[104:105], v[66:67], v[50:51] op_sel:[0,0,0] op_sel_hi:[1,0,1]
	v_pk_fma_f32 v[48:49], v[106:107], v[90:91], v[48:49] op_sel:[0,1,0] op_sel_hi:[1,1,1]
	v_pk_fma_f32 v[50:51], v[106:107], v[66:67], v[50:51] op_sel:[0,1,0] op_sel_hi:[1,1,1]
	v_pk_fma_f32 v[48:49], v[108:109], v[92:93], v[48:49] op_sel:[0,0,0] op_sel_hi:[1,0,1]
	v_pk_fma_f32 v[50:51], v[108:109], v[68:69], v[50:51] op_sel:[0,0,0] op_sel_hi:[1,0,1]
	v_pk_fma_f32 v[48:49], v[110:111], v[92:93], v[48:49] op_sel:[0,1,0] op_sel_hi:[1,1,1]
	v_pk_fma_f32 v[50:51], v[110:111], v[68:69], v[50:51] op_sel:[0,1,0] op_sel_hi:[1,1,1]
	s_waitcnt lgkmcnt(11)
	ds_read_b128 v[70:73], v44 offset:24832
	ds_read_b128 v[74:77], v44 offset:24848
	ds_read_b128 v[78:81], v44 offset:25344
	ds_read_b128 v[82:85], v44 offset:25360
	ds_read_b128 v[86:89], v44 offset:25600
	ds_read_b128 v[90:93], v44 offset:25616
	ds_read_b64 v[146:147], v46 offset:24576
	ds_read_b128 v[62:65], v44 offset:26624
	ds_read_b128 v[66:69], v44 offset:26640
	v_add_f32_dpp v48, v48, v48 quad_perm:[1,0,3,2] row_mask:0xf bank_mask:0xf bound_ctrl:1
	v_add_f32_dpp v49, v49, v49 quad_perm:[1,0,3,2] row_mask:0xf bank_mask:0xf bound_ctrl:1
	v_add_f32_dpp v50, v50, v50 quad_perm:[1,0,3,2] row_mask:0xf bank_mask:0xf bound_ctrl:1
	v_add_f32_dpp v51, v51, v51 quad_perm:[1,0,3,2] row_mask:0xf bank_mask:0xf bound_ctrl:1
	v_pk_fma_f32 v[96:97], v[192:193], v[168:169], v[96:97] op_sel:[0,0,0] op_sel_hi:[1,0,1]
	v_pk_fma_f32 v[98:99], v[192:193], v[168:169], v[98:99] op_sel:[0,1,0] op_sel_hi:[1,1,1]
	v_pk_fma_f32 v[100:101], v[192:193], v[170:171], v[100:101] op_sel:[0,0,0] op_sel_hi:[1,0,1]
	v_add_f32_dpp v48, v48, v48 quad_perm:[2,3,0,1] row_mask:0xf bank_mask:0xf bound_ctrl:1
	v_add_f32_dpp v49, v49, v49 quad_perm:[2,3,0,1] row_mask:0xf bank_mask:0xf bound_ctrl:1
	v_add_f32_dpp v50, v50, v50 quad_perm:[2,3,0,1] row_mask:0xf bank_mask:0xf bound_ctrl:1
	v_add_f32_dpp v51, v51, v51 quad_perm:[2,3,0,1] row_mask:0xf bank_mask:0xf bound_ctrl:1
	v_pk_fma_f32 v[102:103], v[192:193], v[170:171], v[102:103] op_sel:[0,1,0] op_sel_hi:[1,1,1]
; #define LAS __attribute__((address_space(3)))
; __device__ __forceinline__ float red8(float x) { x += dpp_mov<0xB1>(x); x += dpp_mov<0x4E>(x); x += dpp_mov<0x141>(x); return x; }
; __device__ __forceinline__ void scan_phase(const KP& P, LAS unsigned char* lds, const int tid, const int bx, const int G) {
;     ...
;             for (int s = 0; s < 32; ++s) {
;                 const LAS float* p = cb + s * 384;
;                 const f32x4 w0 = *(const LAS f32x4*)(p), w1 = *(const LAS f32x4*)(p + 4);
;                 const f32x4 k0 = *(const LAS f32x4*)(p + 64), k1 = *(const LAS f32x4*)(p + 68);
;                 const f32x4 a0 = *(const LAS f32x4*)(p + 128), a1 = *(const LAS f32x4*)(p + 132);
;                 const f32x4 b0 = *(const LAS f32x4*)(p + 192), b1 = *(const LAS f32x4*)(p + 196);
;                 const f32x4 r0 = *(const LAS f32x4*)(p + 256), r1 = *(const LAS f32x4*)(p + 260);
;                 const float vv = buf[(c & 1) * 12288 + s * 384 + 320 + v];
;                 f32x2 sa2 = S[0] * (f32x2){a0.x, a0.y};
;                 sa2 += S[1] * (f32x2){a0.z, a0.w}; sa2 += S[2] * (f32x2){a1.x, a1.y}; sa2 += S[3] * (f32x2){a1.z, a1.w};
;                 const float sa = red8(sa2.x + sa2.y);
;                 const f32x2 sav = {sa, sa}, vv2 = {vv, vv};
;                 S[0] = S[0] * (f32x2){w0.x, w0.y} + sav * (f32x2){b0.x, b0.y} + vv2 * (f32x2){k0.x, k0.y};
;                 S[1] = S[1] * (f32x2){w0.z, w0.w} + sav * (f32x2){b0.z, b0.w} + vv2 * (f32x2){k0.z, k0.w};
;                 S[2] = S[2] * (f32x2){w1.x, w1.y} + sav * (f32x2){b1.x, b1.y} + vv2 * (f32x2){k1.x, k1.y};
;                 S[3] = S[3] * (f32x2){w1.z, w1.w} + sav * (f32x2){b1.z, b1.w} + vv2 * (f32x2){k1.z, k1.w};
;                 f32x2 y2 = S[0] * (f32x2){r0.x, r0.y};
;                 y2 += S[1] * (f32x2){r0.z, r0.w}; y2 += S[2] * (f32x2){r1.x, r1.y}; y2 += S[3] * (f32x2){r1.z, r1.w};
;                 const float y = red8(y2.x + y2.y);
;                 if (kc == 0) ybuf[s * 64 + v] = y;
;             }
	v_pk_fma_f32 v[104:105], v[192:193], v[172:173], v[104:105] op_sel:[0,0,0] op_sel_hi:[1,0,1]
	v_pk_fma_f32 v[106:107], v[192:193], v[172:173], v[106:107] op_sel:[0,1,0] op_sel_hi:[1,1,1]
	v_add_f32_dpp v50, v50, v50 row_half_mirror row_mask:0xf bank_mask:0xf bound_ctrl:1
	v_add_f32_dpp v51, v51, v51 row_half_mirror row_mask:0xf bank_mask:0xf bound_ctrl:1
	v_pk_fma_f32 v[108:109], v[192:193], v[174:175], v[108:109] op_sel:[0,0,0] op_sel_hi:[1,0,1]
	s_mov_b64 exec, s[86:87]
	ds_write_b64 v45, v[48:49] offset:6656
	s_mov_b64 exec, s[0:1]
	v_pk_fma_f32 v[110:111], v[192:193], v[174:175], v[110:111] op_sel:[0,1,0] op_sel_hi:[1,1,1]
	s_nop 0
	v_pk_fma_f32 v[96:97], v[50:51], v[176:177], v[96:97] op_sel:[0,0,0] op_sel_hi:[1,0,1]
	v_pk_fma_f32 v[98:99], v[50:51], v[176:177], v[98:99] op_sel:[0,1,0] op_sel_hi:[1,1,1]
	v_pk_fma_f32 v[100:101], v[50:51], v[178:179], v[100:101] op_sel:[0,0,0] op_sel_hi:[1,0,1]
	v_pk_fma_f32 v[102:103], v[50:51], v[178:179], v[102:103] op_sel:[0,1,0] op_sel_hi:[1,1,1]
	v_pk_fma_f32 v[104:105], v[50:51], v[180:181], v[104:105] op_sel:[0,0,0] op_sel_hi:[1,0,1]
	v_pk_fma_f32 v[106:107], v[50:51], v[180:181], v[106:107] op_sel:[0,1,0] op_sel_hi:[1,1,1]
	v_pk_fma_f32 v[108:109], v[50:51], v[182:183], v[108:109] op_sel:[0,0,0] op_sel_hi:[1,0,1]
	v_pk_fma_f32 v[110:111], v[50:51], v[182:183], v[110:111] op_sel:[0,1,0] op_sel_hi:[1,1,1]
	v_pk_mul_f32 v[48:49], v[96:97], v[184:185] op_sel:[0,0] op_sel_hi:[1,0]
	v_pk_mul_f32 v[50:51], v[96:97], v[148:149] op_sel:[0,0] op_sel_hi:[1,0]
	v_pk_fma_f32 v[48:49], v[98:99], v[184:185], v[48:49] op_sel:[0,1,0] op_sel_hi:[1,1,1]
	v_pk_fma_f32 v[50:51], v[98:99], v[148:149], v[50:51] op_sel:[0,1,0] op_sel_hi:[1,1,1]
	v_pk_fma_f32 v[48:49], v[100:101], v[186:187], v[48:49] op_sel:[0,0,0] op_sel_hi:[1,0,1]
	v_pk_fma_f32 v[50:51], v[100:101], v[150:151], v[50:51] op_sel:[0,0,0] op_sel_hi:[1,0,1]
	v_pk_fma_f32 v[48:49], v[102:103], v[186:187], v[48:49] op_sel:[0,1,0] op_sel_hi:[1,1,1]
	v_pk_fma_f32 v[50:51], v[102:103], v[150:151], v[50:51] op_sel:[0,1,0] op_sel_hi:[1,1,1]
	v_pk_fma_f32 v[48:49], v[104:105], v[188:189], v[48:49] op_sel:[0,0,0] op_sel_hi:[1,0,1]
	v_pk_fma_f32 v[50:51], v[104:105], v[152:153], v[50:51] op_sel:[0,0,0] op_sel_hi:[1,0,1]
	v_pk_fma_f32 v[48:49], v[106:107], v[188:189], v[48:49] op_sel:[0,1,0] op_sel_hi:[1,1,1]
	v_pk_fma_f32 v[50:51], v[106:107], v[152:153], v[50:51] op_sel:[0,1,0] op_sel_hi:[1,1,1]
	v_pk_fma_f32 v[48:49], v[108:109], v[190:191], v[48:49] op_sel:[0,0,0] op_sel_hi:[1,0,1]
	v_pk_fma_f32 v[50:51], v[108:109], v[154:155], v[50:51] op_sel:[0,0,0] op_sel_hi:[1,0,1]
	v_pk_fma_f32 v[48:49], v[110:111], v[190:191], v[48:49] op_sel:[0,1,0] op_sel_hi:[1,1,1]
	v_pk_fma_f32 v[50:51], v[110:111], v[154:155], v[50:51] op_sel:[0,1,0] op_sel_hi:[1,1,1]
	s_waitcnt lgkmcnt(11)
	ds_read_b128 v[168:171], v44 offset:26368
	ds_read_b128 v[172:175], v44 offset:26384
	ds_read_b128 v[176:179], v44 offset:26880
	ds_read_b128 v[180:183], v44 offset:26896
	ds_read_b128 v[184:187], v44 offset:27136
	ds_read_b128 v[188:191], v44 offset:27152
	ds_read_b64 v[192:193], v46 offset:26112
	ds_read_b128 v[148:151], v44 offset:28160
	ds_read_b128 v[152:155], v44 offset:28176
	v_add_f32_dpp v48, v48, v48 quad_perm:[1,0,3,2] row_mask:0xf bank_mask:0xf bound_ctrl:1
	v_add_f32_dpp v49, v49, v49 quad_perm:[1,0,3,2] row_mask:0xf bank_mask:0xf bound_ctrl:1
	v_add_f32_dpp v50, v50, v50 quad_perm:[1,0,3,2] row_mask:0xf bank_mask:0xf bound_ctrl:1
	v_add_f32_dpp v51, v51, v51 quad_perm:[1,0,3,2] row_mask:0xf bank_mask:0xf bound_ctrl:1
	v_pk_fma_f32 v[96:97], v[144:145], v[120:121], v[96:97] op_sel:[0,0,0] op_sel_hi:[1,0,1]
	v_pk_fma_f32 v[98:99], v[144:145], v[120:121], v[98:99] op_sel:[0,1,0] op_sel_hi:[1,1,1]
	v_pk_fma_f32 v[100:101], v[144:145], v[122:123], v[100:101] op_sel:[0,0,0] op_sel_hi:[1,0,1]
	v_add_f32_dpp v48, v48, v48 quad_perm:[2,3,0,1] row_mask:0xf bank_mask:0xf bound_ctrl:1
	v_add_f32_dpp v49, v49, v49 quad_perm:[2,3,0,1] row_mask:0xf bank_mask:0xf bound_ctrl:1
	v_add_f32_dpp v50, v50, v50 quad_perm:[2,3,0,1] row_mask:0xf bank_mask:0xf bound_ctrl:1
	v_add_f32_dpp v51, v51, v51 quad_perm:[2,3,0,1] row_mask:0xf bank_mask:0xf bound_ctrl:1
	v_pk_fma_f32 v[102:103], v[144:145], v[122:123], v[102:103] op_sel:[0,1,0] op_sel_hi:[1,1,1]
	v_pk_fma_f32 v[104:105], v[144:145], v[124:125], v[104:105] op_sel:[0,0,0] op_sel_hi:[1,0,1]
	v_pk_fma_f32 v[106:107], v[144:145], v[124:125], v[106:107] op_sel:[0,1,0] op_sel_hi:[1,1,1]
	v_add_f32_dpp v50, v50, v50 row_half_mirror row_mask:0xf bank_mask:0xf bound_ctrl:1
	v_add_f32_dpp v51, v51, v51 row_half_mirror row_mask:0xf bank_mask:0xf bound_ctrl:1
	v_pk_fma_f32 v[108:109], v[144:145], v[126:127], v[108:109] op_sel:[0,0,0] op_sel_hi:[1,0,1]
	s_mov_b64 exec, s[86:87]
	ds_write_b64 v45, v[48:49] offset:7168
	s_mov_b64 exec, s[0:1]
	v_pk_fma_f32 v[110:111], v[144:145], v[126:127], v[110:111] op_sel:[0,1,0] op_sel_hi:[1,1,1]
	s_nop 0
	v_pk_fma_f32 v[96:97], v[50:51], v[128:129], v[96:97] op_sel:[0,0,0] op_sel_hi:[1,0,1]
	v_pk_fma_f32 v[98:99], v[50:51], v[128:129], v[98:99] op_sel:[0,1,0] op_sel_hi:[1,1,1]
	v_pk_fma_f32 v[100:101], v[50:51], v[130:131], v[100:101] op_sel:[0,0,0] op_sel_hi:[1,0,1]
	v_pk_fma_f32 v[102:103], v[50:51], v[130:131], v[102:103] op_sel:[0,1,0] op_sel_hi:[1,1,1]
	v_pk_fma_f32 v[104:105], v[50:51], v[132:133], v[104:105] op_sel:[0,0,0] op_sel_hi:[1,0,1]
	v_pk_fma_f32 v[106:107], v[50:51], v[132:133], v[106:107] op_sel:[0,1,0] op_sel_hi:[1,1,1]
	v_pk_fma_f32 v[108:109], v[50:51], v[134:135], v[108:109] op_sel:[0,0,0] op_sel_hi:[1,0,1]
	v_pk_fma_f32 v[110:111], v[50:51], v[134:135], v[110:111] op_sel:[0,1,0] op_sel_hi:[1,1,1]
; #define LAS __attribute__((address_space(3)))
; __device__ __forceinline__ float red8(float x) { x += dpp_mov<0xB1>(x); x += dpp_mov<0x4E>(x); x += dpp_mov<0x141>(x); return x; }
; __device__ __forceinline__ void scan_phase(const KP& P, LAS unsigned char* lds, const int tid, const int bx, const int G) {
;     ...
;             for (int s = 0; s < 32; ++s) {
;                 const LAS float* p = cb + s * 384;
;                 const f32x4 w0 = *(const LAS f32x4*)(p), w1 = *(const LAS f32x4*)(p + 4);
;                 const f32x4 k0 = *(const LAS f32x4*)(p + 64), k1 = *(const LAS f32x4*)(p + 68);
;                 const f32x4 a0 = *(const LAS f32x4*)(p + 128), a1 = *(const LAS f32x4*)(p + 132);
;                 const f32x4 b0 = *(const LAS f32x4*)(p + 192), b1 = *(const LAS f32x4*)(p + 196);
;                 const f32x4 r0 = *(const LAS f32x4*)(p + 256), r1 = *(const LAS f32x4*)(p + 260);
;                 const float vv = buf[(c & 1) * 12288 + s * 384 + 320 + v];
;                 f32x2 sa2 = S[0] * (f32x2){a0.x, a0.y};
;                 sa2 += S[1] * (f32x2){a0.z, a0.w}; sa2 += S[2] * (f32x2){a1.x, a1.y}; sa2 += S[3] * (f32x2){a1.z, a1.w};
;                 const float sa = red8(sa2.x + sa2.y);
;                 const f32x2 sav = {sa, sa}, vv2 = {vv, vv};
;                 S[0] = S[0] * (f32x2){w0.x, w0.y} + sav * (f32x2){b0.x, b0.y} + vv2 * (f32x2){k0.x, k0.y};
;                 S[1] = S[1] * (f32x2){w0.z, w0.w} + sav * (f32x2){b0.z, b0.w} + vv2 * (f32x2){k0.z, k0.w};
;                 S[2] = S[2] * (f32x2){w1.x, w1.y} + sav * (f32x2){b1.x, b1.y} + vv2 * (f32x2){k1.x, k1.y};
;                 S[3] = S[3] * (f32x2){w1.z, w1.w} + sav * (f32x2){b1.z, b1.w} + vv2 * (f32x2){k1.z, k1.w};
;                 f32x2 y2 = S[0] * (f32x2){r0.x, r0.y};
;                 y2 += S[1] * (f32x2){r0.z, r0.w}; y2 += S[2] * (f32x2){r1.x, r1.y}; y2 += S[3] * (f32x2){r1.z, r1.w};
;                 const float y = red8(y2.x + y2.y);
;                 if (kc == 0) ybuf[s * 64 + v] = y;
;             }
	v_pk_mul_f32 v[48:49], v[96:97], v[136:137] op_sel:[0,0] op_sel_hi:[1,0]
	v_pk_mul_f32 v[50:51], v[96:97], v[156:157] op_sel:[0,0] op_sel_hi:[1,0]
	v_pk_fma_f32 v[48:49], v[98:99], v[136:137], v[48:49] op_sel:[0,1,0] op_sel_hi:[1,1,1]
	v_pk_fma_f32 v[50:51], v[98:99], v[156:157], v[50:51] op_sel:[0,1,0] op_sel_hi:[1,1,1]
	v_pk_fma_f32 v[48:49], v[100:101], v[138:139], v[48:49] op_sel:[0,0,0] op_sel_hi:[1,0,1]
	v_pk_fma_f32 v[50:51], v[100:101], v[158:159], v[50:51] op_sel:[0,0,0] op_sel_hi:[1,0,1]
	v_pk_fma_f32 v[48:49], v[102:103], v[138:139], v[48:49] op_sel:[0,1,0] op_sel_hi:[1,1,1]
	v_pk_fma_f32 v[50:51], v[102:103], v[158:159], v[50:51] op_sel:[0,1,0] op_sel_hi:[1,1,1]
	v_pk_fma_f32 v[48:49], v[104:105], v[140:141], v[48:49] op_sel:[0,0,0] op_sel_hi:[1,0,1]
	v_pk_fma_f32 v[50:51], v[104:105], v[160:161], v[50:51] op_sel:[0,0,0] op_sel_hi:[1,0,1]
	v_pk_fma_f32 v[48:49], v[106:107], v[140:141], v[48:49] op_sel:[0,1,0] op_sel_hi:[1,1,1]
	v_pk_fma_f32 v[50:51], v[106:107], v[160:161], v[50:51] op_sel:[0,1,0] op_sel_hi:[1,1,1]
	v_pk_fma_f32 v[48:49], v[108:109], v[142:143], v[48:49] op_sel:[0,0,0] op_sel_hi:[1,0,1]
	v_pk_fma_f32 v[50:51], v[108:109], v[162:163], v[50:51] op_sel:[0,0,0] op_sel_hi:[1,0,1]
	v_pk_fma_f32 v[48:49], v[110:111], v[142:143], v[48:49] op_sel:[0,1,0] op_sel_hi:[1,1,1]
	v_pk_fma_f32 v[50:51], v[110:111], v[162:163], v[50:51] op_sel:[0,1,0] op_sel_hi:[1,1,1]
	s_waitcnt lgkmcnt(11)
	ds_read_b128 v[120:123], v44 offset:27904
	ds_read_b128 v[124:127], v44 offset:27920
	ds_read_b128 v[128:131], v44 offset:28416
	ds_read_b128 v[132:135], v44 offset:28432
	ds_read_b128 v[136:139], v44 offset:28672
	ds_read_b128 v[140:143], v44 offset:28688
	ds_read_b64 v[144:145], v46 offset:27648
	ds_read_b128 v[156:159], v44 offset:29696
	ds_read_b128 v[160:163], v44 offset:29712
	v_add_f32_dpp v48, v48, v48 quad_perm:[1,0,3,2] row_mask:0xf bank_mask:0xf bound_ctrl:1
	v_add_f32_dpp v49, v49, v49 quad_perm:[1,0,3,2] row_mask:0xf bank_mask:0xf bound_ctrl:1
	v_add_f32_dpp v50, v50, v50 quad_perm:[1,0,3,2] row_mask:0xf bank_mask:0xf bound_ctrl:1
	v_add_f32_dpp v51, v51, v51 quad_perm:[1,0,3,2] row_mask:0xf bank_mask:0xf bound_ctrl:1
	v_pk_fma_f32 v[96:97], v[146:147], v[70:71], v[96:97] op_sel:[0,0,0] op_sel_hi:[1,0,1]
	v_pk_fma_f32 v[98:99], v[146:147], v[70:71], v[98:99] op_sel:[0,1,0] op_sel_hi:[1,1,1]
	v_pk_fma_f32 v[100:101], v[146:147], v[72:73], v[100:101] op_sel:[0,0,0] op_sel_hi:[1,0,1]
	v_add_f32_dpp v48, v48, v48 quad_perm:[2,3,0,1] row_mask:0xf bank_mask:0xf bound_ctrl:1
	v_add_f32_dpp v49, v49, v49 quad_perm:[2,3,0,1] row_mask:0xf bank_mask:0xf bound_ctrl:1
	v_add_f32_dpp v50, v50, v50 quad_perm:[2,3,0,1] row_mask:0xf bank_mask:0xf bound_ctrl:1
	v_add_f32_dpp v51, v51, v51 quad_perm:[2,3,0,1] row_mask:0xf bank_mask:0xf bound_ctrl:1
	v_pk_fma_f32 v[102:103], v[146:147], v[72:73], v[102:103] op_sel:[0,1,0] op_sel_hi:[1,1,1]
	v_pk_fma_f32 v[104:105], v[146:147], v[74:75], v[104:105] op_sel:[0,0,0] op_sel_hi:[1,0,1]
	v_pk_fma_f32 v[106:107], v[146:147], v[74:75], v[106:107] op_sel:[0,1,0] op_sel_hi:[1,1,1]
	v_add_f32_dpp v50, v50, v50 row_half_mirror row_mask:0xf bank_mask:0xf bound_ctrl:1
	v_add_f32_dpp v51, v51, v51 row_half_mirror row_mask:0xf bank_mask:0xf bound_ctrl:1
	v_pk_fma_f32 v[108:109], v[146:147], v[76:77], v[108:109] op_sel:[0,0,0] op_sel_hi:[1,0,1]
	s_mov_b64 exec, s[86:87]
	ds_write_b64 v45, v[48:49] offset:7680
	s_mov_b64 exec, s[0:1]
	v_pk_fma_f32 v[110:111], v[146:147], v[76:77], v[110:111] op_sel:[0,1,0] op_sel_hi:[1,1,1]
	s_nop 0
	v_pk_fma_f32 v[96:97], v[50:51], v[78:79], v[96:97] op_sel:[0,0,0] op_sel_hi:[1,0,1]
	v_pk_fma_f32 v[98:99], v[50:51], v[78:79], v[98:99] op_sel:[0,1,0] op_sel_hi:[1,1,1]
	v_pk_fma_f32 v[100:101], v[50:51], v[80:81], v[100:101] op_sel:[0,0,0] op_sel_hi:[1,0,1]
	v_pk_fma_f32 v[102:103], v[50:51], v[80:81], v[102:103] op_sel:[0,1,0] op_sel_hi:[1,1,1]
	v_pk_fma_f32 v[104:105], v[50:51], v[82:83], v[104:105] op_sel:[0,0,0] op_sel_hi:[1,0,1]
	v_pk_fma_f32 v[106:107], v[50:51], v[82:83], v[106:107] op_sel:[0,1,0] op_sel_hi:[1,1,1]
	v_pk_fma_f32 v[108:109], v[50:51], v[84:85], v[108:109] op_sel:[0,0,0] op_sel_hi:[1,0,1]
	v_pk_fma_f32 v[110:111], v[50:51], v[84:85], v[110:111] op_sel:[0,1,0] op_sel_hi:[1,1,1]
	v_pk_mul_f32 v[48:49], v[96:97], v[86:87] op_sel:[0,0] op_sel_hi:[1,0]
	v_pk_mul_f32 v[50:51], v[96:97], v[62:63] op_sel:[0,0] op_sel_hi:[1,0]
	v_pk_fma_f32 v[48:49], v[98:99], v[86:87], v[48:49] op_sel:[0,1,0] op_sel_hi:[1,1,1]
	v_pk_fma_f32 v[50:51], v[98:99], v[62:63], v[50:51] op_sel:[0,1,0] op_sel_hi:[1,1,1]
	v_pk_fma_f32 v[48:49], v[100:101], v[88:89], v[48:49] op_sel:[0,0,0] op_sel_hi:[1,0,1]
	v_pk_fma_f32 v[50:51], v[100:101], v[64:65], v[50:51] op_sel:[0,0,0] op_sel_hi:[1,0,1]
	v_pk_fma_f32 v[48:49], v[102:103], v[88:89], v[48:49] op_sel:[0,1,0] op_sel_hi:[1,1,1]
	v_pk_fma_f32 v[50:51], v[102:103], v[64:65], v[50:51] op_sel:[0,1,0] op_sel_hi:[1,1,1]
	v_pk_fma_f32 v[48:49], v[104:105], v[90:91], v[48:49] op_sel:[0,0,0] op_sel_hi:[1,0,1]
	v_pk_fma_f32 v[50:51], v[104:105], v[66:67], v[50:51] op_sel:[0,0,0] op_sel_hi:[1,0,1]
	v_pk_fma_f32 v[48:49], v[106:107], v[90:91], v[48:49] op_sel:[0,1,0] op_sel_hi:[1,1,1]
	v_pk_fma_f32 v[50:51], v[106:107], v[66:67], v[50:51] op_sel:[0,1,0] op_sel_hi:[1,1,1]
	v_pk_fma_f32 v[48:49], v[108:109], v[92:93], v[48:49] op_sel:[0,0,0] op_sel_hi:[1,0,1]
	v_pk_fma_f32 v[50:51], v[108:109], v[68:69], v[50:51] op_sel:[0,0,0] op_sel_hi:[1,0,1]
	v_pk_fma_f32 v[48:49], v[110:111], v[92:93], v[48:49] op_sel:[0,1,0] op_sel_hi:[1,1,1]
	v_pk_fma_f32 v[50:51], v[110:111], v[68:69], v[50:51] op_sel:[0,1,0] op_sel_hi:[1,1,1]
	s_waitcnt lgkmcnt(11)
; #define LAS __attribute__((address_space(3)))
; __device__ __forceinline__ float red8(float x) { x += dpp_mov<0xB1>(x); x += dpp_mov<0x4E>(x); x += dpp_mov<0x141>(x); return x; }
; __device__ __forceinline__ void scan_phase(const KP& P, LAS unsigned char* lds, const int tid, const int bx, const int G) {
;     ...
;             for (int s = 0; s < 32; ++s) {
;                 const LAS float* p = cb + s * 384;
;                 const f32x4 w0 = *(const LAS f32x4*)(p), w1 = *(const LAS f32x4*)(p + 4);
;                 const f32x4 k0 = *(const LAS f32x4*)(p + 64), k1 = *(const LAS f32x4*)(p + 68);
;                 const f32x4 a0 = *(const LAS f32x4*)(p + 128), a1 = *(const LAS f32x4*)(p + 132);
;                 const f32x4 b0 = *(const LAS f32x4*)(p + 192), b1 = *(const LAS f32x4*)(p + 196);
;                 const f32x4 r0 = *(const LAS f32x4*)(p + 256), r1 = *(const LAS f32x4*)(p + 260);
;                 const float vv = buf[(c & 1) * 12288 + s * 384 + 320 + v];
;                 f32x2 sa2 = S[0] * (f32x2){a0.x, a0.y};
;                 sa2 += S[1] * (f32x2){a0.z, a0.w}; sa2 += S[2] * (f32x2){a1.x, a1.y}; sa2 += S[3] * (f32x2){a1.z, a1.w};
;                 const float sa = red8(sa2.x + sa2.y);
;                 const f32x2 sav = {sa, sa}, vv2 = {vv, vv};
;                 S[0] = S[0] * (f32x2){w0.x, w0.y} + sav * (f32x2){b0.x, b0.y} + vv2 * (f32x2){k0.x, k0.y};
;                 S[1] = S[1] * (f32x2){w0.z, w0.w} + sav * (f32x2){b0.z, b0.w} + vv2 * (f32x2){k0.z, k0.w};
;                 S[2] = S[2] * (f32x2){w1.x, w1.y} + sav * (f32x2){b1.x, b1.y} + vv2 * (f32x2){k1.x, k1.y};
;                 S[3] = S[3] * (f32x2){w1.z, w1.w} + sav * (f32x2){b1.z, b1.w} + vv2 * (f32x2){k1.z, k1.w};
;                 f32x2 y2 = S[0] * (f32x2){r0.x, r0.y};
;                 y2 += S[1] * (f32x2){r0.z, r0.w}; y2 += S[2] * (f32x2){r1.x, r1.y}; y2 += S[3] * (f32x2){r1.z, r1.w};
;                 const float y = red8(y2.x + y2.y);
;                 if (kc == 0) ybuf[s * 64 + v] = y;
;             }
	ds_read_b128 v[70:73], v44 offset:29440
	ds_read_b128 v[74:77], v44 offset:29456
	ds_read_b128 v[78:81], v44 offset:29952
	ds_read_b128 v[82:85], v44 offset:29968
	ds_read_b128 v[86:89], v44 offset:30208
	ds_read_b128 v[90:93], v44 offset:30224
	ds_read_b64 v[146:147], v46 offset:29184
	ds_read_b128 v[62:65], v44 offset:31232
	ds_read_b128 v[66:69], v44 offset:31248
	v_add_f32_dpp v48, v48, v48 quad_perm:[1,0,3,2] row_mask:0xf bank_mask:0xf bound_ctrl:1
	v_add_f32_dpp v49, v49, v49 quad_perm:[1,0,3,2] row_mask:0xf bank_mask:0xf bound_ctrl:1
	v_add_f32_dpp v50, v50, v50 quad_perm:[1,0,3,2] row_mask:0xf bank_mask:0xf bound_ctrl:1
	v_add_f32_dpp v51, v51, v51 quad_perm:[1,0,3,2] row_mask:0xf bank_mask:0xf bound_ctrl:1
	v_pk_fma_f32 v[96:97], v[192:193], v[168:169], v[96:97] op_sel:[0,0,0] op_sel_hi:[1,0,1]
	v_pk_fma_f32 v[98:99], v[192:193], v[168:169], v[98:99] op_sel:[0,1,0] op_sel_hi:[1,1,1]
	v_pk_fma_f32 v[100:101], v[192:193], v[170:171], v[100:101] op_sel:[0,0,0] op_sel_hi:[1,0,1]
	v_add_f32_dpp v48, v48, v48 quad_perm:[2,3,0,1] row_mask:0xf bank_mask:0xf bound_ctrl:1
	v_add_f32_dpp v49, v49, v49 quad_perm:[2,3,0,1] row_mask:0xf bank_mask:0xf bound_ctrl:1
	v_add_f32_dpp v50, v50, v50 quad_perm:[2,3,0,1] row_mask:0xf bank_mask:0xf bound_ctrl:1
	v_add_f32_dpp v51, v51, v51 quad_perm:[2,3,0,1] row_mask:0xf bank_mask:0xf bound_ctrl:1
	v_pk_fma_f32 v[102:103], v[192:193], v[170:171], v[102:103] op_sel:[0,1,0] op_sel_hi:[1,1,1]
	v_pk_fma_f32 v[104:105], v[192:193], v[172:173], v[104:105] op_sel:[0,0,0] op_sel_hi:[1,0,1]
	v_pk_fma_f32 v[106:107], v[192:193], v[172:173], v[106:107] op_sel:[0,1,0] op_sel_hi:[1,1,1]
	v_add_f32_dpp v50, v50, v50 row_half_mirror row_mask:0xf bank_mask:0xf bound_ctrl:1
	v_add_f32_dpp v51, v51, v51 row_half_mirror row_mask:0xf bank_mask:0xf bound_ctrl:1
	v_pk_fma_f32 v[108:109], v[192:193], v[174:175], v[108:109] op_sel:[0,0,0] op_sel_hi:[1,0,1]
	s_mov_b64 exec, s[86:87]
	ds_write_b64 v45, v[48:49] offset:8192
	s_mov_b64 exec, s[0:1]
	v_pk_fma_f32 v[110:111], v[192:193], v[174:175], v[110:111] op_sel:[0,1,0] op_sel_hi:[1,1,1]
	s_nop 0
	v_pk_fma_f32 v[96:97], v[50:51], v[176:177], v[96:97] op_sel:[0,0,0] op_sel_hi:[1,0,1]
	v_pk_fma_f32 v[98:99], v[50:51], v[176:177], v[98:99] op_sel:[0,1,0] op_sel_hi:[1,1,1]
	v_pk_fma_f32 v[100:101], v[50:51], v[178:179], v[100:101] op_sel:[0,0,0] op_sel_hi:[1,0,1]
	v_pk_fma_f32 v[102:103], v[50:51], v[178:179], v[102:103] op_sel:[0,1,0] op_sel_hi:[1,1,1]
	v_pk_fma_f32 v[104:105], v[50:51], v[180:181], v[104:105] op_sel:[0,0,0] op_sel_hi:[1,0,1]
	v_pk_fma_f32 v[106:107], v[50:51], v[180:181], v[106:107] op_sel:[0,1,0] op_sel_hi:[1,1,1]
	v_pk_fma_f32 v[108:109], v[50:51], v[182:183], v[108:109] op_sel:[0,0,0] op_sel_hi:[1,0,1]
	v_pk_fma_f32 v[110:111], v[50:51], v[182:183], v[110:111] op_sel:[0,1,0] op_sel_hi:[1,1,1]
	v_pk_mul_f32 v[48:49], v[96:97], v[184:185] op_sel:[0,0] op_sel_hi:[1,0]
	v_pk_mul_f32 v[50:51], v[96:97], v[148:149] op_sel:[0,0] op_sel_hi:[1,0]
	v_pk_fma_f32 v[48:49], v[98:99], v[184:185], v[48:49] op_sel:[0,1,0] op_sel_hi:[1,1,1]
	v_pk_fma_f32 v[50:51], v[98:99], v[148:149], v[50:51] op_sel:[0,1,0] op_sel_hi:[1,1,1]
	v_pk_fma_f32 v[48:49], v[100:101], v[186:187], v[48:49] op_sel:[0,0,0] op_sel_hi:[1,0,1]
	v_pk_fma_f32 v[50:51], v[100:101], v[150:151], v[50:51] op_sel:[0,0,0] op_sel_hi:[1,0,1]
	v_pk_fma_f32 v[48:49], v[102:103], v[186:187], v[48:49] op_sel:[0,1,0] op_sel_hi:[1,1,1]
	v_pk_fma_f32 v[50:51], v[102:103], v[150:151], v[50:51] op_sel:[0,1,0] op_sel_hi:[1,1,1]
	v_pk_fma_f32 v[48:49], v[104:105], v[188:189], v[48:49] op_sel:[0,0,0] op_sel_hi:[1,0,1]
	v_pk_fma_f32 v[50:51], v[104:105], v[152:153], v[50:51] op_sel:[0,0,0] op_sel_hi:[1,0,1]
	v_pk_fma_f32 v[48:49], v[106:107], v[188:189], v[48:49] op_sel:[0,1,0] op_sel_hi:[1,1,1]
	v_pk_fma_f32 v[50:51], v[106:107], v[152:153], v[50:51] op_sel:[0,1,0] op_sel_hi:[1,1,1]
	v_pk_fma_f32 v[48:49], v[108:109], v[190:191], v[48:49] op_sel:[0,0,0] op_sel_hi:[1,0,1]
	v_pk_fma_f32 v[50:51], v[108:109], v[154:155], v[50:51] op_sel:[0,0,0] op_sel_hi:[1,0,1]
	v_pk_fma_f32 v[48:49], v[110:111], v[190:191], v[48:49] op_sel:[0,1,0] op_sel_hi:[1,1,1]
	v_pk_fma_f32 v[50:51], v[110:111], v[154:155], v[50:51] op_sel:[0,1,0] op_sel_hi:[1,1,1]
	s_waitcnt lgkmcnt(11)
; #define LAS __attribute__((address_space(3)))
; __device__ __forceinline__ float red8(float x) { x += dpp_mov<0xB1>(x); x += dpp_mov<0x4E>(x); x += dpp_mov<0x141>(x); return x; }
; __device__ __forceinline__ void scan_phase(const KP& P, LAS unsigned char* lds, const int tid, const int bx, const int G) {
;     ...
;             for (int s = 0; s < 32; ++s) {
;                 const LAS float* p = cb + s * 384;
;                 const f32x4 w0 = *(const LAS f32x4*)(p), w1 = *(const LAS f32x4*)(p + 4);
;                 const f32x4 k0 = *(const LAS f32x4*)(p + 64), k1 = *(const LAS f32x4*)(p + 68);
;                 const f32x4 a0 = *(const LAS f32x4*)(p + 128), a1 = *(const LAS f32x4*)(p + 132);
;                 const f32x4 b0 = *(const LAS f32x4*)(p + 192), b1 = *(const LAS f32x4*)(p + 196);
;                 const f32x4 r0 = *(const LAS f32x4*)(p + 256), r1 = *(const LAS f32x4*)(p + 260);
;                 const float vv = buf[(c & 1) * 12288 + s * 384 + 320 + v];
;                 f32x2 sa2 = S[0] * (f32x2){a0.x, a0.y};
;                 sa2 += S[1] * (f32x2){a0.z, a0.w}; sa2 += S[2] * (f32x2){a1.x, a1.y}; sa2 += S[3] * (f32x2){a1.z, a1.w};
;                 const float sa = red8(sa2.x + sa2.y);
;                 const f32x2 sav = {sa, sa}, vv2 = {vv, vv};
;                 S[0] = S[0] * (f32x2){w0.x, w0.y} + sav * (f32x2){b0.x, b0.y} + vv2 * (f32x2){k0.x, k0.y};
;                 S[1] = S[1] * (f32x2){w0.z, w0.w} + sav * (f32x2){b0.z, b0.w} + vv2 * (f32x2){k0.z, k0.w};
;                 S[2] = S[2] * (f32x2){w1.x, w1.y} + sav * (f32x2){b1.x, b1.y} + vv2 * (f32x2){k1.x, k1.y};
;                 S[3] = S[3] * (f32x2){w1.z, w1.w} + sav * (f32x2){b1.z, b1.w} + vv2 * (f32x2){k1.z, k1.w};
;                 f32x2 y2 = S[0] * (f32x2){r0.x, r0.y};
;                 y2 += S[1] * (f32x2){r0.z, r0.w}; y2 += S[2] * (f32x2){r1.x, r1.y}; y2 += S[3] * (f32x2){r1.z, r1.w};
;                 const float y = red8(y2.x + y2.y);
;                 if (kc == 0) ybuf[s * 64 + v] = y;
;             }
	ds_read_b128 v[168:171], v44 offset:30976
	ds_read_b128 v[172:175], v44 offset:30992
	ds_read_b128 v[176:179], v44 offset:31488
	ds_read_b128 v[180:183], v44 offset:31504
	ds_read_b128 v[184:187], v44 offset:31744
	ds_read_b128 v[188:191], v44 offset:31760
	ds_read_b64 v[192:193], v46 offset:30720
	ds_read_b128 v[148:151], v44 offset:32768
	ds_read_b128 v[152:155], v44 offset:32784
	v_add_f32_dpp v48, v48, v48 quad_perm:[1,0,3,2] row_mask:0xf bank_mask:0xf bound_ctrl:1
	v_add_f32_dpp v49, v49, v49 quad_perm:[1,0,3,2] row_mask:0xf bank_mask:0xf bound_ctrl:1
	v_add_f32_dpp v50, v50, v50 quad_perm:[1,0,3,2] row_mask:0xf bank_mask:0xf bound_ctrl:1
	v_add_f32_dpp v51, v51, v51 quad_perm:[1,0,3,2] row_mask:0xf bank_mask:0xf bound_ctrl:1
	v_pk_fma_f32 v[96:97], v[144:145], v[120:121], v[96:97] op_sel:[0,0,0] op_sel_hi:[1,0,1]
	v_pk_fma_f32 v[98:99], v[144:145], v[120:121], v[98:99] op_sel:[0,1,0] op_sel_hi:[1,1,1]
	v_pk_fma_f32 v[100:101], v[144:145], v[122:123], v[100:101] op_sel:[0,0,0] op_sel_hi:[1,0,1]
	v_add_f32_dpp v48, v48, v48 quad_perm:[2,3,0,1] row_mask:0xf bank_mask:0xf bound_ctrl:1
	v_add_f32_dpp v49, v49, v49 quad_perm:[2,3,0,1] row_mask:0xf bank_mask:0xf bound_ctrl:1
	v_add_f32_dpp v50, v50, v50 quad_perm:[2,3,0,1] row_mask:0xf bank_mask:0xf bound_ctrl:1
	v_add_f32_dpp v51, v51, v51 quad_perm:[2,3,0,1] row_mask:0xf bank_mask:0xf bound_ctrl:1
	v_pk_fma_f32 v[102:103], v[144:145], v[122:123], v[102:103] op_sel:[0,1,0] op_sel_hi:[1,1,1]
	v_pk_fma_f32 v[104:105], v[144:145], v[124:125], v[104:105] op_sel:[0,0,0] op_sel_hi:[1,0,1]
	v_pk_fma_f32 v[106:107], v[144:145], v[124:125], v[106:107] op_sel:[0,1,0] op_sel_hi:[1,1,1]
	v_add_f32_dpp v50, v50, v50 row_half_mirror row_mask:0xf bank_mask:0xf bound_ctrl:1
	v_add_f32_dpp v51, v51, v51 row_half_mirror row_mask:0xf bank_mask:0xf bound_ctrl:1
	v_pk_fma_f32 v[108:109], v[144:145], v[126:127], v[108:109] op_sel:[0,0,0] op_sel_hi:[1,0,1]
	s_mov_b64 exec, s[86:87]
	ds_write_b64 v45, v[48:49] offset:8704
	s_mov_b64 exec, s[0:1]
	v_pk_fma_f32 v[110:111], v[144:145], v[126:127], v[110:111] op_sel:[0,1,0] op_sel_hi:[1,1,1]
	s_nop 0
	v_pk_fma_f32 v[96:97], v[50:51], v[128:129], v[96:97] op_sel:[0,0,0] op_sel_hi:[1,0,1]
	v_pk_fma_f32 v[98:99], v[50:51], v[128:129], v[98:99] op_sel:[0,1,0] op_sel_hi:[1,1,1]
	v_pk_fma_f32 v[100:101], v[50:51], v[130:131], v[100:101] op_sel:[0,0,0] op_sel_hi:[1,0,1]
	v_pk_fma_f32 v[102:103], v[50:51], v[130:131], v[102:103] op_sel:[0,1,0] op_sel_hi:[1,1,1]
	v_pk_fma_f32 v[104:105], v[50:51], v[132:133], v[104:105] op_sel:[0,0,0] op_sel_hi:[1,0,1]
	v_pk_fma_f32 v[106:107], v[50:51], v[132:133], v[106:107] op_sel:[0,1,0] op_sel_hi:[1,1,1]
	v_pk_fma_f32 v[108:109], v[50:51], v[134:135], v[108:109] op_sel:[0,0,0] op_sel_hi:[1,0,1]
	v_pk_fma_f32 v[110:111], v[50:51], v[134:135], v[110:111] op_sel:[0,1,0] op_sel_hi:[1,1,1]
	v_pk_mul_f32 v[48:49], v[96:97], v[136:137] op_sel:[0,0] op_sel_hi:[1,0]
	v_pk_mul_f32 v[50:51], v[96:97], v[156:157] op_sel:[0,0] op_sel_hi:[1,0]
	v_pk_fma_f32 v[48:49], v[98:99], v[136:137], v[48:49] op_sel:[0,1,0] op_sel_hi:[1,1,1]
	v_pk_fma_f32 v[50:51], v[98:99], v[156:157], v[50:51] op_sel:[0,1,0] op_sel_hi:[1,1,1]
	v_pk_fma_f32 v[48:49], v[100:101], v[138:139], v[48:49] op_sel:[0,0,0] op_sel_hi:[1,0,1]
	v_pk_fma_f32 v[50:51], v[100:101], v[158:159], v[50:51] op_sel:[0,0,0] op_sel_hi:[1,0,1]
	v_pk_fma_f32 v[48:49], v[102:103], v[138:139], v[48:49] op_sel:[0,1,0] op_sel_hi:[1,1,1]
	v_pk_fma_f32 v[50:51], v[102:103], v[158:159], v[50:51] op_sel:[0,1,0] op_sel_hi:[1,1,1]
	v_pk_fma_f32 v[48:49], v[104:105], v[140:141], v[48:49] op_sel:[0,0,0] op_sel_hi:[1,0,1]
	v_pk_fma_f32 v[50:51], v[104:105], v[160:161], v[50:51] op_sel:[0,0,0] op_sel_hi:[1,0,1]
	v_pk_fma_f32 v[48:49], v[106:107], v[140:141], v[48:49] op_sel:[0,1,0] op_sel_hi:[1,1,1]
	v_pk_fma_f32 v[50:51], v[106:107], v[160:161], v[50:51] op_sel:[0,1,0] op_sel_hi:[1,1,1]
	v_pk_fma_f32 v[48:49], v[108:109], v[142:143], v[48:49] op_sel:[0,0,0] op_sel_hi:[1,0,1]
	v_pk_fma_f32 v[50:51], v[108:109], v[162:163], v[50:51] op_sel:[0,0,0] op_sel_hi:[1,0,1]
	v_pk_fma_f32 v[48:49], v[110:111], v[142:143], v[48:49] op_sel:[0,1,0] op_sel_hi:[1,1,1]
	v_pk_fma_f32 v[50:51], v[110:111], v[162:163], v[50:51] op_sel:[0,1,0] op_sel_hi:[1,1,1]
	s_waitcnt lgkmcnt(11)
; #define LAS __attribute__((address_space(3)))
; __device__ __forceinline__ float red8(float x) { x += dpp_mov<0xB1>(x); x += dpp_mov<0x4E>(x); x += dpp_mov<0x141>(x); return x; }
; __device__ __forceinline__ void scan_phase(const KP& P, LAS unsigned char* lds, const int tid, const int bx, const int G) {
;     ...
;             for (int s = 0; s < 32; ++s) {
;                 const LAS float* p = cb + s * 384;
;                 const f32x4 w0 = *(const LAS f32x4*)(p), w1 = *(const LAS f32x4*)(p + 4);
;                 const f32x4 k0 = *(const LAS f32x4*)(p + 64), k1 = *(const LAS f32x4*)(p + 68);
;                 const f32x4 a0 = *(const LAS f32x4*)(p + 128), a1 = *(const LAS f32x4*)(p + 132);
;                 const f32x4 b0 = *(const LAS f32x4*)(p + 192), b1 = *(const LAS f32x4*)(p + 196);
;                 const f32x4 r0 = *(const LAS f32x4*)(p + 256), r1 = *(const LAS f32x4*)(p + 260);
;                 const float vv = buf[(c & 1) * 12288 + s * 384 + 320 + v];
;                 f32x2 sa2 = S[0] * (f32x2){a0.x, a0.y};
;                 sa2 += S[1] * (f32x2){a0.z, a0.w}; sa2 += S[2] * (f32x2){a1.x, a1.y}; sa2 += S[3] * (f32x2){a1.z, a1.w};
;                 const float sa = red8(sa2.x + sa2.y);
;                 const f32x2 sav = {sa, sa}, vv2 = {vv, vv};
;                 S[0] = S[0] * (f32x2){w0.x, w0.y} + sav * (f32x2){b0.x, b0.y} + vv2 * (f32x2){k0.x, k0.y};
;                 S[1] = S[1] * (f32x2){w0.z, w0.w} + sav * (f32x2){b0.z, b0.w} + vv2 * (f32x2){k0.z, k0.w};
;                 S[2] = S[2] * (f32x2){w1.x, w1.y} + sav * (f32x2){b1.x, b1.y} + vv2 * (f32x2){k1.x, k1.y};
;                 S[3] = S[3] * (f32x2){w1.z, w1.w} + sav * (f32x2){b1.z, b1.w} + vv2 * (f32x2){k1.z, k1.w};
;                 f32x2 y2 = S[0] * (f32x2){r0.x, r0.y};
;                 y2 += S[1] * (f32x2){r0.z, r0.w}; y2 += S[2] * (f32x2){r1.x, r1.y}; y2 += S[3] * (f32x2){r1.z, r1.w};
;                 const float y = red8(y2.x + y2.y);
;                 if (kc == 0) ybuf[s * 64 + v] = y;
;             }
	ds_read_b128 v[120:123], v44 offset:32512
	ds_read_b128 v[124:127], v44 offset:32528
	ds_read_b128 v[128:131], v44 offset:33024
	ds_read_b128 v[132:135], v44 offset:33040
	ds_read_b128 v[136:139], v44 offset:33280
	ds_read_b128 v[140:143], v44 offset:33296
	ds_read_b64 v[144:145], v46 offset:32256
	ds_read_b128 v[156:159], v44 offset:34304
	ds_read_b128 v[160:163], v44 offset:34320
	v_add_f32_dpp v48, v48, v48 quad_perm:[1,0,3,2] row_mask:0xf bank_mask:0xf bound_ctrl:1
	v_add_f32_dpp v49, v49, v49 quad_perm:[1,0,3,2] row_mask:0xf bank_mask:0xf bound_ctrl:1
	v_add_f32_dpp v50, v50, v50 quad_perm:[1,0,3,2] row_mask:0xf bank_mask:0xf bound_ctrl:1
	v_add_f32_dpp v51, v51, v51 quad_perm:[1,0,3,2] row_mask:0xf bank_mask:0xf bound_ctrl:1
	v_pk_fma_f32 v[96:97], v[146:147], v[70:71], v[96:97] op_sel:[0,0,0] op_sel_hi:[1,0,1]
	v_pk_fma_f32 v[98:99], v[146:147], v[70:71], v[98:99] op_sel:[0,1,0] op_sel_hi:[1,1,1]
	v_pk_fma_f32 v[100:101], v[146:147], v[72:73], v[100:101] op_sel:[0,0,0] op_sel_hi:[1,0,1]
	v_add_f32_dpp v48, v48, v48 quad_perm:[2,3,0,1] row_mask:0xf bank_mask:0xf bound_ctrl:1
	v_add_f32_dpp v49, v49, v49 quad_perm:[2,3,0,1] row_mask:0xf bank_mask:0xf bound_ctrl:1
	v_add_f32_dpp v50, v50, v50 quad_perm:[2,3,0,1] row_mask:0xf bank_mask:0xf bound_ctrl:1
	v_add_f32_dpp v51, v51, v51 quad_perm:[2,3,0,1] row_mask:0xf bank_mask:0xf bound_ctrl:1
	v_pk_fma_f32 v[102:103], v[146:147], v[72:73], v[102:103] op_sel:[0,1,0] op_sel_hi:[1,1,1]
	v_pk_fma_f32 v[104:105], v[146:147], v[74:75], v[104:105] op_sel:[0,0,0] op_sel_hi:[1,0,1]
	v_pk_fma_f32 v[106:107], v[146:147], v[74:75], v[106:107] op_sel:[0,1,0] op_sel_hi:[1,1,1]
	v_add_f32_dpp v50, v50, v50 row_half_mirror row_mask:0xf bank_mask:0xf bound_ctrl:1
	v_add_f32_dpp v51, v51, v51 row_half_mirror row_mask:0xf bank_mask:0xf bound_ctrl:1
	v_pk_fma_f32 v[108:109], v[146:147], v[76:77], v[108:109] op_sel:[0,0,0] op_sel_hi:[1,0,1]
	s_mov_b64 exec, s[86:87]
	ds_write_b64 v45, v[48:49] offset:9216
	s_mov_b64 exec, s[0:1]
	v_pk_fma_f32 v[110:111], v[146:147], v[76:77], v[110:111] op_sel:[0,1,0] op_sel_hi:[1,1,1]
	s_nop 0
	v_pk_fma_f32 v[96:97], v[50:51], v[78:79], v[96:97] op_sel:[0,0,0] op_sel_hi:[1,0,1]
	v_pk_fma_f32 v[98:99], v[50:51], v[78:79], v[98:99] op_sel:[0,1,0] op_sel_hi:[1,1,1]
	v_pk_fma_f32 v[100:101], v[50:51], v[80:81], v[100:101] op_sel:[0,0,0] op_sel_hi:[1,0,1]
	v_pk_fma_f32 v[102:103], v[50:51], v[80:81], v[102:103] op_sel:[0,1,0] op_sel_hi:[1,1,1]
	v_pk_fma_f32 v[104:105], v[50:51], v[82:83], v[104:105] op_sel:[0,0,0] op_sel_hi:[1,0,1]
	v_pk_fma_f32 v[106:107], v[50:51], v[82:83], v[106:107] op_sel:[0,1,0] op_sel_hi:[1,1,1]
	v_pk_fma_f32 v[108:109], v[50:51], v[84:85], v[108:109] op_sel:[0,0,0] op_sel_hi:[1,0,1]
	v_pk_fma_f32 v[110:111], v[50:51], v[84:85], v[110:111] op_sel:[0,1,0] op_sel_hi:[1,1,1]
	v_pk_mul_f32 v[48:49], v[96:97], v[86:87] op_sel:[0,0] op_sel_hi:[1,0]
	v_pk_mul_f32 v[50:51], v[96:97], v[62:63] op_sel:[0,0] op_sel_hi:[1,0]
	v_pk_fma_f32 v[48:49], v[98:99], v[86:87], v[48:49] op_sel:[0,1,0] op_sel_hi:[1,1,1]
	v_pk_fma_f32 v[50:51], v[98:99], v[62:63], v[50:51] op_sel:[0,1,0] op_sel_hi:[1,1,1]
	v_pk_fma_f32 v[48:49], v[100:101], v[88:89], v[48:49] op_sel:[0,0,0] op_sel_hi:[1,0,1]
	v_pk_fma_f32 v[50:51], v[100:101], v[64:65], v[50:51] op_sel:[0,0,0] op_sel_hi:[1,0,1]
	v_pk_fma_f32 v[48:49], v[102:103], v[88:89], v[48:49] op_sel:[0,1,0] op_sel_hi:[1,1,1]
	v_pk_fma_f32 v[50:51], v[102:103], v[64:65], v[50:51] op_sel:[0,1,0] op_sel_hi:[1,1,1]
	v_pk_fma_f32 v[48:49], v[104:105], v[90:91], v[48:49] op_sel:[0,0,0] op_sel_hi:[1,0,1]
	v_pk_fma_f32 v[50:51], v[104:105], v[66:67], v[50:51] op_sel:[0,0,0] op_sel_hi:[1,0,1]
	v_pk_fma_f32 v[48:49], v[106:107], v[90:91], v[48:49] op_sel:[0,1,0] op_sel_hi:[1,1,1]
	v_pk_fma_f32 v[50:51], v[106:107], v[66:67], v[50:51] op_sel:[0,1,0] op_sel_hi:[1,1,1]
	v_pk_fma_f32 v[48:49], v[108:109], v[92:93], v[48:49] op_sel:[0,0,0] op_sel_hi:[1,0,1]
	v_pk_fma_f32 v[50:51], v[108:109], v[68:69], v[50:51] op_sel:[0,0,0] op_sel_hi:[1,0,1]
	v_pk_fma_f32 v[48:49], v[110:111], v[92:93], v[48:49] op_sel:[0,1,0] op_sel_hi:[1,1,1]
	v_pk_fma_f32 v[50:51], v[110:111], v[68:69], v[50:51] op_sel:[0,1,0] op_sel_hi:[1,1,1]
	s_waitcnt lgkmcnt(11)
	ds_read_b128 v[70:73], v44 offset:34048
	ds_read_b128 v[74:77], v44 offset:34064
	ds_read_b128 v[78:81], v44 offset:34560
	ds_read_b128 v[82:85], v44 offset:34576
	ds_read_b128 v[86:89], v44 offset:34816
	ds_read_b128 v[90:93], v44 offset:34832
	ds_read_b64 v[146:147], v46 offset:33792
	ds_read_b128 v[62:65], v44 offset:35840
	ds_read_b128 v[66:69], v44 offset:35856
	v_add_f32_dpp v48, v48, v48 quad_perm:[1,0,3,2] row_mask:0xf bank_mask:0xf bound_ctrl:1
	v_add_f32_dpp v49, v49, v49 quad_perm:[1,0,3,2] row_mask:0xf bank_mask:0xf bound_ctrl:1
	v_add_f32_dpp v50, v50, v50 quad_perm:[1,0,3,2] row_mask:0xf bank_mask:0xf bound_ctrl:1
	v_add_f32_dpp v51, v51, v51 quad_perm:[1,0,3,2] row_mask:0xf bank_mask:0xf bound_ctrl:1
	v_pk_fma_f32 v[96:97], v[192:193], v[168:169], v[96:97] op_sel:[0,0,0] op_sel_hi:[1,0,1]
	v_pk_fma_f32 v[98:99], v[192:193], v[168:169], v[98:99] op_sel:[0,1,0] op_sel_hi:[1,1,1]
	v_pk_fma_f32 v[100:101], v[192:193], v[170:171], v[100:101] op_sel:[0,0,0] op_sel_hi:[1,0,1]
	v_add_f32_dpp v48, v48, v48 quad_perm:[2,3,0,1] row_mask:0xf bank_mask:0xf bound_ctrl:1
	v_add_f32_dpp v49, v49, v49 quad_perm:[2,3,0,1] row_mask:0xf bank_mask:0xf bound_ctrl:1
	v_add_f32_dpp v50, v50, v50 quad_perm:[2,3,0,1] row_mask:0xf bank_mask:0xf bound_ctrl:1
	v_add_f32_dpp v51, v51, v51 quad_perm:[2,3,0,1] row_mask:0xf bank_mask:0xf bound_ctrl:1
	v_pk_fma_f32 v[102:103], v[192:193], v[170:171], v[102:103] op_sel:[0,1,0] op_sel_hi:[1,1,1]
; #define LAS __attribute__((address_space(3)))
; __device__ __forceinline__ float red8(float x) { x += dpp_mov<0xB1>(x); x += dpp_mov<0x4E>(x); x += dpp_mov<0x141>(x); return x; }
; __device__ __forceinline__ void scan_phase(const KP& P, LAS unsigned char* lds, const int tid, const int bx, const int G) {
;     ...
;             for (int s = 0; s < 32; ++s) {
;                 const LAS float* p = cb + s * 384;
;                 const f32x4 w0 = *(const LAS f32x4*)(p), w1 = *(const LAS f32x4*)(p + 4);
;                 const f32x4 k0 = *(const LAS f32x4*)(p + 64), k1 = *(const LAS f32x4*)(p + 68);
;                 const f32x4 a0 = *(const LAS f32x4*)(p + 128), a1 = *(const LAS f32x4*)(p + 132);
;                 const f32x4 b0 = *(const LAS f32x4*)(p + 192), b1 = *(const LAS f32x4*)(p + 196);
;                 const f32x4 r0 = *(const LAS f32x4*)(p + 256), r1 = *(const LAS f32x4*)(p + 260);
;                 const float vv = buf[(c & 1) * 12288 + s * 384 + 320 + v];
;                 f32x2 sa2 = S[0] * (f32x2){a0.x, a0.y};
;                 sa2 += S[1] * (f32x2){a0.z, a0.w}; sa2 += S[2] * (f32x2){a1.x, a1.y}; sa2 += S[3] * (f32x2){a1.z, a1.w};
;                 const float sa = red8(sa2.x + sa2.y);
;                 const f32x2 sav = {sa, sa}, vv2 = {vv, vv};
;                 S[0] = S[0] * (f32x2){w0.x, w0.y} + sav * (f32x2){b0.x, b0.y} + vv2 * (f32x2){k0.x, k0.y};
;                 S[1] = S[1] * (f32x2){w0.z, w0.w} + sav * (f32x2){b0.z, b0.w} + vv2 * (f32x2){k0.z, k0.w};
;                 S[2] = S[2] * (f32x2){w1.x, w1.y} + sav * (f32x2){b1.x, b1.y} + vv2 * (f32x2){k1.x, k1.y};
;                 S[3] = S[3] * (f32x2){w1.z, w1.w} + sav * (f32x2){b1.z, b1.w} + vv2 * (f32x2){k1.z, k1.w};
;                 f32x2 y2 = S[0] * (f32x2){r0.x, r0.y};
;                 y2 += S[1] * (f32x2){r0.z, r0.w}; y2 += S[2] * (f32x2){r1.x, r1.y}; y2 += S[3] * (f32x2){r1.z, r1.w};
;                 const float y = red8(y2.x + y2.y);
;                 if (kc == 0) ybuf[s * 64 + v] = y;
;             }
	v_pk_fma_f32 v[104:105], v[192:193], v[172:173], v[104:105] op_sel:[0,0,0] op_sel_hi:[1,0,1]
	v_pk_fma_f32 v[106:107], v[192:193], v[172:173], v[106:107] op_sel:[0,1,0] op_sel_hi:[1,1,1]
	v_add_f32_dpp v50, v50, v50 row_half_mirror row_mask:0xf bank_mask:0xf bound_ctrl:1
	v_add_f32_dpp v51, v51, v51 row_half_mirror row_mask:0xf bank_mask:0xf bound_ctrl:1
	v_pk_fma_f32 v[108:109], v[192:193], v[174:175], v[108:109] op_sel:[0,0,0] op_sel_hi:[1,0,1]
	s_mov_b64 exec, s[86:87]
	ds_write_b64 v45, v[48:49] offset:9728
	s_mov_b64 exec, s[0:1]
	v_pk_fma_f32 v[110:111], v[192:193], v[174:175], v[110:111] op_sel:[0,1,0] op_sel_hi:[1,1,1]
	s_nop 0
	v_pk_fma_f32 v[96:97], v[50:51], v[176:177], v[96:97] op_sel:[0,0,0] op_sel_hi:[1,0,1]
	v_pk_fma_f32 v[98:99], v[50:51], v[176:177], v[98:99] op_sel:[0,1,0] op_sel_hi:[1,1,1]
	v_pk_fma_f32 v[100:101], v[50:51], v[178:179], v[100:101] op_sel:[0,0,0] op_sel_hi:[1,0,1]
	v_pk_fma_f32 v[102:103], v[50:51], v[178:179], v[102:103] op_sel:[0,1,0] op_sel_hi:[1,1,1]
	v_pk_fma_f32 v[104:105], v[50:51], v[180:181], v[104:105] op_sel:[0,0,0] op_sel_hi:[1,0,1]
	v_pk_fma_f32 v[106:107], v[50:51], v[180:181], v[106:107] op_sel:[0,1,0] op_sel_hi:[1,1,1]
	v_pk_fma_f32 v[108:109], v[50:51], v[182:183], v[108:109] op_sel:[0,0,0] op_sel_hi:[1,0,1]
	v_pk_fma_f32 v[110:111], v[50:51], v[182:183], v[110:111] op_sel:[0,1,0] op_sel_hi:[1,1,1]
	v_pk_mul_f32 v[48:49], v[96:97], v[184:185] op_sel:[0,0] op_sel_hi:[1,0]
	v_pk_mul_f32 v[50:51], v[96:97], v[148:149] op_sel:[0,0] op_sel_hi:[1,0]
	v_pk_fma_f32 v[48:49], v[98:99], v[184:185], v[48:49] op_sel:[0,1,0] op_sel_hi:[1,1,1]
	v_pk_fma_f32 v[50:51], v[98:99], v[148:149], v[50:51] op_sel:[0,1,0] op_sel_hi:[1,1,1]
	v_pk_fma_f32 v[48:49], v[100:101], v[186:187], v[48:49] op_sel:[0,0,0] op_sel_hi:[1,0,1]
	v_pk_fma_f32 v[50:51], v[100:101], v[150:151], v[50:51] op_sel:[0,0,0] op_sel_hi:[1,0,1]
	v_pk_fma_f32 v[48:49], v[102:103], v[186:187], v[48:49] op_sel:[0,1,0] op_sel_hi:[1,1,1]
	v_pk_fma_f32 v[50:51], v[102:103], v[150:151], v[50:51] op_sel:[0,1,0] op_sel_hi:[1,1,1]
	v_pk_fma_f32 v[48:49], v[104:105], v[188:189], v[48:49] op_sel:[0,0,0] op_sel_hi:[1,0,1]
	v_pk_fma_f32 v[50:51], v[104:105], v[152:153], v[50:51] op_sel:[0,0,0] op_sel_hi:[1,0,1]
	v_pk_fma_f32 v[48:49], v[106:107], v[188:189], v[48:49] op_sel:[0,1,0] op_sel_hi:[1,1,1]
	v_pk_fma_f32 v[50:51], v[106:107], v[152:153], v[50:51] op_sel:[0,1,0] op_sel_hi:[1,1,1]
	v_pk_fma_f32 v[48:49], v[108:109], v[190:191], v[48:49] op_sel:[0,0,0] op_sel_hi:[1,0,1]
	v_pk_fma_f32 v[50:51], v[108:109], v[154:155], v[50:51] op_sel:[0,0,0] op_sel_hi:[1,0,1]
	v_pk_fma_f32 v[48:49], v[110:111], v[190:191], v[48:49] op_sel:[0,1,0] op_sel_hi:[1,1,1]
	v_pk_fma_f32 v[50:51], v[110:111], v[154:155], v[50:51] op_sel:[0,1,0] op_sel_hi:[1,1,1]
	s_waitcnt lgkmcnt(11)
	ds_read_b128 v[168:171], v44 offset:35584
	ds_read_b128 v[172:175], v44 offset:35600
	ds_read_b128 v[176:179], v44 offset:36096
	ds_read_b128 v[180:183], v44 offset:36112
	ds_read_b128 v[184:187], v44 offset:36352
	ds_read_b128 v[188:191], v44 offset:36368
	ds_read_b64 v[192:193], v46 offset:35328
	ds_read_b128 v[148:151], v44 offset:37376
	ds_read_b128 v[152:155], v44 offset:37392
	v_add_f32_dpp v48, v48, v48 quad_perm:[1,0,3,2] row_mask:0xf bank_mask:0xf bound_ctrl:1
	v_add_f32_dpp v49, v49, v49 quad_perm:[1,0,3,2] row_mask:0xf bank_mask:0xf bound_ctrl:1
	v_add_f32_dpp v50, v50, v50 quad_perm:[1,0,3,2] row_mask:0xf bank_mask:0xf bound_ctrl:1
	v_add_f32_dpp v51, v51, v51 quad_perm:[1,0,3,2] row_mask:0xf bank_mask:0xf bound_ctrl:1
	v_pk_fma_f32 v[96:97], v[144:145], v[120:121], v[96:97] op_sel:[0,0,0] op_sel_hi:[1,0,1]
	v_pk_fma_f32 v[98:99], v[144:145], v[120:121], v[98:99] op_sel:[0,1,0] op_sel_hi:[1,1,1]
	v_pk_fma_f32 v[100:101], v[144:145], v[122:123], v[100:101] op_sel:[0,0,0] op_sel_hi:[1,0,1]
	v_add_f32_dpp v48, v48, v48 quad_perm:[2,3,0,1] row_mask:0xf bank_mask:0xf bound_ctrl:1
	v_add_f32_dpp v49, v49, v49 quad_perm:[2,3,0,1] row_mask:0xf bank_mask:0xf bound_ctrl:1
	v_add_f32_dpp v50, v50, v50 quad_perm:[2,3,0,1] row_mask:0xf bank_mask:0xf bound_ctrl:1
	v_add_f32_dpp v51, v51, v51 quad_perm:[2,3,0,1] row_mask:0xf bank_mask:0xf bound_ctrl:1
	v_pk_fma_f32 v[102:103], v[144:145], v[122:123], v[102:103] op_sel:[0,1,0] op_sel_hi:[1,1,1]
	v_pk_fma_f32 v[104:105], v[144:145], v[124:125], v[104:105] op_sel:[0,0,0] op_sel_hi:[1,0,1]
	v_pk_fma_f32 v[106:107], v[144:145], v[124:125], v[106:107] op_sel:[0,1,0] op_sel_hi:[1,1,1]
	v_add_f32_dpp v50, v50, v50 row_half_mirror row_mask:0xf bank_mask:0xf bound_ctrl:1
	v_add_f32_dpp v51, v51, v51 row_half_mirror row_mask:0xf bank_mask:0xf bound_ctrl:1
	v_pk_fma_f32 v[108:109], v[144:145], v[126:127], v[108:109] op_sel:[0,0,0] op_sel_hi:[1,0,1]
	s_mov_b64 exec, s[86:87]
	ds_write_b64 v45, v[48:49] offset:10240
	s_mov_b64 exec, s[0:1]
	v_pk_fma_f32 v[110:111], v[144:145], v[126:127], v[110:111] op_sel:[0,1,0] op_sel_hi:[1,1,1]
	s_nop 0
	v_pk_fma_f32 v[96:97], v[50:51], v[128:129], v[96:97] op_sel:[0,0,0] op_sel_hi:[1,0,1]
	v_pk_fma_f32 v[98:99], v[50:51], v[128:129], v[98:99] op_sel:[0,1,0] op_sel_hi:[1,1,1]
	v_pk_fma_f32 v[100:101], v[50:51], v[130:131], v[100:101] op_sel:[0,0,0] op_sel_hi:[1,0,1]
	v_pk_fma_f32 v[102:103], v[50:51], v[130:131], v[102:103] op_sel:[0,1,0] op_sel_hi:[1,1,1]
	v_pk_fma_f32 v[104:105], v[50:51], v[132:133], v[104:105] op_sel:[0,0,0] op_sel_hi:[1,0,1]
	v_pk_fma_f32 v[106:107], v[50:51], v[132:133], v[106:107] op_sel:[0,1,0] op_sel_hi:[1,1,1]
	v_pk_fma_f32 v[108:109], v[50:51], v[134:135], v[108:109] op_sel:[0,0,0] op_sel_hi:[1,0,1]
	v_pk_fma_f32 v[110:111], v[50:51], v[134:135], v[110:111] op_sel:[0,1,0] op_sel_hi:[1,1,1]
; #define LAS __attribute__((address_space(3)))
; __device__ __forceinline__ float red8(float x) { x += dpp_mov<0xB1>(x); x += dpp_mov<0x4E>(x); x += dpp_mov<0x141>(x); return x; }
; __device__ __forceinline__ void scan_phase(const KP& P, LAS unsigned char* lds, const int tid, const int bx, const int G) {
;     ...
;             for (int s = 0; s < 32; ++s) {
;                 const LAS float* p = cb + s * 384;
;                 const f32x4 w0 = *(const LAS f32x4*)(p), w1 = *(const LAS f32x4*)(p + 4);
;                 const f32x4 k0 = *(const LAS f32x4*)(p + 64), k1 = *(const LAS f32x4*)(p + 68);
;                 const f32x4 a0 = *(const LAS f32x4*)(p + 128), a1 = *(const LAS f32x4*)(p + 132);
;                 const f32x4 b0 = *(const LAS f32x4*)(p + 192), b1 = *(const LAS f32x4*)(p + 196);
;                 const f32x4 r0 = *(const LAS f32x4*)(p + 256), r1 = *(const LAS f32x4*)(p + 260);
;                 const float vv = buf[(c & 1) * 12288 + s * 384 + 320 + v];
;                 f32x2 sa2 = S[0] * (f32x2){a0.x, a0.y};
;                 sa2 += S[1] * (f32x2){a0.z, a0.w}; sa2 += S[2] * (f32x2){a1.x, a1.y}; sa2 += S[3] * (f32x2){a1.z, a1.w};
;                 const float sa = red8(sa2.x + sa2.y);
;                 const f32x2 sav = {sa, sa}, vv2 = {vv, vv};
;                 S[0] = S[0] * (f32x2){w0.x, w0.y} + sav * (f32x2){b0.x, b0.y} + vv2 * (f32x2){k0.x, k0.y};
;                 S[1] = S[1] * (f32x2){w0.z, w0.w} + sav * (f32x2){b0.z, b0.w} + vv2 * (f32x2){k0.z, k0.w};
;                 S[2] = S[2] * (f32x2){w1.x, w1.y} + sav * (f32x2){b1.x, b1.y} + vv2 * (f32x2){k1.x, k1.y};
;                 S[3] = S[3] * (f32x2){w1.z, w1.w} + sav * (f32x2){b1.z, b1.w} + vv2 * (f32x2){k1.z, k1.w};
;                 f32x2 y2 = S[0] * (f32x2){r0.x, r0.y};
;                 y2 += S[1] * (f32x2){r0.z, r0.w}; y2 += S[2] * (f32x2){r1.x, r1.y}; y2 += S[3] * (f32x2){r1.z, r1.w};
;                 const float y = red8(y2.x + y2.y);
;                 if (kc == 0) ybuf[s * 64 + v] = y;
;             }
	v_pk_mul_f32 v[48:49], v[96:97], v[136:137] op_sel:[0,0] op_sel_hi:[1,0]
	v_pk_mul_f32 v[50:51], v[96:97], v[156:157] op_sel:[0,0] op_sel_hi:[1,0]
	v_pk_fma_f32 v[48:49], v[98:99], v[136:137], v[48:49] op_sel:[0,1,0] op_sel_hi:[1,1,1]
	v_pk_fma_f32 v[50:51], v[98:99], v[156:157], v[50:51] op_sel:[0,1,0] op_sel_hi:[1,1,1]
	v_pk_fma_f32 v[48:49], v[100:101], v[138:139], v[48:49] op_sel:[0,0,0] op_sel_hi:[1,0,1]
	v_pk_fma_f32 v[50:51], v[100:101], v[158:159], v[50:51] op_sel:[0,0,0] op_sel_hi:[1,0,1]
	v_pk_fma_f32 v[48:49], v[102:103], v[138:139], v[48:49] op_sel:[0,1,0] op_sel_hi:[1,1,1]
	v_pk_fma_f32 v[50:51], v[102:103], v[158:159], v[50:51] op_sel:[0,1,0] op_sel_hi:[1,1,1]
	v_pk_fma_f32 v[48:49], v[104:105], v[140:141], v[48:49] op_sel:[0,0,0] op_sel_hi:[1,0,1]
	v_pk_fma_f32 v[50:51], v[104:105], v[160:161], v[50:51] op_sel:[0,0,0] op_sel_hi:[1,0,1]
	v_pk_fma_f32 v[48:49], v[106:107], v[140:141], v[48:49] op_sel:[0,1,0] op_sel_hi:[1,1,1]
	v_pk_fma_f32 v[50:51], v[106:107], v[160:161], v[50:51] op_sel:[0,1,0] op_sel_hi:[1,1,1]
	v_pk_fma_f32 v[48:49], v[108:109], v[142:143], v[48:49] op_sel:[0,0,0] op_sel_hi:[1,0,1]
	v_pk_fma_f32 v[50:51], v[108:109], v[162:163], v[50:51] op_sel:[0,0,0] op_sel_hi:[1,0,1]
	v_pk_fma_f32 v[48:49], v[110:111], v[142:143], v[48:49] op_sel:[0,1,0] op_sel_hi:[1,1,1]
	v_pk_fma_f32 v[50:51], v[110:111], v[162:163], v[50:51] op_sel:[0,1,0] op_sel_hi:[1,1,1]
	s_waitcnt lgkmcnt(11)
	ds_read_b128 v[120:123], v44 offset:37120
	ds_read_b128 v[124:127], v44 offset:37136
	ds_read_b128 v[128:131], v44 offset:37632
	ds_read_b128 v[132:135], v44 offset:37648
	ds_read_b128 v[136:139], v44 offset:37888
	ds_read_b128 v[140:143], v44 offset:37904
	ds_read_b64 v[144:145], v46 offset:36864
	ds_read_b128 v[156:159], v44 offset:38912
	ds_read_b128 v[160:163], v44 offset:38928
	v_add_f32_dpp v48, v48, v48 quad_perm:[1,0,3,2] row_mask:0xf bank_mask:0xf bound_ctrl:1
	v_add_f32_dpp v49, v49, v49 quad_perm:[1,0,3,2] row_mask:0xf bank_mask:0xf bound_ctrl:1
	v_add_f32_dpp v50, v50, v50 quad_perm:[1,0,3,2] row_mask:0xf bank_mask:0xf bound_ctrl:1
	v_add_f32_dpp v51, v51, v51 quad_perm:[1,0,3,2] row_mask:0xf bank_mask:0xf bound_ctrl:1
	v_pk_fma_f32 v[96:97], v[146:147], v[70:71], v[96:97] op_sel:[0,0,0] op_sel_hi:[1,0,1]
	v_pk_fma_f32 v[98:99], v[146:147], v[70:71], v[98:99] op_sel:[0,1,0] op_sel_hi:[1,1,1]
	v_pk_fma_f32 v[100:101], v[146:147], v[72:73], v[100:101] op_sel:[0,0,0] op_sel_hi:[1,0,1]
	v_add_f32_dpp v48, v48, v48 quad_perm:[2,3,0,1] row_mask:0xf bank_mask:0xf bound_ctrl:1
	v_add_f32_dpp v49, v49, v49 quad_perm:[2,3,0,1] row_mask:0xf bank_mask:0xf bound_ctrl:1
	v_add_f32_dpp v50, v50, v50 quad_perm:[2,3,0,1] row_mask:0xf bank_mask:0xf bound_ctrl:1
	v_add_f32_dpp v51, v51, v51 quad_perm:[2,3,0,1] row_mask:0xf bank_mask:0xf bound_ctrl:1
	v_pk_fma_f32 v[102:103], v[146:147], v[72:73], v[102:103] op_sel:[0,1,0] op_sel_hi:[1,1,1]
	v_pk_fma_f32 v[104:105], v[146:147], v[74:75], v[104:105] op_sel:[0,0,0] op_sel_hi:[1,0,1]
	v_pk_fma_f32 v[106:107], v[146:147], v[74:75], v[106:107] op_sel:[0,1,0] op_sel_hi:[1,1,1]
	v_add_f32_dpp v50, v50, v50 row_half_mirror row_mask:0xf bank_mask:0xf bound_ctrl:1
	v_add_f32_dpp v51, v51, v51 row_half_mirror row_mask:0xf bank_mask:0xf bound_ctrl:1
	v_pk_fma_f32 v[108:109], v[146:147], v[76:77], v[108:109] op_sel:[0,0,0] op_sel_hi:[1,0,1]
	s_mov_b64 exec, s[86:87]
	ds_write_b64 v45, v[48:49] offset:10752
	s_mov_b64 exec, s[0:1]
	v_pk_fma_f32 v[110:111], v[146:147], v[76:77], v[110:111] op_sel:[0,1,0] op_sel_hi:[1,1,1]
	s_nop 0
	v_pk_fma_f32 v[96:97], v[50:51], v[78:79], v[96:97] op_sel:[0,0,0] op_sel_hi:[1,0,1]
	v_pk_fma_f32 v[98:99], v[50:51], v[78:79], v[98:99] op_sel:[0,1,0] op_sel_hi:[1,1,1]
	v_pk_fma_f32 v[100:101], v[50:51], v[80:81], v[100:101] op_sel:[0,0,0] op_sel_hi:[1,0,1]
	v_pk_fma_f32 v[102:103], v[50:51], v[80:81], v[102:103] op_sel:[0,1,0] op_sel_hi:[1,1,1]
	v_pk_fma_f32 v[104:105], v[50:51], v[82:83], v[104:105] op_sel:[0,0,0] op_sel_hi:[1,0,1]
	v_pk_fma_f32 v[106:107], v[50:51], v[82:83], v[106:107] op_sel:[0,1,0] op_sel_hi:[1,1,1]
	v_pk_fma_f32 v[108:109], v[50:51], v[84:85], v[108:109] op_sel:[0,0,0] op_sel_hi:[1,0,1]
	v_pk_fma_f32 v[110:111], v[50:51], v[84:85], v[110:111] op_sel:[0,1,0] op_sel_hi:[1,1,1]
	v_pk_mul_f32 v[48:49], v[96:97], v[86:87] op_sel:[0,0] op_sel_hi:[1,0]
	v_pk_mul_f32 v[50:51], v[96:97], v[62:63] op_sel:[0,0] op_sel_hi:[1,0]
	v_pk_fma_f32 v[48:49], v[98:99], v[86:87], v[48:49] op_sel:[0,1,0] op_sel_hi:[1,1,1]
	v_pk_fma_f32 v[50:51], v[98:99], v[62:63], v[50:51] op_sel:[0,1,0] op_sel_hi:[1,1,1]
	v_pk_fma_f32 v[48:49], v[100:101], v[88:89], v[48:49] op_sel:[0,0,0] op_sel_hi:[1,0,1]
	v_pk_fma_f32 v[50:51], v[100:101], v[64:65], v[50:51] op_sel:[0,0,0] op_sel_hi:[1,0,1]
	v_pk_fma_f32 v[48:49], v[102:103], v[88:89], v[48:49] op_sel:[0,1,0] op_sel_hi:[1,1,1]
	v_pk_fma_f32 v[50:51], v[102:103], v[64:65], v[50:51] op_sel:[0,1,0] op_sel_hi:[1,1,1]
	v_pk_fma_f32 v[48:49], v[104:105], v[90:91], v[48:49] op_sel:[0,0,0] op_sel_hi:[1,0,1]
	v_pk_fma_f32 v[50:51], v[104:105], v[66:67], v[50:51] op_sel:[0,0,0] op_sel_hi:[1,0,1]
	v_pk_fma_f32 v[48:49], v[106:107], v[90:91], v[48:49] op_sel:[0,1,0] op_sel_hi:[1,1,1]
	v_pk_fma_f32 v[50:51], v[106:107], v[66:67], v[50:51] op_sel:[0,1,0] op_sel_hi:[1,1,1]
	v_pk_fma_f32 v[48:49], v[108:109], v[92:93], v[48:49] op_sel:[0,0,0] op_sel_hi:[1,0,1]
	v_pk_fma_f32 v[50:51], v[108:109], v[68:69], v[50:51] op_sel:[0,0,0] op_sel_hi:[1,0,1]
	v_pk_fma_f32 v[48:49], v[110:111], v[92:93], v[48:49] op_sel:[0,1,0] op_sel_hi:[1,1,1]
	v_pk_fma_f32 v[50:51], v[110:111], v[68:69], v[50:51] op_sel:[0,1,0] op_sel_hi:[1,1,1]
	s_waitcnt lgkmcnt(11)
; #define LAS __attribute__((address_space(3)))
; __device__ __forceinline__ float red8(float x) { x += dpp_mov<0xB1>(x); x += dpp_mov<0x4E>(x); x += dpp_mov<0x141>(x); return x; }
; __device__ __forceinline__ void scan_phase(const KP& P, LAS unsigned char* lds, const int tid, const int bx, const int G) {
;     ...
;             for (int s = 0; s < 32; ++s) {
;                 const LAS float* p = cb + s * 384;
;                 const f32x4 w0 = *(const LAS f32x4*)(p), w1 = *(const LAS f32x4*)(p + 4);
;                 const f32x4 k0 = *(const LAS f32x4*)(p + 64), k1 = *(const LAS f32x4*)(p + 68);
;                 const f32x4 a0 = *(const LAS f32x4*)(p + 128), a1 = *(const LAS f32x4*)(p + 132);
;                 const f32x4 b0 = *(const LAS f32x4*)(p + 192), b1 = *(const LAS f32x4*)(p + 196);
;                 const f32x4 r0 = *(const LAS f32x4*)(p + 256), r1 = *(const LAS f32x4*)(p + 260);
;                 const float vv = buf[(c & 1) * 12288 + s * 384 + 320 + v];
;                 f32x2 sa2 = S[0] * (f32x2){a0.x, a0.y};
;                 sa2 += S[1] * (f32x2){a0.z, a0.w}; sa2 += S[2] * (f32x2){a1.x, a1.y}; sa2 += S[3] * (f32x2){a1.z, a1.w};
;                 const float sa = red8(sa2.x + sa2.y);
;                 const f32x2 sav = {sa, sa}, vv2 = {vv, vv};
;                 S[0] = S[0] * (f32x2){w0.x, w0.y} + sav * (f32x2){b0.x, b0.y} + vv2 * (f32x2){k0.x, k0.y};
;                 S[1] = S[1] * (f32x2){w0.z, w0.w} + sav * (f32x2){b0.z, b0.w} + vv2 * (f32x2){k0.z, k0.w};
;                 S[2] = S[2] * (f32x2){w1.x, w1.y} + sav * (f32x2){b1.x, b1.y} + vv2 * (f32x2){k1.x, k1.y};
;                 S[3] = S[3] * (f32x2){w1.z, w1.w} + sav * (f32x2){b1.z, b1.w} + vv2 * (f32x2){k1.z, k1.w};
;                 f32x2 y2 = S[0] * (f32x2){r0.x, r0.y};
;                 y2 += S[1] * (f32x2){r0.z, r0.w}; y2 += S[2] * (f32x2){r1.x, r1.y}; y2 += S[3] * (f32x2){r1.z, r1.w};
;                 const float y = red8(y2.x + y2.y);
;                 if (kc == 0) ybuf[s * 64 + v] = y;
;             }
	ds_read_b128 v[70:73], v44 offset:38656
	ds_read_b128 v[74:77], v44 offset:38672
	ds_read_b128 v[78:81], v44 offset:39168
	ds_read_b128 v[82:85], v44 offset:39184
	ds_read_b128 v[86:89], v44 offset:39424
	ds_read_b128 v[90:93], v44 offset:39440
	ds_read_b64 v[146:147], v46 offset:38400
	ds_read_b128 v[62:65], v44 offset:40448
	ds_read_b128 v[66:69], v44 offset:40464
	v_add_f32_dpp v48, v48, v48 quad_perm:[1,0,3,2] row_mask:0xf bank_mask:0xf bound_ctrl:1
	v_add_f32_dpp v49, v49, v49 quad_perm:[1,0,3,2] row_mask:0xf bank_mask:0xf bound_ctrl:1
	v_add_f32_dpp v50, v50, v50 quad_perm:[1,0,3,2] row_mask:0xf bank_mask:0xf bound_ctrl:1
	v_add_f32_dpp v51, v51, v51 quad_perm:[1,0,3,2] row_mask:0xf bank_mask:0xf bound_ctrl:1
	v_pk_fma_f32 v[96:97], v[192:193], v[168:169], v[96:97] op_sel:[0,0,0] op_sel_hi:[1,0,1]
	v_pk_fma_f32 v[98:99], v[192:193], v[168:169], v[98:99] op_sel:[0,1,0] op_sel_hi:[1,1,1]
	v_pk_fma_f32 v[100:101], v[192:193], v[170:171], v[100:101] op_sel:[0,0,0] op_sel_hi:[1,0,1]
	v_add_f32_dpp v48, v48, v48 quad_perm:[2,3,0,1] row_mask:0xf bank_mask:0xf bound_ctrl:1
	v_add_f32_dpp v49, v49, v49 quad_perm:[2,3,0,1] row_mask:0xf bank_mask:0xf bound_ctrl:1
	v_add_f32_dpp v50, v50, v50 quad_perm:[2,3,0,1] row_mask:0xf bank_mask:0xf bound_ctrl:1
	v_add_f32_dpp v51, v51, v51 quad_perm:[2,3,0,1] row_mask:0xf bank_mask:0xf bound_ctrl:1
	v_pk_fma_f32 v[102:103], v[192:193], v[170:171], v[102:103] op_sel:[0,1,0] op_sel_hi:[1,1,1]
	v_pk_fma_f32 v[104:105], v[192:193], v[172:173], v[104:105] op_sel:[0,0,0] op_sel_hi:[1,0,1]
	v_pk_fma_f32 v[106:107], v[192:193], v[172:173], v[106:107] op_sel:[0,1,0] op_sel_hi:[1,1,1]
	v_add_f32_dpp v50, v50, v50 row_half_mirror row_mask:0xf bank_mask:0xf bound_ctrl:1
	v_add_f32_dpp v51, v51, v51 row_half_mirror row_mask:0xf bank_mask:0xf bound_ctrl:1
	v_pk_fma_f32 v[108:109], v[192:193], v[174:175], v[108:109] op_sel:[0,0,0] op_sel_hi:[1,0,1]
	s_mov_b64 exec, s[86:87]
	ds_write_b64 v45, v[48:49] offset:11264
	s_mov_b64 exec, s[0:1]
	v_pk_fma_f32 v[110:111], v[192:193], v[174:175], v[110:111] op_sel:[0,1,0] op_sel_hi:[1,1,1]
	s_nop 0
	v_pk_fma_f32 v[96:97], v[50:51], v[176:177], v[96:97] op_sel:[0,0,0] op_sel_hi:[1,0,1]
	v_pk_fma_f32 v[98:99], v[50:51], v[176:177], v[98:99] op_sel:[0,1,0] op_sel_hi:[1,1,1]
	v_pk_fma_f32 v[100:101], v[50:51], v[178:179], v[100:101] op_sel:[0,0,0] op_sel_hi:[1,0,1]
	v_pk_fma_f32 v[102:103], v[50:51], v[178:179], v[102:103] op_sel:[0,1,0] op_sel_hi:[1,1,1]
	v_pk_fma_f32 v[104:105], v[50:51], v[180:181], v[104:105] op_sel:[0,0,0] op_sel_hi:[1,0,1]
	v_pk_fma_f32 v[106:107], v[50:51], v[180:181], v[106:107] op_sel:[0,1,0] op_sel_hi:[1,1,1]
	v_pk_fma_f32 v[108:109], v[50:51], v[182:183], v[108:109] op_sel:[0,0,0] op_sel_hi:[1,0,1]
	v_pk_fma_f32 v[110:111], v[50:51], v[182:183], v[110:111] op_sel:[0,1,0] op_sel_hi:[1,1,1]
	v_pk_mul_f32 v[48:49], v[96:97], v[184:185] op_sel:[0,0] op_sel_hi:[1,0]
	v_pk_mul_f32 v[50:51], v[96:97], v[148:149] op_sel:[0,0] op_sel_hi:[1,0]
	v_pk_fma_f32 v[48:49], v[98:99], v[184:185], v[48:49] op_sel:[0,1,0] op_sel_hi:[1,1,1]
	v_pk_fma_f32 v[50:51], v[98:99], v[148:149], v[50:51] op_sel:[0,1,0] op_sel_hi:[1,1,1]
	v_pk_fma_f32 v[48:49], v[100:101], v[186:187], v[48:49] op_sel:[0,0,0] op_sel_hi:[1,0,1]
	v_pk_fma_f32 v[50:51], v[100:101], v[150:151], v[50:51] op_sel:[0,0,0] op_sel_hi:[1,0,1]
	v_pk_fma_f32 v[48:49], v[102:103], v[186:187], v[48:49] op_sel:[0,1,0] op_sel_hi:[1,1,1]
	v_pk_fma_f32 v[50:51], v[102:103], v[150:151], v[50:51] op_sel:[0,1,0] op_sel_hi:[1,1,1]
	v_pk_fma_f32 v[48:49], v[104:105], v[188:189], v[48:49] op_sel:[0,0,0] op_sel_hi:[1,0,1]
	v_pk_fma_f32 v[50:51], v[104:105], v[152:153], v[50:51] op_sel:[0,0,0] op_sel_hi:[1,0,1]
	v_pk_fma_f32 v[48:49], v[106:107], v[188:189], v[48:49] op_sel:[0,1,0] op_sel_hi:[1,1,1]
	v_pk_fma_f32 v[50:51], v[106:107], v[152:153], v[50:51] op_sel:[0,1,0] op_sel_hi:[1,1,1]
	v_pk_fma_f32 v[48:49], v[108:109], v[190:191], v[48:49] op_sel:[0,0,0] op_sel_hi:[1,0,1]
	v_pk_fma_f32 v[50:51], v[108:109], v[154:155], v[50:51] op_sel:[0,0,0] op_sel_hi:[1,0,1]
	v_pk_fma_f32 v[48:49], v[110:111], v[190:191], v[48:49] op_sel:[0,1,0] op_sel_hi:[1,1,1]
	v_pk_fma_f32 v[50:51], v[110:111], v[154:155], v[50:51] op_sel:[0,1,0] op_sel_hi:[1,1,1]
	s_waitcnt lgkmcnt(11)
; #define LAS __attribute__((address_space(3)))
; __device__ __forceinline__ float red8(float x) { x += dpp_mov<0xB1>(x); x += dpp_mov<0x4E>(x); x += dpp_mov<0x141>(x); return x; }
; __device__ __forceinline__ void scan_phase(const KP& P, LAS unsigned char* lds, const int tid, const int bx, const int G) {
;     ...
;             for (int s = 0; s < 32; ++s) {
;                 const LAS float* p = cb + s * 384;
;                 const f32x4 w0 = *(const LAS f32x4*)(p), w1 = *(const LAS f32x4*)(p + 4);
;                 const f32x4 k0 = *(const LAS f32x4*)(p + 64), k1 = *(const LAS f32x4*)(p + 68);
;                 const f32x4 a0 = *(const LAS f32x4*)(p + 128), a1 = *(const LAS f32x4*)(p + 132);
;                 const f32x4 b0 = *(const LAS f32x4*)(p + 192), b1 = *(const LAS f32x4*)(p + 196);
;                 const f32x4 r0 = *(const LAS f32x4*)(p + 256), r1 = *(const LAS f32x4*)(p + 260);
;                 const float vv = buf[(c & 1) * 12288 + s * 384 + 320 + v];
;                 f32x2 sa2 = S[0] * (f32x2){a0.x, a0.y};
;                 sa2 += S[1] * (f32x2){a0.z, a0.w}; sa2 += S[2] * (f32x2){a1.x, a1.y}; sa2 += S[3] * (f32x2){a1.z, a1.w};
;                 const float sa = red8(sa2.x + sa2.y);
;                 const f32x2 sav = {sa, sa}, vv2 = {vv, vv};
;                 S[0] = S[0] * (f32x2){w0.x, w0.y} + sav * (f32x2){b0.x, b0.y} + vv2 * (f32x2){k0.x, k0.y};
;                 S[1] = S[1] * (f32x2){w0.z, w0.w} + sav * (f32x2){b0.z, b0.w} + vv2 * (f32x2){k0.z, k0.w};
;                 S[2] = S[2] * (f32x2){w1.x, w1.y} + sav * (f32x2){b1.x, b1.y} + vv2 * (f32x2){k1.x, k1.y};
;                 S[3] = S[3] * (f32x2){w1.z, w1.w} + sav * (f32x2){b1.z, b1.w} + vv2 * (f32x2){k1.z, k1.w};
;                 f32x2 y2 = S[0] * (f32x2){r0.x, r0.y};
;                 y2 += S[1] * (f32x2){r0.z, r0.w}; y2 += S[2] * (f32x2){r1.x, r1.y}; y2 += S[3] * (f32x2){r1.z, r1.w};
;                 const float y = red8(y2.x + y2.y);
;                 if (kc == 0) ybuf[s * 64 + v] = y;
;             }
	ds_read_b128 v[168:171], v44 offset:40192
	ds_read_b128 v[172:175], v44 offset:40208
	ds_read_b128 v[176:179], v44 offset:40704
	ds_read_b128 v[180:183], v44 offset:40720
	ds_read_b128 v[184:187], v44 offset:40960
	ds_read_b128 v[188:191], v44 offset:40976
	ds_read_b64 v[192:193], v46 offset:39936
	ds_read_b128 v[148:151], v44 offset:41984
	ds_read_b128 v[152:155], v44 offset:42000
	v_add_f32_dpp v48, v48, v48 quad_perm:[1,0,3,2] row_mask:0xf bank_mask:0xf bound_ctrl:1
	v_add_f32_dpp v49, v49, v49 quad_perm:[1,0,3,2] row_mask:0xf bank_mask:0xf bound_ctrl:1
	v_add_f32_dpp v50, v50, v50 quad_perm:[1,0,3,2] row_mask:0xf bank_mask:0xf bound_ctrl:1
	v_add_f32_dpp v51, v51, v51 quad_perm:[1,0,3,2] row_mask:0xf bank_mask:0xf bound_ctrl:1
	v_pk_fma_f32 v[96:97], v[144:145], v[120:121], v[96:97] op_sel:[0,0,0] op_sel_hi:[1,0,1]
	v_pk_fma_f32 v[98:99], v[144:145], v[120:121], v[98:99] op_sel:[0,1,0] op_sel_hi:[1,1,1]
	v_pk_fma_f32 v[100:101], v[144:145], v[122:123], v[100:101] op_sel:[0,0,0] op_sel_hi:[1,0,1]
	v_add_f32_dpp v48, v48, v48 quad_perm:[2,3,0,1] row_mask:0xf bank_mask:0xf bound_ctrl:1
	v_add_f32_dpp v49, v49, v49 quad_perm:[2,3,0,1] row_mask:0xf bank_mask:0xf bound_ctrl:1
	v_add_f32_dpp v50, v50, v50 quad_perm:[2,3,0,1] row_mask:0xf bank_mask:0xf bound_ctrl:1
	v_add_f32_dpp v51, v51, v51 quad_perm:[2,3,0,1] row_mask:0xf bank_mask:0xf bound_ctrl:1
	v_pk_fma_f32 v[102:103], v[144:145], v[122:123], v[102:103] op_sel:[0,1,0] op_sel_hi:[1,1,1]
	v_pk_fma_f32 v[104:105], v[144:145], v[124:125], v[104:105] op_sel:[0,0,0] op_sel_hi:[1,0,1]
	v_pk_fma_f32 v[106:107], v[144:145], v[124:125], v[106:107] op_sel:[0,1,0] op_sel_hi:[1,1,1]
	v_add_f32_dpp v50, v50, v50 row_half_mirror row_mask:0xf bank_mask:0xf bound_ctrl:1
	v_add_f32_dpp v51, v51, v51 row_half_mirror row_mask:0xf bank_mask:0xf bound_ctrl:1
	v_pk_fma_f32 v[108:109], v[144:145], v[126:127], v[108:109] op_sel:[0,0,0] op_sel_hi:[1,0,1]
	s_mov_b64 exec, s[86:87]
	ds_write_b64 v45, v[48:49] offset:11776
	s_mov_b64 exec, s[0:1]
	v_pk_fma_f32 v[110:111], v[144:145], v[126:127], v[110:111] op_sel:[0,1,0] op_sel_hi:[1,1,1]
	s_nop 0
	v_pk_fma_f32 v[96:97], v[50:51], v[128:129], v[96:97] op_sel:[0,0,0] op_sel_hi:[1,0,1]
	v_pk_fma_f32 v[98:99], v[50:51], v[128:129], v[98:99] op_sel:[0,1,0] op_sel_hi:[1,1,1]
	v_pk_fma_f32 v[100:101], v[50:51], v[130:131], v[100:101] op_sel:[0,0,0] op_sel_hi:[1,0,1]
	v_pk_fma_f32 v[102:103], v[50:51], v[130:131], v[102:103] op_sel:[0,1,0] op_sel_hi:[1,1,1]
	v_pk_fma_f32 v[104:105], v[50:51], v[132:133], v[104:105] op_sel:[0,0,0] op_sel_hi:[1,0,1]
	v_pk_fma_f32 v[106:107], v[50:51], v[132:133], v[106:107] op_sel:[0,1,0] op_sel_hi:[1,1,1]
	v_pk_fma_f32 v[108:109], v[50:51], v[134:135], v[108:109] op_sel:[0,0,0] op_sel_hi:[1,0,1]
	v_pk_fma_f32 v[110:111], v[50:51], v[134:135], v[110:111] op_sel:[0,1,0] op_sel_hi:[1,1,1]
	v_pk_mul_f32 v[48:49], v[96:97], v[136:137] op_sel:[0,0] op_sel_hi:[1,0]
	v_pk_mul_f32 v[50:51], v[96:97], v[156:157] op_sel:[0,0] op_sel_hi:[1,0]
	v_pk_fma_f32 v[48:49], v[98:99], v[136:137], v[48:49] op_sel:[0,1,0] op_sel_hi:[1,1,1]
	v_pk_fma_f32 v[50:51], v[98:99], v[156:157], v[50:51] op_sel:[0,1,0] op_sel_hi:[1,1,1]
	v_pk_fma_f32 v[48:49], v[100:101], v[138:139], v[48:49] op_sel:[0,0,0] op_sel_hi:[1,0,1]
	v_pk_fma_f32 v[50:51], v[100:101], v[158:159], v[50:51] op_sel:[0,0,0] op_sel_hi:[1,0,1]
	v_pk_fma_f32 v[48:49], v[102:103], v[138:139], v[48:49] op_sel:[0,1,0] op_sel_hi:[1,1,1]
	v_pk_fma_f32 v[50:51], v[102:103], v[158:159], v[50:51] op_sel:[0,1,0] op_sel_hi:[1,1,1]
	v_pk_fma_f32 v[48:49], v[104:105], v[140:141], v[48:49] op_sel:[0,0,0] op_sel_hi:[1,0,1]
	v_pk_fma_f32 v[50:51], v[104:105], v[160:161], v[50:51] op_sel:[0,0,0] op_sel_hi:[1,0,1]
	v_pk_fma_f32 v[48:49], v[106:107], v[140:141], v[48:49] op_sel:[0,1,0] op_sel_hi:[1,1,1]
	v_pk_fma_f32 v[50:51], v[106:107], v[160:161], v[50:51] op_sel:[0,1,0] op_sel_hi:[1,1,1]
	v_pk_fma_f32 v[48:49], v[108:109], v[142:143], v[48:49] op_sel:[0,0,0] op_sel_hi:[1,0,1]
	v_pk_fma_f32 v[50:51], v[108:109], v[162:163], v[50:51] op_sel:[0,0,0] op_sel_hi:[1,0,1]
	v_pk_fma_f32 v[48:49], v[110:111], v[142:143], v[48:49] op_sel:[0,1,0] op_sel_hi:[1,1,1]
	v_pk_fma_f32 v[50:51], v[110:111], v[162:163], v[50:51] op_sel:[0,1,0] op_sel_hi:[1,1,1]
	s_waitcnt lgkmcnt(11)
; #define LAS __attribute__((address_space(3)))
; __device__ __forceinline__ float red8(float x) { x += dpp_mov<0xB1>(x); x += dpp_mov<0x4E>(x); x += dpp_mov<0x141>(x); return x; }
; __device__ __forceinline__ void scan_phase(const KP& P, LAS unsigned char* lds, const int tid, const int bx, const int G) {
;     ...
;             for (int s = 0; s < 32; ++s) {
;                 const LAS float* p = cb + s * 384;
;                 const f32x4 w0 = *(const LAS f32x4*)(p), w1 = *(const LAS f32x4*)(p + 4);
;                 const f32x4 k0 = *(const LAS f32x4*)(p + 64), k1 = *(const LAS f32x4*)(p + 68);
;                 const f32x4 a0 = *(const LAS f32x4*)(p + 128), a1 = *(const LAS f32x4*)(p + 132);
;                 const f32x4 b0 = *(const LAS f32x4*)(p + 192), b1 = *(const LAS f32x4*)(p + 196);
;                 const f32x4 r0 = *(const LAS f32x4*)(p + 256), r1 = *(const LAS f32x4*)(p + 260);
;                 const float vv = buf[(c & 1) * 12288 + s * 384 + 320 + v];
;                 f32x2 sa2 = S[0] * (f32x2){a0.x, a0.y};
;                 sa2 += S[1] * (f32x2){a0.z, a0.w}; sa2 += S[2] * (f32x2){a1.x, a1.y}; sa2 += S[3] * (f32x2){a1.z, a1.w};
;                 const float sa = red8(sa2.x + sa2.y);
;                 const f32x2 sav = {sa, sa}, vv2 = {vv, vv};
;                 S[0] = S[0] * (f32x2){w0.x, w0.y} + sav * (f32x2){b0.x, b0.y} + vv2 * (f32x2){k0.x, k0.y};
;                 S[1] = S[1] * (f32x2){w0.z, w0.w} + sav * (f32x2){b0.z, b0.w} + vv2 * (f32x2){k0.z, k0.w};
;                 S[2] = S[2] * (f32x2){w1.x, w1.y} + sav * (f32x2){b1.x, b1.y} + vv2 * (f32x2){k1.x, k1.y};
;                 S[3] = S[3] * (f32x2){w1.z, w1.w} + sav * (f32x2){b1.z, b1.w} + vv2 * (f32x2){k1.z, k1.w};
;                 f32x2 y2 = S[0] * (f32x2){r0.x, r0.y};
;                 y2 += S[1] * (f32x2){r0.z, r0.w}; y2 += S[2] * (f32x2){r1.x, r1.y}; y2 += S[3] * (f32x2){r1.z, r1.w};
;                 const float y = red8(y2.x + y2.y);
;                 if (kc == 0) ybuf[s * 64 + v] = y;
;             }
	ds_read_b128 v[120:123], v44 offset:41728
	ds_read_b128 v[124:127], v44 offset:41744
	ds_read_b128 v[128:131], v44 offset:42240
	ds_read_b128 v[132:135], v44 offset:42256
	ds_read_b128 v[136:139], v44 offset:42496
	ds_read_b128 v[140:143], v44 offset:42512
	ds_read_b64 v[144:145], v46 offset:41472
	ds_read_b128 v[156:159], v44 offset:43520
	ds_read_b128 v[160:163], v44 offset:43536
	v_add_f32_dpp v48, v48, v48 quad_perm:[1,0,3,2] row_mask:0xf bank_mask:0xf bound_ctrl:1
	v_add_f32_dpp v49, v49, v49 quad_perm:[1,0,3,2] row_mask:0xf bank_mask:0xf bound_ctrl:1
	v_add_f32_dpp v50, v50, v50 quad_perm:[1,0,3,2] row_mask:0xf bank_mask:0xf bound_ctrl:1
	v_add_f32_dpp v51, v51, v51 quad_perm:[1,0,3,2] row_mask:0xf bank_mask:0xf bound_ctrl:1
	v_pk_fma_f32 v[96:97], v[146:147], v[70:71], v[96:97] op_sel:[0,0,0] op_sel_hi:[1,0,1]
	v_pk_fma_f32 v[98:99], v[146:147], v[70:71], v[98:99] op_sel:[0,1,0] op_sel_hi:[1,1,1]
	v_pk_fma_f32 v[100:101], v[146:147], v[72:73], v[100:101] op_sel:[0,0,0] op_sel_hi:[1,0,1]
	v_add_f32_dpp v48, v48, v48 quad_perm:[2,3,0,1] row_mask:0xf bank_mask:0xf bound_ctrl:1
	v_add_f32_dpp v49, v49, v49 quad_perm:[2,3,0,1] row_mask:0xf bank_mask:0xf bound_ctrl:1
	v_add_f32_dpp v50, v50, v50 quad_perm:[2,3,0,1] row_mask:0xf bank_mask:0xf bound_ctrl:1
	v_add_f32_dpp v51, v51, v51 quad_perm:[2,3,0,1] row_mask:0xf bank_mask:0xf bound_ctrl:1
	v_pk_fma_f32 v[102:103], v[146:147], v[72:73], v[102:103] op_sel:[0,1,0] op_sel_hi:[1,1,1]
	v_pk_fma_f32 v[104:105], v[146:147], v[74:75], v[104:105] op_sel:[0,0,0] op_sel_hi:[1,0,1]
	v_pk_fma_f32 v[106:107], v[146:147], v[74:75], v[106:107] op_sel:[0,1,0] op_sel_hi:[1,1,1]
	v_add_f32_dpp v50, v50, v50 row_half_mirror row_mask:0xf bank_mask:0xf bound_ctrl:1
	v_add_f32_dpp v51, v51, v51 row_half_mirror row_mask:0xf bank_mask:0xf bound_ctrl:1
	v_pk_fma_f32 v[108:109], v[146:147], v[76:77], v[108:109] op_sel:[0,0,0] op_sel_hi:[1,0,1]
	s_mov_b64 exec, s[86:87]
	ds_write_b64 v45, v[48:49] offset:12288
	s_mov_b64 exec, s[0:1]
	v_pk_fma_f32 v[110:111], v[146:147], v[76:77], v[110:111] op_sel:[0,1,0] op_sel_hi:[1,1,1]
	s_nop 0
	v_pk_fma_f32 v[96:97], v[50:51], v[78:79], v[96:97] op_sel:[0,0,0] op_sel_hi:[1,0,1]
	v_pk_fma_f32 v[98:99], v[50:51], v[78:79], v[98:99] op_sel:[0,1,0] op_sel_hi:[1,1,1]
	v_pk_fma_f32 v[100:101], v[50:51], v[80:81], v[100:101] op_sel:[0,0,0] op_sel_hi:[1,0,1]
	v_pk_fma_f32 v[102:103], v[50:51], v[80:81], v[102:103] op_sel:[0,1,0] op_sel_hi:[1,1,1]
	v_pk_fma_f32 v[104:105], v[50:51], v[82:83], v[104:105] op_sel:[0,0,0] op_sel_hi:[1,0,1]
	v_pk_fma_f32 v[106:107], v[50:51], v[82:83], v[106:107] op_sel:[0,1,0] op_sel_hi:[1,1,1]
	v_pk_fma_f32 v[108:109], v[50:51], v[84:85], v[108:109] op_sel:[0,0,0] op_sel_hi:[1,0,1]
	v_pk_fma_f32 v[110:111], v[50:51], v[84:85], v[110:111] op_sel:[0,1,0] op_sel_hi:[1,1,1]
	v_pk_mul_f32 v[48:49], v[96:97], v[86:87] op_sel:[0,0] op_sel_hi:[1,0]
	v_pk_mul_f32 v[50:51], v[96:97], v[62:63] op_sel:[0,0] op_sel_hi:[1,0]
	v_pk_fma_f32 v[48:49], v[98:99], v[86:87], v[48:49] op_sel:[0,1,0] op_sel_hi:[1,1,1]
	v_pk_fma_f32 v[50:51], v[98:99], v[62:63], v[50:51] op_sel:[0,1,0] op_sel_hi:[1,1,1]
	v_pk_fma_f32 v[48:49], v[100:101], v[88:89], v[48:49] op_sel:[0,0,0] op_sel_hi:[1,0,1]
	v_pk_fma_f32 v[50:51], v[100:101], v[64:65], v[50:51] op_sel:[0,0,0] op_sel_hi:[1,0,1]
	v_pk_fma_f32 v[48:49], v[102:103], v[88:89], v[48:49] op_sel:[0,1,0] op_sel_hi:[1,1,1]
	v_pk_fma_f32 v[50:51], v[102:103], v[64:65], v[50:51] op_sel:[0,1,0] op_sel_hi:[1,1,1]
	v_pk_fma_f32 v[48:49], v[104:105], v[90:91], v[48:49] op_sel:[0,0,0] op_sel_hi:[1,0,1]
	v_pk_fma_f32 v[50:51], v[104:105], v[66:67], v[50:51] op_sel:[0,0,0] op_sel_hi:[1,0,1]
	v_pk_fma_f32 v[48:49], v[106:107], v[90:91], v[48:49] op_sel:[0,1,0] op_sel_hi:[1,1,1]
	v_pk_fma_f32 v[50:51], v[106:107], v[66:67], v[50:51] op_sel:[0,1,0] op_sel_hi:[1,1,1]
	v_pk_fma_f32 v[48:49], v[108:109], v[92:93], v[48:49] op_sel:[0,0,0] op_sel_hi:[1,0,1]
	v_pk_fma_f32 v[50:51], v[108:109], v[68:69], v[50:51] op_sel:[0,0,0] op_sel_hi:[1,0,1]
	v_pk_fma_f32 v[48:49], v[110:111], v[92:93], v[48:49] op_sel:[0,1,0] op_sel_hi:[1,1,1]
	v_pk_fma_f32 v[50:51], v[110:111], v[68:69], v[50:51] op_sel:[0,1,0] op_sel_hi:[1,1,1]
	s_waitcnt lgkmcnt(11)
	ds_read_b128 v[70:73], v44 offset:43264
	ds_read_b128 v[74:77], v44 offset:43280
	ds_read_b128 v[78:81], v44 offset:43776
	ds_read_b128 v[82:85], v44 offset:43792
	ds_read_b128 v[86:89], v44 offset:44032
	ds_read_b128 v[90:93], v44 offset:44048
	ds_read_b64 v[146:147], v46 offset:43008
	ds_read_b128 v[62:65], v44 offset:45056
	ds_read_b128 v[66:69], v44 offset:45072
	v_add_f32_dpp v48, v48, v48 quad_perm:[1,0,3,2] row_mask:0xf bank_mask:0xf bound_ctrl:1
	v_add_f32_dpp v49, v49, v49 quad_perm:[1,0,3,2] row_mask:0xf bank_mask:0xf bound_ctrl:1
	v_add_f32_dpp v50, v50, v50 quad_perm:[1,0,3,2] row_mask:0xf bank_mask:0xf bound_ctrl:1
	v_add_f32_dpp v51, v51, v51 quad_perm:[1,0,3,2] row_mask:0xf bank_mask:0xf bound_ctrl:1
	v_pk_fma_f32 v[96:97], v[192:193], v[168:169], v[96:97] op_sel:[0,0,0] op_sel_hi:[1,0,1]
	v_pk_fma_f32 v[98:99], v[192:193], v[168:169], v[98:99] op_sel:[0,1,0] op_sel_hi:[1,1,1]
	v_pk_fma_f32 v[100:101], v[192:193], v[170:171], v[100:101] op_sel:[0,0,0] op_sel_hi:[1,0,1]
	v_add_f32_dpp v48, v48, v48 quad_perm:[2,3,0,1] row_mask:0xf bank_mask:0xf bound_ctrl:1
	v_add_f32_dpp v49, v49, v49 quad_perm:[2,3,0,1] row_mask:0xf bank_mask:0xf bound_ctrl:1
	v_add_f32_dpp v50, v50, v50 quad_perm:[2,3,0,1] row_mask:0xf bank_mask:0xf bound_ctrl:1
	v_add_f32_dpp v51, v51, v51 quad_perm:[2,3,0,1] row_mask:0xf bank_mask:0xf bound_ctrl:1
	v_pk_fma_f32 v[102:103], v[192:193], v[170:171], v[102:103] op_sel:[0,1,0] op_sel_hi:[1,1,1]
; #define LAS __attribute__((address_space(3)))
; __device__ __forceinline__ float red8(float x) { x += dpp_mov<0xB1>(x); x += dpp_mov<0x4E>(x); x += dpp_mov<0x141>(x); return x; }
; __device__ __forceinline__ void scan_phase(const KP& P, LAS unsigned char* lds, const int tid, const int bx, const int G) {
;     ...
;             for (int s = 0; s < 32; ++s) {
;                 const LAS float* p = cb + s * 384;
;                 const f32x4 w0 = *(const LAS f32x4*)(p), w1 = *(const LAS f32x4*)(p + 4);
;                 const f32x4 k0 = *(const LAS f32x4*)(p + 64), k1 = *(const LAS f32x4*)(p + 68);
;                 const f32x4 a0 = *(const LAS f32x4*)(p + 128), a1 = *(const LAS f32x4*)(p + 132);
;                 const f32x4 b0 = *(const LAS f32x4*)(p + 192), b1 = *(const LAS f32x4*)(p + 196);
;                 const f32x4 r0 = *(const LAS f32x4*)(p + 256), r1 = *(const LAS f32x4*)(p + 260);
;                 const float vv = buf[(c & 1) * 12288 + s * 384 + 320 + v];
;                 f32x2 sa2 = S[0] * (f32x2){a0.x, a0.y};
;                 sa2 += S[1] * (f32x2){a0.z, a0.w}; sa2 += S[2] * (f32x2){a1.x, a1.y}; sa2 += S[3] * (f32x2){a1.z, a1.w};
;                 const float sa = red8(sa2.x + sa2.y);
;                 const f32x2 sav = {sa, sa}, vv2 = {vv, vv};
;                 S[0] = S[0] * (f32x2){w0.x, w0.y} + sav * (f32x2){b0.x, b0.y} + vv2 * (f32x2){k0.x, k0.y};
;                 S[1] = S[1] * (f32x2){w0.z, w0.w} + sav * (f32x2){b0.z, b0.w} + vv2 * (f32x2){k0.z, k0.w};
;                 S[2] = S[2] * (f32x2){w1.x, w1.y} + sav * (f32x2){b1.x, b1.y} + vv2 * (f32x2){k1.x, k1.y};
;                 S[3] = S[3] * (f32x2){w1.z, w1.w} + sav * (f32x2){b1.z, b1.w} + vv2 * (f32x2){k1.z, k1.w};
;                 f32x2 y2 = S[0] * (f32x2){r0.x, r0.y};
;                 y2 += S[1] * (f32x2){r0.z, r0.w}; y2 += S[2] * (f32x2){r1.x, r1.y}; y2 += S[3] * (f32x2){r1.z, r1.w};
;                 const float y = red8(y2.x + y2.y);
;                 if (kc == 0) ybuf[s * 64 + v] = y;
;             }
	v_pk_fma_f32 v[104:105], v[192:193], v[172:173], v[104:105] op_sel:[0,0,0] op_sel_hi:[1,0,1]
	v_pk_fma_f32 v[106:107], v[192:193], v[172:173], v[106:107] op_sel:[0,1,0] op_sel_hi:[1,1,1]
	v_add_f32_dpp v50, v50, v50 row_half_mirror row_mask:0xf bank_mask:0xf bound_ctrl:1
	v_add_f32_dpp v51, v51, v51 row_half_mirror row_mask:0xf bank_mask:0xf bound_ctrl:1
	v_pk_fma_f32 v[108:109], v[192:193], v[174:175], v[108:109] op_sel:[0,0,0] op_sel_hi:[1,0,1]
	s_mov_b64 exec, s[86:87]
	ds_write_b64 v45, v[48:49] offset:12800
	s_mov_b64 exec, s[0:1]
	v_pk_fma_f32 v[110:111], v[192:193], v[174:175], v[110:111] op_sel:[0,1,0] op_sel_hi:[1,1,1]
	s_nop 0
	v_pk_fma_f32 v[96:97], v[50:51], v[176:177], v[96:97] op_sel:[0,0,0] op_sel_hi:[1,0,1]
	v_pk_fma_f32 v[98:99], v[50:51], v[176:177], v[98:99] op_sel:[0,1,0] op_sel_hi:[1,1,1]
	v_pk_fma_f32 v[100:101], v[50:51], v[178:179], v[100:101] op_sel:[0,0,0] op_sel_hi:[1,0,1]
	v_pk_fma_f32 v[102:103], v[50:51], v[178:179], v[102:103] op_sel:[0,1,0] op_sel_hi:[1,1,1]
	v_pk_fma_f32 v[104:105], v[50:51], v[180:181], v[104:105] op_sel:[0,0,0] op_sel_hi:[1,0,1]
	v_pk_fma_f32 v[106:107], v[50:51], v[180:181], v[106:107] op_sel:[0,1,0] op_sel_hi:[1,1,1]
	v_pk_fma_f32 v[108:109], v[50:51], v[182:183], v[108:109] op_sel:[0,0,0] op_sel_hi:[1,0,1]
	v_pk_fma_f32 v[110:111], v[50:51], v[182:183], v[110:111] op_sel:[0,1,0] op_sel_hi:[1,1,1]
	v_pk_mul_f32 v[48:49], v[96:97], v[184:185] op_sel:[0,0] op_sel_hi:[1,0]
	v_pk_mul_f32 v[50:51], v[96:97], v[148:149] op_sel:[0,0] op_sel_hi:[1,0]
	v_pk_fma_f32 v[48:49], v[98:99], v[184:185], v[48:49] op_sel:[0,1,0] op_sel_hi:[1,1,1]
	v_pk_fma_f32 v[50:51], v[98:99], v[148:149], v[50:51] op_sel:[0,1,0] op_sel_hi:[1,1,1]
	v_pk_fma_f32 v[48:49], v[100:101], v[186:187], v[48:49] op_sel:[0,0,0] op_sel_hi:[1,0,1]
	v_pk_fma_f32 v[50:51], v[100:101], v[150:151], v[50:51] op_sel:[0,0,0] op_sel_hi:[1,0,1]
	v_pk_fma_f32 v[48:49], v[102:103], v[186:187], v[48:49] op_sel:[0,1,0] op_sel_hi:[1,1,1]
	v_pk_fma_f32 v[50:51], v[102:103], v[150:151], v[50:51] op_sel:[0,1,0] op_sel_hi:[1,1,1]
	v_pk_fma_f32 v[48:49], v[104:105], v[188:189], v[48:49] op_sel:[0,0,0] op_sel_hi:[1,0,1]
	v_pk_fma_f32 v[50:51], v[104:105], v[152:153], v[50:51] op_sel:[0,0,0] op_sel_hi:[1,0,1]
	v_pk_fma_f32 v[48:49], v[106:107], v[188:189], v[48:49] op_sel:[0,1,0] op_sel_hi:[1,1,1]
	v_pk_fma_f32 v[50:51], v[106:107], v[152:153], v[50:51] op_sel:[0,1,0] op_sel_hi:[1,1,1]
	v_pk_fma_f32 v[48:49], v[108:109], v[190:191], v[48:49] op_sel:[0,0,0] op_sel_hi:[1,0,1]
	v_pk_fma_f32 v[50:51], v[108:109], v[154:155], v[50:51] op_sel:[0,0,0] op_sel_hi:[1,0,1]
	v_pk_fma_f32 v[48:49], v[110:111], v[190:191], v[48:49] op_sel:[0,1,0] op_sel_hi:[1,1,1]
	v_pk_fma_f32 v[50:51], v[110:111], v[154:155], v[50:51] op_sel:[0,1,0] op_sel_hi:[1,1,1]
	s_waitcnt lgkmcnt(11)
	ds_read_b128 v[168:171], v44 offset:44800
	ds_read_b128 v[172:175], v44 offset:44816
	ds_read_b128 v[176:179], v44 offset:45312
	ds_read_b128 v[180:183], v44 offset:45328
	ds_read_b128 v[184:187], v44 offset:45568
	ds_read_b128 v[188:191], v44 offset:45584
	ds_read_b64 v[192:193], v46 offset:44544
	ds_read_b128 v[148:151], v44 offset:46592
	ds_read_b128 v[152:155], v44 offset:46608
	v_add_f32_dpp v48, v48, v48 quad_perm:[1,0,3,2] row_mask:0xf bank_mask:0xf bound_ctrl:1
	v_add_f32_dpp v49, v49, v49 quad_perm:[1,0,3,2] row_mask:0xf bank_mask:0xf bound_ctrl:1
	v_add_f32_dpp v50, v50, v50 quad_perm:[1,0,3,2] row_mask:0xf bank_mask:0xf bound_ctrl:1
	v_add_f32_dpp v51, v51, v51 quad_perm:[1,0,3,2] row_mask:0xf bank_mask:0xf bound_ctrl:1
	v_pk_fma_f32 v[96:97], v[144:145], v[120:121], v[96:97] op_sel:[0,0,0] op_sel_hi:[1,0,1]
	v_pk_fma_f32 v[98:99], v[144:145], v[120:121], v[98:99] op_sel:[0,1,0] op_sel_hi:[1,1,1]
	v_pk_fma_f32 v[100:101], v[144:145], v[122:123], v[100:101] op_sel:[0,0,0] op_sel_hi:[1,0,1]
	v_add_f32_dpp v48, v48, v48 quad_perm:[2,3,0,1] row_mask:0xf bank_mask:0xf bound_ctrl:1
	v_add_f32_dpp v49, v49, v49 quad_perm:[2,3,0,1] row_mask:0xf bank_mask:0xf bound_ctrl:1
	v_add_f32_dpp v50, v50, v50 quad_perm:[2,3,0,1] row_mask:0xf bank_mask:0xf bound_ctrl:1
	v_add_f32_dpp v51, v51, v51 quad_perm:[2,3,0,1] row_mask:0xf bank_mask:0xf bound_ctrl:1
	v_pk_fma_f32 v[102:103], v[144:145], v[122:123], v[102:103] op_sel:[0,1,0] op_sel_hi:[1,1,1]
	v_pk_fma_f32 v[104:105], v[144:145], v[124:125], v[104:105] op_sel:[0,0,0] op_sel_hi:[1,0,1]
	v_pk_fma_f32 v[106:107], v[144:145], v[124:125], v[106:107] op_sel:[0,1,0] op_sel_hi:[1,1,1]
	v_add_f32_dpp v50, v50, v50 row_half_mirror row_mask:0xf bank_mask:0xf bound_ctrl:1
	v_add_f32_dpp v51, v51, v51 row_half_mirror row_mask:0xf bank_mask:0xf bound_ctrl:1
	v_pk_fma_f32 v[108:109], v[144:145], v[126:127], v[108:109] op_sel:[0,0,0] op_sel_hi:[1,0,1]
	s_mov_b64 exec, s[86:87]
	ds_write_b64 v45, v[48:49] offset:13312
	s_mov_b64 exec, s[0:1]
	v_pk_fma_f32 v[110:111], v[144:145], v[126:127], v[110:111] op_sel:[0,1,0] op_sel_hi:[1,1,1]
	s_nop 0
	v_pk_fma_f32 v[96:97], v[50:51], v[128:129], v[96:97] op_sel:[0,0,0] op_sel_hi:[1,0,1]
	v_pk_fma_f32 v[98:99], v[50:51], v[128:129], v[98:99] op_sel:[0,1,0] op_sel_hi:[1,1,1]
	v_pk_fma_f32 v[100:101], v[50:51], v[130:131], v[100:101] op_sel:[0,0,0] op_sel_hi:[1,0,1]
	v_pk_fma_f32 v[102:103], v[50:51], v[130:131], v[102:103] op_sel:[0,1,0] op_sel_hi:[1,1,1]
	v_pk_fma_f32 v[104:105], v[50:51], v[132:133], v[104:105] op_sel:[0,0,0] op_sel_hi:[1,0,1]
	v_pk_fma_f32 v[106:107], v[50:51], v[132:133], v[106:107] op_sel:[0,1,0] op_sel_hi:[1,1,1]
	v_pk_fma_f32 v[108:109], v[50:51], v[134:135], v[108:109] op_sel:[0,0,0] op_sel_hi:[1,0,1]
	v_pk_fma_f32 v[110:111], v[50:51], v[134:135], v[110:111] op_sel:[0,1,0] op_sel_hi:[1,1,1]
; #define LAS __attribute__((address_space(3)))
; __device__ __forceinline__ float red8(float x) { x += dpp_mov<0xB1>(x); x += dpp_mov<0x4E>(x); x += dpp_mov<0x141>(x); return x; }
; __device__ __forceinline__ void scan_phase(const KP& P, LAS unsigned char* lds, const int tid, const int bx, const int G) {
;     ...
;             for (int s = 0; s < 32; ++s) {
;                 const LAS float* p = cb + s * 384;
;                 const f32x4 w0 = *(const LAS f32x4*)(p), w1 = *(const LAS f32x4*)(p + 4);
;                 const f32x4 k0 = *(const LAS f32x4*)(p + 64), k1 = *(const LAS f32x4*)(p + 68);
;                 const f32x4 a0 = *(const LAS f32x4*)(p + 128), a1 = *(const LAS f32x4*)(p + 132);
;                 const f32x4 b0 = *(const LAS f32x4*)(p + 192), b1 = *(const LAS f32x4*)(p + 196);
;                 const f32x4 r0 = *(const LAS f32x4*)(p + 256), r1 = *(const LAS f32x4*)(p + 260);
;                 const float vv = buf[(c & 1) * 12288 + s * 384 + 320 + v];
;                 f32x2 sa2 = S[0] * (f32x2){a0.x, a0.y};
;                 sa2 += S[1] * (f32x2){a0.z, a0.w}; sa2 += S[2] * (f32x2){a1.x, a1.y}; sa2 += S[3] * (f32x2){a1.z, a1.w};
;                 const float sa = red8(sa2.x + sa2.y);
;                 const f32x2 sav = {sa, sa}, vv2 = {vv, vv};
;                 S[0] = S[0] * (f32x2){w0.x, w0.y} + sav * (f32x2){b0.x, b0.y} + vv2 * (f32x2){k0.x, k0.y};
;                 S[1] = S[1] * (f32x2){w0.z, w0.w} + sav * (f32x2){b0.z, b0.w} + vv2 * (f32x2){k0.z, k0.w};
;                 S[2] = S[2] * (f32x2){w1.x, w1.y} + sav * (f32x2){b1.x, b1.y} + vv2 * (f32x2){k1.x, k1.y};
;                 S[3] = S[3] * (f32x2){w1.z, w1.w} + sav * (f32x2){b1.z, b1.w} + vv2 * (f32x2){k1.z, k1.w};
;                 f32x2 y2 = S[0] * (f32x2){r0.x, r0.y};
;                 y2 += S[1] * (f32x2){r0.z, r0.w}; y2 += S[2] * (f32x2){r1.x, r1.y}; y2 += S[3] * (f32x2){r1.z, r1.w};
;                 const float y = red8(y2.x + y2.y);
;                 if (kc == 0) ybuf[s * 64 + v] = y;
;             }
	v_pk_mul_f32 v[48:49], v[96:97], v[136:137] op_sel:[0,0] op_sel_hi:[1,0]
	v_pk_mul_f32 v[50:51], v[96:97], v[156:157] op_sel:[0,0] op_sel_hi:[1,0]
	v_pk_fma_f32 v[48:49], v[98:99], v[136:137], v[48:49] op_sel:[0,1,0] op_sel_hi:[1,1,1]
	v_pk_fma_f32 v[50:51], v[98:99], v[156:157], v[50:51] op_sel:[0,1,0] op_sel_hi:[1,1,1]
	v_pk_fma_f32 v[48:49], v[100:101], v[138:139], v[48:49] op_sel:[0,0,0] op_sel_hi:[1,0,1]
	v_pk_fma_f32 v[50:51], v[100:101], v[158:159], v[50:51] op_sel:[0,0,0] op_sel_hi:[1,0,1]
	v_pk_fma_f32 v[48:49], v[102:103], v[138:139], v[48:49] op_sel:[0,1,0] op_sel_hi:[1,1,1]
	v_pk_fma_f32 v[50:51], v[102:103], v[158:159], v[50:51] op_sel:[0,1,0] op_sel_hi:[1,1,1]
	v_pk_fma_f32 v[48:49], v[104:105], v[140:141], v[48:49] op_sel:[0,0,0] op_sel_hi:[1,0,1]
	v_pk_fma_f32 v[50:51], v[104:105], v[160:161], v[50:51] op_sel:[0,0,0] op_sel_hi:[1,0,1]
	v_pk_fma_f32 v[48:49], v[106:107], v[140:141], v[48:49] op_sel:[0,1,0] op_sel_hi:[1,1,1]
	v_pk_fma_f32 v[50:51], v[106:107], v[160:161], v[50:51] op_sel:[0,1,0] op_sel_hi:[1,1,1]
	v_pk_fma_f32 v[48:49], v[108:109], v[142:143], v[48:49] op_sel:[0,0,0] op_sel_hi:[1,0,1]
	v_pk_fma_f32 v[50:51], v[108:109], v[162:163], v[50:51] op_sel:[0,0,0] op_sel_hi:[1,0,1]
	v_pk_fma_f32 v[48:49], v[110:111], v[142:143], v[48:49] op_sel:[0,1,0] op_sel_hi:[1,1,1]
	v_pk_fma_f32 v[50:51], v[110:111], v[162:163], v[50:51] op_sel:[0,1,0] op_sel_hi:[1,1,1]
	s_waitcnt lgkmcnt(11)
	ds_read_b128 v[120:123], v44 offset:46336
	ds_read_b128 v[124:127], v44 offset:46352
	ds_read_b128 v[128:131], v44 offset:46848
	ds_read_b128 v[132:135], v44 offset:46864
	ds_read_b128 v[136:139], v44 offset:47104
	ds_read_b128 v[140:143], v44 offset:47120
	ds_read_b64 v[144:145], v46 offset:46080
	ds_read_b128 v[156:159], v44 offset:48128
	ds_read_b128 v[160:163], v44 offset:48144
	v_add_f32_dpp v48, v48, v48 quad_perm:[1,0,3,2] row_mask:0xf bank_mask:0xf bound_ctrl:1
	v_add_f32_dpp v49, v49, v49 quad_perm:[1,0,3,2] row_mask:0xf bank_mask:0xf bound_ctrl:1
	v_add_f32_dpp v50, v50, v50 quad_perm:[1,0,3,2] row_mask:0xf bank_mask:0xf bound_ctrl:1
	v_add_f32_dpp v51, v51, v51 quad_perm:[1,0,3,2] row_mask:0xf bank_mask:0xf bound_ctrl:1
	v_pk_fma_f32 v[96:97], v[146:147], v[70:71], v[96:97] op_sel:[0,0,0] op_sel_hi:[1,0,1]
	v_pk_fma_f32 v[98:99], v[146:147], v[70:71], v[98:99] op_sel:[0,1,0] op_sel_hi:[1,1,1]
	v_pk_fma_f32 v[100:101], v[146:147], v[72:73], v[100:101] op_sel:[0,0,0] op_sel_hi:[1,0,1]
	v_add_f32_dpp v48, v48, v48 quad_perm:[2,3,0,1] row_mask:0xf bank_mask:0xf bound_ctrl:1
	v_add_f32_dpp v49, v49, v49 quad_perm:[2,3,0,1] row_mask:0xf bank_mask:0xf bound_ctrl:1
	v_add_f32_dpp v50, v50, v50 quad_perm:[2,3,0,1] row_mask:0xf bank_mask:0xf bound_ctrl:1
	v_add_f32_dpp v51, v51, v51 quad_perm:[2,3,0,1] row_mask:0xf bank_mask:0xf bound_ctrl:1
	v_pk_fma_f32 v[102:103], v[146:147], v[72:73], v[102:103] op_sel:[0,1,0] op_sel_hi:[1,1,1]
	v_pk_fma_f32 v[104:105], v[146:147], v[74:75], v[104:105] op_sel:[0,0,0] op_sel_hi:[1,0,1]
	v_pk_fma_f32 v[106:107], v[146:147], v[74:75], v[106:107] op_sel:[0,1,0] op_sel_hi:[1,1,1]
	v_add_f32_dpp v50, v50, v50 row_half_mirror row_mask:0xf bank_mask:0xf bound_ctrl:1
	v_add_f32_dpp v51, v51, v51 row_half_mirror row_mask:0xf bank_mask:0xf bound_ctrl:1
	v_pk_fma_f32 v[108:109], v[146:147], v[76:77], v[108:109] op_sel:[0,0,0] op_sel_hi:[1,0,1]
	s_mov_b64 exec, s[86:87]
	ds_write_b64 v45, v[48:49] offset:13824
	s_mov_b64 exec, s[0:1]
	v_pk_fma_f32 v[110:111], v[146:147], v[76:77], v[110:111] op_sel:[0,1,0] op_sel_hi:[1,1,1]
	s_nop 0
	v_pk_fma_f32 v[96:97], v[50:51], v[78:79], v[96:97] op_sel:[0,0,0] op_sel_hi:[1,0,1]
	v_pk_fma_f32 v[98:99], v[50:51], v[78:79], v[98:99] op_sel:[0,1,0] op_sel_hi:[1,1,1]
	v_pk_fma_f32 v[100:101], v[50:51], v[80:81], v[100:101] op_sel:[0,0,0] op_sel_hi:[1,0,1]
	v_pk_fma_f32 v[102:103], v[50:51], v[80:81], v[102:103] op_sel:[0,1,0] op_sel_hi:[1,1,1]
	v_pk_fma_f32 v[104:105], v[50:51], v[82:83], v[104:105] op_sel:[0,0,0] op_sel_hi:[1,0,1]
	v_pk_fma_f32 v[106:107], v[50:51], v[82:83], v[106:107] op_sel:[0,1,0] op_sel_hi:[1,1,1]
	v_pk_fma_f32 v[108:109], v[50:51], v[84:85], v[108:109] op_sel:[0,0,0] op_sel_hi:[1,0,1]
	v_pk_fma_f32 v[110:111], v[50:51], v[84:85], v[110:111] op_sel:[0,1,0] op_sel_hi:[1,1,1]
	v_pk_mul_f32 v[48:49], v[96:97], v[86:87] op_sel:[0,0] op_sel_hi:[1,0]
	v_pk_mul_f32 v[50:51], v[96:97], v[62:63] op_sel:[0,0] op_sel_hi:[1,0]
	v_pk_fma_f32 v[48:49], v[98:99], v[86:87], v[48:49] op_sel:[0,1,0] op_sel_hi:[1,1,1]
	v_pk_fma_f32 v[50:51], v[98:99], v[62:63], v[50:51] op_sel:[0,1,0] op_sel_hi:[1,1,1]
	v_pk_fma_f32 v[48:49], v[100:101], v[88:89], v[48:49] op_sel:[0,0,0] op_sel_hi:[1,0,1]
	v_pk_fma_f32 v[50:51], v[100:101], v[64:65], v[50:51] op_sel:[0,0,0] op_sel_hi:[1,0,1]
	v_pk_fma_f32 v[48:49], v[102:103], v[88:89], v[48:49] op_sel:[0,1,0] op_sel_hi:[1,1,1]
	v_pk_fma_f32 v[50:51], v[102:103], v[64:65], v[50:51] op_sel:[0,1,0] op_sel_hi:[1,1,1]
	v_pk_fma_f32 v[48:49], v[104:105], v[90:91], v[48:49] op_sel:[0,0,0] op_sel_hi:[1,0,1]
	v_pk_fma_f32 v[50:51], v[104:105], v[66:67], v[50:51] op_sel:[0,0,0] op_sel_hi:[1,0,1]
	v_pk_fma_f32 v[48:49], v[106:107], v[90:91], v[48:49] op_sel:[0,1,0] op_sel_hi:[1,1,1]
	v_pk_fma_f32 v[50:51], v[106:107], v[66:67], v[50:51] op_sel:[0,1,0] op_sel_hi:[1,1,1]
	v_pk_fma_f32 v[48:49], v[108:109], v[92:93], v[48:49] op_sel:[0,0,0] op_sel_hi:[1,0,1]
	v_pk_fma_f32 v[50:51], v[108:109], v[68:69], v[50:51] op_sel:[0,0,0] op_sel_hi:[1,0,1]
	v_pk_fma_f32 v[48:49], v[110:111], v[92:93], v[48:49] op_sel:[0,1,0] op_sel_hi:[1,1,1]
	v_pk_fma_f32 v[50:51], v[110:111], v[68:69], v[50:51] op_sel:[0,1,0] op_sel_hi:[1,1,1]
	s_waitcnt lgkmcnt(11)
; #define LAS __attribute__((address_space(3)))
; __device__ __forceinline__ float red8(float x) { x += dpp_mov<0xB1>(x); x += dpp_mov<0x4E>(x); x += dpp_mov<0x141>(x); return x; }
; __device__ __forceinline__ void scan_phase(const KP& P, LAS unsigned char* lds, const int tid, const int bx, const int G) {
;     ...
;             for (int s = 0; s < 32; ++s) {
;                 const LAS float* p = cb + s * 384;
;                 const f32x4 w0 = *(const LAS f32x4*)(p), w1 = *(const LAS f32x4*)(p + 4);
;                 const f32x4 k0 = *(const LAS f32x4*)(p + 64), k1 = *(const LAS f32x4*)(p + 68);
;                 const f32x4 a0 = *(const LAS f32x4*)(p + 128), a1 = *(const LAS f32x4*)(p + 132);
;                 const f32x4 b0 = *(const LAS f32x4*)(p + 192), b1 = *(const LAS f32x4*)(p + 196);
;                 const f32x4 r0 = *(const LAS f32x4*)(p + 256), r1 = *(const LAS f32x4*)(p + 260);
;                 const float vv = buf[(c & 1) * 12288 + s * 384 + 320 + v];
;                 f32x2 sa2 = S[0] * (f32x2){a0.x, a0.y};
;                 sa2 += S[1] * (f32x2){a0.z, a0.w}; sa2 += S[2] * (f32x2){a1.x, a1.y}; sa2 += S[3] * (f32x2){a1.z, a1.w};
;                 const float sa = red8(sa2.x + sa2.y);
;                 const f32x2 sav = {sa, sa}, vv2 = {vv, vv};
;                 S[0] = S[0] * (f32x2){w0.x, w0.y} + sav * (f32x2){b0.x, b0.y} + vv2 * (f32x2){k0.x, k0.y};
;                 S[1] = S[1] * (f32x2){w0.z, w0.w} + sav * (f32x2){b0.z, b0.w} + vv2 * (f32x2){k0.z, k0.w};
;                 S[2] = S[2] * (f32x2){w1.x, w1.y} + sav * (f32x2){b1.x, b1.y} + vv2 * (f32x2){k1.x, k1.y};
;                 S[3] = S[3] * (f32x2){w1.z, w1.w} + sav * (f32x2){b1.z, b1.w} + vv2 * (f32x2){k1.z, k1.w};
;                 f32x2 y2 = S[0] * (f32x2){r0.x, r0.y};
;                 y2 += S[1] * (f32x2){r0.z, r0.w}; y2 += S[2] * (f32x2){r1.x, r1.y}; y2 += S[3] * (f32x2){r1.z, r1.w};
;                 const float y = red8(y2.x + y2.y);
;                 if (kc == 0) ybuf[s * 64 + v] = y;
;             }
	ds_read_b128 v[70:73], v44 offset:47872
	ds_read_b128 v[74:77], v44 offset:47888
	ds_read_b128 v[78:81], v44 offset:48384
	ds_read_b128 v[82:85], v44 offset:48400
	ds_read_b128 v[86:89], v44 offset:48640
	ds_read_b128 v[90:93], v44 offset:48656
	ds_read_b64 v[146:147], v46 offset:47616
	v_add_f32_dpp v48, v48, v48 quad_perm:[1,0,3,2] row_mask:0xf bank_mask:0xf bound_ctrl:1
	v_add_f32_dpp v49, v49, v49 quad_perm:[1,0,3,2] row_mask:0xf bank_mask:0xf bound_ctrl:1
	v_add_f32_dpp v50, v50, v50 quad_perm:[1,0,3,2] row_mask:0xf bank_mask:0xf bound_ctrl:1
	v_add_f32_dpp v51, v51, v51 quad_perm:[1,0,3,2] row_mask:0xf bank_mask:0xf bound_ctrl:1
	v_pk_fma_f32 v[96:97], v[192:193], v[168:169], v[96:97] op_sel:[0,0,0] op_sel_hi:[1,0,1]
	v_pk_fma_f32 v[98:99], v[192:193], v[168:169], v[98:99] op_sel:[0,1,0] op_sel_hi:[1,1,1]
	v_pk_fma_f32 v[100:101], v[192:193], v[170:171], v[100:101] op_sel:[0,0,0] op_sel_hi:[1,0,1]
	v_add_f32_dpp v48, v48, v48 quad_perm:[2,3,0,1] row_mask:0xf bank_mask:0xf bound_ctrl:1
	v_add_f32_dpp v49, v49, v49 quad_perm:[2,3,0,1] row_mask:0xf bank_mask:0xf bound_ctrl:1
	v_add_f32_dpp v50, v50, v50 quad_perm:[2,3,0,1] row_mask:0xf bank_mask:0xf bound_ctrl:1
	v_add_f32_dpp v51, v51, v51 quad_perm:[2,3,0,1] row_mask:0xf bank_mask:0xf bound_ctrl:1
	v_pk_fma_f32 v[102:103], v[192:193], v[170:171], v[102:103] op_sel:[0,1,0] op_sel_hi:[1,1,1]
	v_pk_fma_f32 v[104:105], v[192:193], v[172:173], v[104:105] op_sel:[0,0,0] op_sel_hi:[1,0,1]
	v_pk_fma_f32 v[106:107], v[192:193], v[172:173], v[106:107] op_sel:[0,1,0] op_sel_hi:[1,1,1]
	v_add_f32_dpp v50, v50, v50 row_half_mirror row_mask:0xf bank_mask:0xf bound_ctrl:1
	v_add_f32_dpp v51, v51, v51 row_half_mirror row_mask:0xf bank_mask:0xf bound_ctrl:1
	v_pk_fma_f32 v[108:109], v[192:193], v[174:175], v[108:109] op_sel:[0,0,0] op_sel_hi:[1,0,1]
	s_mov_b64 exec, s[86:87]
	ds_write_b64 v45, v[48:49] offset:14336
	s_mov_b64 exec, s[0:1]
	v_pk_fma_f32 v[110:111], v[192:193], v[174:175], v[110:111] op_sel:[0,1,0] op_sel_hi:[1,1,1]
	s_nop 0
	v_pk_fma_f32 v[96:97], v[50:51], v[176:177], v[96:97] op_sel:[0,0,0] op_sel_hi:[1,0,1]
	v_pk_fma_f32 v[98:99], v[50:51], v[176:177], v[98:99] op_sel:[0,1,0] op_sel_hi:[1,1,1]
	v_pk_fma_f32 v[100:101], v[50:51], v[178:179], v[100:101] op_sel:[0,0,0] op_sel_hi:[1,0,1]
	v_pk_fma_f32 v[102:103], v[50:51], v[178:179], v[102:103] op_sel:[0,1,0] op_sel_hi:[1,1,1]
	v_pk_fma_f32 v[104:105], v[50:51], v[180:181], v[104:105] op_sel:[0,0,0] op_sel_hi:[1,0,1]
	v_pk_fma_f32 v[106:107], v[50:51], v[180:181], v[106:107] op_sel:[0,1,0] op_sel_hi:[1,1,1]
	v_pk_fma_f32 v[108:109], v[50:51], v[182:183], v[108:109] op_sel:[0,0,0] op_sel_hi:[1,0,1]
	v_pk_fma_f32 v[110:111], v[50:51], v[182:183], v[110:111] op_sel:[0,1,0] op_sel_hi:[1,1,1]
	v_pk_mul_f32 v[48:49], v[96:97], v[184:185] op_sel:[0,0] op_sel_hi:[1,0]
	v_pk_mul_f32 v[50:51], v[96:97], v[148:149] op_sel:[0,0] op_sel_hi:[1,0]
	v_pk_fma_f32 v[48:49], v[98:99], v[184:185], v[48:49] op_sel:[0,1,0] op_sel_hi:[1,1,1]
	v_pk_fma_f32 v[50:51], v[98:99], v[148:149], v[50:51] op_sel:[0,1,0] op_sel_hi:[1,1,1]
	v_pk_fma_f32 v[48:49], v[100:101], v[186:187], v[48:49] op_sel:[0,0,0] op_sel_hi:[1,0,1]
	v_pk_fma_f32 v[50:51], v[100:101], v[150:151], v[50:51] op_sel:[0,0,0] op_sel_hi:[1,0,1]
	v_pk_fma_f32 v[48:49], v[102:103], v[186:187], v[48:49] op_sel:[0,1,0] op_sel_hi:[1,1,1]
	v_pk_fma_f32 v[50:51], v[102:103], v[150:151], v[50:51] op_sel:[0,1,0] op_sel_hi:[1,1,1]
	v_pk_fma_f32 v[48:49], v[104:105], v[188:189], v[48:49] op_sel:[0,0,0] op_sel_hi:[1,0,1]
	v_pk_fma_f32 v[50:51], v[104:105], v[152:153], v[50:51] op_sel:[0,0,0] op_sel_hi:[1,0,1]
	v_pk_fma_f32 v[48:49], v[106:107], v[188:189], v[48:49] op_sel:[0,1,0] op_sel_hi:[1,1,1]
	v_pk_fma_f32 v[50:51], v[106:107], v[152:153], v[50:51] op_sel:[0,1,0] op_sel_hi:[1,1,1]
	v_pk_fma_f32 v[48:49], v[108:109], v[190:191], v[48:49] op_sel:[0,0,0] op_sel_hi:[1,0,1]
	v_pk_fma_f32 v[50:51], v[108:109], v[154:155], v[50:51] op_sel:[0,0,0] op_sel_hi:[1,0,1]
	v_pk_fma_f32 v[48:49], v[110:111], v[190:191], v[48:49] op_sel:[0,1,0] op_sel_hi:[1,1,1]
	v_pk_fma_f32 v[50:51], v[110:111], v[154:155], v[50:51] op_sel:[0,1,0] op_sel_hi:[1,1,1]
	s_waitcnt lgkmcnt(9)
	s_nop 1
	v_add_f32_dpp v48, v48, v48 quad_perm:[1,0,3,2] row_mask:0xf bank_mask:0xf bound_ctrl:1
	v_add_f32_dpp v49, v49, v49 quad_perm:[1,0,3,2] row_mask:0xf bank_mask:0xf bound_ctrl:1
	v_add_f32_dpp v50, v50, v50 quad_perm:[1,0,3,2] row_mask:0xf bank_mask:0xf bound_ctrl:1
	v_add_f32_dpp v51, v51, v51 quad_perm:[1,0,3,2] row_mask:0xf bank_mask:0xf bound_ctrl:1
	v_pk_fma_f32 v[96:97], v[144:145], v[120:121], v[96:97] op_sel:[0,0,0] op_sel_hi:[1,0,1]
	v_pk_fma_f32 v[98:99], v[144:145], v[120:121], v[98:99] op_sel:[0,1,0] op_sel_hi:[1,1,1]
	v_pk_fma_f32 v[100:101], v[144:145], v[122:123], v[100:101] op_sel:[0,0,0] op_sel_hi:[1,0,1]
	v_add_f32_dpp v48, v48, v48 quad_perm:[2,3,0,1] row_mask:0xf bank_mask:0xf bound_ctrl:1
	v_add_f32_dpp v49, v49, v49 quad_perm:[2,3,0,1] row_mask:0xf bank_mask:0xf bound_ctrl:1
	v_add_f32_dpp v50, v50, v50 quad_perm:[2,3,0,1] row_mask:0xf bank_mask:0xf bound_ctrl:1
	v_add_f32_dpp v51, v51, v51 quad_perm:[2,3,0,1] row_mask:0xf bank_mask:0xf bound_ctrl:1
	v_pk_fma_f32 v[102:103], v[144:145], v[122:123], v[102:103] op_sel:[0,1,0] op_sel_hi:[1,1,1]
	v_pk_fma_f32 v[104:105], v[144:145], v[124:125], v[104:105] op_sel:[0,0,0] op_sel_hi:[1,0,1]
	v_pk_fma_f32 v[106:107], v[144:145], v[124:125], v[106:107] op_sel:[0,1,0] op_sel_hi:[1,1,1]
	v_add_f32_dpp v50, v50, v50 row_half_mirror row_mask:0xf bank_mask:0xf bound_ctrl:1
	v_add_f32_dpp v51, v51, v51 row_half_mirror row_mask:0xf bank_mask:0xf bound_ctrl:1
; #define LAS __attribute__((address_space(3)))
; __device__ __forceinline__ float red8(float x) { x += dpp_mov<0xB1>(x); x += dpp_mov<0x4E>(x); x += dpp_mov<0x141>(x); return x; }
; __device__ __forceinline__ void scan_phase(const KP& P, LAS unsigned char* lds, const int tid, const int bx, const int G) {
;     ...
;             for (int s = 0; s < 32; ++s) {
;                 const LAS float* p = cb + s * 384;
;                 const f32x4 w0 = *(const LAS f32x4*)(p), w1 = *(const LAS f32x4*)(p + 4);
;                 const f32x4 k0 = *(const LAS f32x4*)(p + 64), k1 = *(const LAS f32x4*)(p + 68);
;                 const f32x4 a0 = *(const LAS f32x4*)(p + 128), a1 = *(const LAS f32x4*)(p + 132);
;                 const f32x4 b0 = *(const LAS f32x4*)(p + 192), b1 = *(const LAS f32x4*)(p + 196);
;                 const f32x4 r0 = *(const LAS f32x4*)(p + 256), r1 = *(const LAS f32x4*)(p + 260);
;                 const float vv = buf[(c & 1) * 12288 + s * 384 + 320 + v];
;                 f32x2 sa2 = S[0] * (f32x2){a0.x, a0.y};
;                 sa2 += S[1] * (f32x2){a0.z, a0.w}; sa2 += S[2] * (f32x2){a1.x, a1.y}; sa2 += S[3] * (f32x2){a1.z, a1.w};
;                 const float sa = red8(sa2.x + sa2.y);
;                 const f32x2 sav = {sa, sa}, vv2 = {vv, vv};
;                 S[0] = S[0] * (f32x2){w0.x, w0.y} + sav * (f32x2){b0.x, b0.y} + vv2 * (f32x2){k0.x, k0.y};
;                 S[1] = S[1] * (f32x2){w0.z, w0.w} + sav * (f32x2){b0.z, b0.w} + vv2 * (f32x2){k0.z, k0.w};
;                 S[2] = S[2] * (f32x2){w1.x, w1.y} + sav * (f32x2){b1.x, b1.y} + vv2 * (f32x2){k1.x, k1.y};
;                 S[3] = S[3] * (f32x2){w1.z, w1.w} + sav * (f32x2){b1.z, b1.w} + vv2 * (f32x2){k1.z, k1.w};
;                 f32x2 y2 = S[0] * (f32x2){r0.x, r0.y};
;                 y2 += S[1] * (f32x2){r0.z, r0.w}; y2 += S[2] * (f32x2){r1.x, r1.y}; y2 += S[3] * (f32x2){r1.z, r1.w};
;                 const float y = red8(y2.x + y2.y);
;                 if (kc == 0) ybuf[s * 64 + v] = y;
;             }
	v_pk_fma_f32 v[108:109], v[144:145], v[126:127], v[108:109] op_sel:[0,0,0] op_sel_hi:[1,0,1]
	s_mov_b64 exec, s[86:87]
	ds_write_b64 v45, v[48:49] offset:14848
	s_mov_b64 exec, s[0:1]
	v_pk_fma_f32 v[110:111], v[144:145], v[126:127], v[110:111] op_sel:[0,1,0] op_sel_hi:[1,1,1]
	s_nop 0
	v_pk_fma_f32 v[96:97], v[50:51], v[128:129], v[96:97] op_sel:[0,0,0] op_sel_hi:[1,0,1]
	v_pk_fma_f32 v[98:99], v[50:51], v[128:129], v[98:99] op_sel:[0,1,0] op_sel_hi:[1,1,1]
	v_pk_fma_f32 v[100:101], v[50:51], v[130:131], v[100:101] op_sel:[0,0,0] op_sel_hi:[1,0,1]
	v_pk_fma_f32 v[102:103], v[50:51], v[130:131], v[102:103] op_sel:[0,1,0] op_sel_hi:[1,1,1]
	v_pk_fma_f32 v[104:105], v[50:51], v[132:133], v[104:105] op_sel:[0,0,0] op_sel_hi:[1,0,1]
	v_pk_fma_f32 v[106:107], v[50:51], v[132:133], v[106:107] op_sel:[0,1,0] op_sel_hi:[1,1,1]
	v_pk_fma_f32 v[108:109], v[50:51], v[134:135], v[108:109] op_sel:[0,0,0] op_sel_hi:[1,0,1]
	v_pk_fma_f32 v[110:111], v[50:51], v[134:135], v[110:111] op_sel:[0,1,0] op_sel_hi:[1,1,1]
	v_pk_mul_f32 v[48:49], v[96:97], v[136:137] op_sel:[0,0] op_sel_hi:[1,0]
	v_pk_mul_f32 v[50:51], v[96:97], v[156:157] op_sel:[0,0] op_sel_hi:[1,0]
	v_pk_fma_f32 v[48:49], v[98:99], v[136:137], v[48:49] op_sel:[0,1,0] op_sel_hi:[1,1,1]
	v_pk_fma_f32 v[50:51], v[98:99], v[156:157], v[50:51] op_sel:[0,1,0] op_sel_hi:[1,1,1]
	v_pk_fma_f32 v[48:49], v[100:101], v[138:139], v[48:49] op_sel:[0,0,0] op_sel_hi:[1,0,1]
	v_pk_fma_f32 v[50:51], v[100:101], v[158:159], v[50:51] op_sel:[0,0,0] op_sel_hi:[1,0,1]
	v_pk_fma_f32 v[48:49], v[102:103], v[138:139], v[48:49] op_sel:[0,1,0] op_sel_hi:[1,1,1]
	v_pk_fma_f32 v[50:51], v[102:103], v[158:159], v[50:51] op_sel:[0,1,0] op_sel_hi:[1,1,1]
	v_pk_fma_f32 v[48:49], v[104:105], v[140:141], v[48:49] op_sel:[0,0,0] op_sel_hi:[1,0,1]
	v_pk_fma_f32 v[50:51], v[104:105], v[160:161], v[50:51] op_sel:[0,0,0] op_sel_hi:[1,0,1]
	v_pk_fma_f32 v[48:49], v[106:107], v[140:141], v[48:49] op_sel:[0,1,0] op_sel_hi:[1,1,1]
	v_pk_fma_f32 v[50:51], v[106:107], v[160:161], v[50:51] op_sel:[0,1,0] op_sel_hi:[1,1,1]
	v_pk_fma_f32 v[48:49], v[108:109], v[142:143], v[48:49] op_sel:[0,0,0] op_sel_hi:[1,0,1]
	v_pk_fma_f32 v[50:51], v[108:109], v[162:163], v[50:51] op_sel:[0,0,0] op_sel_hi:[1,0,1]
	v_pk_fma_f32 v[48:49], v[110:111], v[142:143], v[48:49] op_sel:[0,1,0] op_sel_hi:[1,1,1]
	v_pk_fma_f32 v[50:51], v[110:111], v[162:163], v[50:51] op_sel:[0,1,0] op_sel_hi:[1,1,1]
	s_waitcnt lgkmcnt(2)
	s_nop 1
	v_add_f32_dpp v48, v48, v48 quad_perm:[1,0,3,2] row_mask:0xf bank_mask:0xf bound_ctrl:1
	v_add_f32_dpp v49, v49, v49 quad_perm:[1,0,3,2] row_mask:0xf bank_mask:0xf bound_ctrl:1
	v_add_f32_dpp v50, v50, v50 quad_perm:[1,0,3,2] row_mask:0xf bank_mask:0xf bound_ctrl:1
	v_add_f32_dpp v51, v51, v51 quad_perm:[1,0,3,2] row_mask:0xf bank_mask:0xf bound_ctrl:1
	v_pk_fma_f32 v[96:97], v[146:147], v[70:71], v[96:97] op_sel:[0,0,0] op_sel_hi:[1,0,1]
	v_pk_fma_f32 v[98:99], v[146:147], v[70:71], v[98:99] op_sel:[0,1,0] op_sel_hi:[1,1,1]
	v_pk_fma_f32 v[100:101], v[146:147], v[72:73], v[100:101] op_sel:[0,0,0] op_sel_hi:[1,0,1]
	v_add_f32_dpp v48, v48, v48 quad_perm:[2,3,0,1] row_mask:0xf bank_mask:0xf bound_ctrl:1
	v_add_f32_dpp v49, v49, v49 quad_perm:[2,3,0,1] row_mask:0xf bank_mask:0xf bound_ctrl:1
	v_add_f32_dpp v50, v50, v50 quad_perm:[2,3,0,1] row_mask:0xf bank_mask:0xf bound_ctrl:1
	v_add_f32_dpp v51, v51, v51 quad_perm:[2,3,0,1] row_mask:0xf bank_mask:0xf bound_ctrl:1
	v_pk_fma_f32 v[102:103], v[146:147], v[72:73], v[102:103] op_sel:[0,1,0] op_sel_hi:[1,1,1]
	v_pk_fma_f32 v[104:105], v[146:147], v[74:75], v[104:105] op_sel:[0,0,0] op_sel_hi:[1,0,1]
	v_pk_fma_f32 v[106:107], v[146:147], v[74:75], v[106:107] op_sel:[0,1,0] op_sel_hi:[1,1,1]
	v_add_f32_dpp v50, v50, v50 row_half_mirror row_mask:0xf bank_mask:0xf bound_ctrl:1
	v_add_f32_dpp v51, v51, v51 row_half_mirror row_mask:0xf bank_mask:0xf bound_ctrl:1
	v_pk_fma_f32 v[108:109], v[146:147], v[76:77], v[108:109] op_sel:[0,0,0] op_sel_hi:[1,0,1]
	s_mov_b64 exec, s[86:87]
	ds_write_b64 v45, v[48:49] offset:15360
	s_mov_b64 exec, s[0:1]
	v_pk_fma_f32 v[110:111], v[146:147], v[76:77], v[110:111] op_sel:[0,1,0] op_sel_hi:[1,1,1]
	s_nop 0
	v_pk_fma_f32 v[96:97], v[50:51], v[78:79], v[96:97] op_sel:[0,0,0] op_sel_hi:[1,0,1]
	v_pk_fma_f32 v[98:99], v[50:51], v[78:79], v[98:99] op_sel:[0,1,0] op_sel_hi:[1,1,1]
	v_pk_fma_f32 v[100:101], v[50:51], v[80:81], v[100:101] op_sel:[0,0,0] op_sel_hi:[1,0,1]
	v_pk_fma_f32 v[102:103], v[50:51], v[80:81], v[102:103] op_sel:[0,1,0] op_sel_hi:[1,1,1]
	v_pk_fma_f32 v[104:105], v[50:51], v[82:83], v[104:105] op_sel:[0,0,0] op_sel_hi:[1,0,1]
	v_pk_fma_f32 v[106:107], v[50:51], v[82:83], v[106:107] op_sel:[0,1,0] op_sel_hi:[1,1,1]
	v_pk_fma_f32 v[108:109], v[50:51], v[84:85], v[108:109] op_sel:[0,0,0] op_sel_hi:[1,0,1]
	v_pk_fma_f32 v[110:111], v[50:51], v[84:85], v[110:111] op_sel:[0,1,0] op_sel_hi:[1,1,1]
	v_pk_mul_f32 v[48:49], v[96:97], v[86:87] op_sel:[0,0] op_sel_hi:[1,0]
	s_nop 0
	v_pk_fma_f32 v[48:49], v[98:99], v[86:87], v[48:49] op_sel:[0,1,0] op_sel_hi:[1,1,1]
	s_nop 0
	v_pk_fma_f32 v[48:49], v[100:101], v[88:89], v[48:49] op_sel:[0,0,0] op_sel_hi:[1,0,1]
	s_nop 0
	v_pk_fma_f32 v[48:49], v[102:103], v[88:89], v[48:49] op_sel:[0,1,0] op_sel_hi:[1,1,1]
	s_nop 0
	v_pk_fma_f32 v[48:49], v[104:105], v[90:91], v[48:49] op_sel:[0,0,0] op_sel_hi:[1,0,1]
	s_nop 0
	v_pk_fma_f32 v[48:49], v[106:107], v[90:91], v[48:49] op_sel:[0,1,0] op_sel_hi:[1,1,1]
	s_nop 0
	v_pk_fma_f32 v[48:49], v[108:109], v[92:93], v[48:49] op_sel:[0,0,0] op_sel_hi:[1,0,1]
	s_nop 0
	v_pk_fma_f32 v[48:49], v[110:111], v[92:93], v[48:49] op_sel:[0,1,0] op_sel_hi:[1,1,1]
	s_nop 0
	v_pk_mul_f32 v[96:97], v[96:97], v[112:113] op_sel:[0,0] op_sel_hi:[1,0]
	v_pk_mul_f32 v[98:99], v[98:99], v[112:113] op_sel:[0,1] op_sel_hi:[1,1]
	v_pk_mul_f32 v[100:101], v[100:101], v[114:115] op_sel:[0,0] op_sel_hi:[1,0]
	v_pk_mul_f32 v[102:103], v[102:103], v[114:115] op_sel:[0,1] op_sel_hi:[1,1]
	v_pk_mul_f32 v[104:105], v[104:105], v[116:117] op_sel:[0,0] op_sel_hi:[1,0]
	v_pk_mul_f32 v[106:107], v[106:107], v[116:117] op_sel:[0,1] op_sel_hi:[1,1]
	v_pk_mul_f32 v[108:109], v[108:109], v[118:119] op_sel:[0,0] op_sel_hi:[1,0]
	v_pk_mul_f32 v[110:111], v[110:111], v[118:119] op_sel:[0,1] op_sel_hi:[1,1]
	v_add_f32_dpp v48, v48, v48 quad_perm:[1,0,3,2] row_mask:0xf bank_mask:0xf bound_ctrl:1
	v_add_f32_dpp v49, v49, v49 quad_perm:[1,0,3,2] row_mask:0xf bank_mask:0xf bound_ctrl:1
	s_nop 1
	v_add_f32_dpp v48, v48, v48 quad_perm:[2,3,0,1] row_mask:0xf bank_mask:0xf bound_ctrl:1
	v_add_f32_dpp v49, v49, v49 quad_perm:[2,3,0,1] row_mask:0xf bank_mask:0xf bound_ctrl:1
	s_nop 1
	s_mov_b64 exec, s[86:87]
	ds_write_b64 v45, v[48:49] offset:15872
	s_mov_b64 exec, s[0:1]
; #define LAS __attribute__((address_space(3)))
; __device__ __forceinline__ unsigned cvt_pk_f16(float lo, float hi) { _Float16 a = (_Float16)lo, b = (_Float16)hi; return (unsigned)__builtin_bit_cast(unsigned short, a) | ((unsigned)__builtin_bit_cast(unsigned short, b) << 16); }
; __device__ __forceinline__ void scan_phase(const KP& P, LAS unsigned char* lds, const int tid, const int bx, const int G) {
;     ...
;             __syncthreads();
;             {
;                 const f32x4 y4 = *(const LAS f32x4*)(ybuf + tk * 64 + cg * 4);
;                 u32x2 w; w.x = cvt_pk_f16(y4.x, y4.y); w.y = cvt_pk_f16(y4.z, y4.w);
;                 *(u32x2*)(Yd + (size_t)scan_row(c, tk, d, b) * D + ch) = w;
;             }
;             if (c + 1 < NCH) SC_WRITE((c + 1) & 1, c + 1);
.LBB0_229:
	s_waitcnt lgkmcnt(0)
	s_barrier
	v_lshl_add_u32 v66, v52, 8, v57
	ds_read_b128 v[14:17], v66
	ds_read_b128 v[62:65], v66 offset:256
	s_cmp_lt_u32 s3, 8
	s_cselect_b64 vcc, -1, 0
	s_and_b64 s[0:1], vcc, exec
	s_cselect_b32 s0, 0xff, s80
	s_waitcnt lgkmcnt(0)
	v_pk_add_f32 v[14:15], v[14:15], v[62:63]
	v_pk_add_f32 v[16:17], v[16:17], v[64:65]
	v_cvt_f16_f32_e32 v0, v14
	v_cvt_f16_f32_sdwa v14, v15 dst_sel:WORD_1 dst_unused:UNUSED_PAD src0_sel:DWORD
	v_cvt_f16_f32_e32 v15, v16
	v_cvt_f16_f32_sdwa v16, v17 dst_sel:WORD_1 dst_unused:UNUSED_PAD src0_sel:DWORD
	s_cselect_b32 s1, s31, s33
	v_or_b32_e32 v14, v14, v0
	v_lshl_add_u32 v0, s3, 5, v52
	v_or_b32_e32 v15, v16, v15
	v_add_u32_e32 v16, 0xffffff00, v0
	v_cndmask_b32_e32 v16, v16, v0, vcc
	v_sub_u32_e32 v0, s0, v0
	v_cndmask_b32_e64 v0, v0, v16, s[12:13]
	v_add_u32_e32 v16, s1, v0
	v_ashrrev_i32_e32 v17, 31, v16
	v_lshlrev_b64 v[16:17], 12, v[16:17]
	v_lshl_add_u64 v[16:17], v[32:33], 0, v[16:17]
	s_and_b64 vcc, exec, s[4:5]
	global_store_dwordx2 v[16:17], v[14:15], off
	s_cbranch_vccz .LBB0_192
	s_waitcnt vmcnt(1)
	v_cvt_f32_f16_sdwa v45, v30 dst_sel:DWORD dst_unused:UNUSED_PAD src0_sel:WORD_1
	v_cvt_f32_f16_e32 v44, v30
	v_cvt_f32_f16_sdwa v47, v31 dst_sel:DWORD dst_unused:UNUSED_PAD src0_sel:WORD_1
	v_cvt_f32_f16_e32 v46, v31
	v_lshlrev_b32_e32 v14, 16, v24
	v_pk_add_f32 v[18:19], v[44:45], -1.0 op_sel_hi:[1,0]
	v_and_b32_e32 v15, 0xffff0000, v24
	v_pk_add_f32 v[20:21], v[46:47], -1.0 op_sel_hi:[1,0]
	v_lshlrev_b32_e32 v16, 16, v25
	v_and_b32_e32 v17, 0xffff0000, v25
	v_pk_fma_f32 v[20:21], v[8:9], v[20:21], 1.0 op_sel_hi:[1,1,0]
	v_pk_fma_f32 v[18:19], v[6:7], v[18:19], 1.0 op_sel_hi:[1,1,0]
	v_pk_mul_f32 v[50:51], v[4:5], v[16:17]
	v_pk_mul_f32 v[48:49], v[2:3], v[14:15]
	v_pk_mul_f32 v[20:21], v[20:21], v[16:17]
	v_pk_mul_f32 v[18:19], v[18:19], v[14:15]
	v_lshlrev_b32_e32 v14, 16, v22
	v_and_b32_e32 v15, 0xffff0000, v22
	v_lshlrev_b32_e32 v16, 16, v23
	v_and_b32_e32 v17, 0xffff0000, v23
	v_pk_mul_f32 v[62:63], v[18:19], v[14:15]
	v_pk_mul_f32 v[64:65], v[20:21], v[16:17]
	v_mul_f32_e32 v0, v49, v49
	v_mul_f32_e32 v61, v51, v51
	v_pk_mul_f32 v[64:65], v[12:13], v[64:65]
	v_pk_mul_f32 v[62:63], v[10:11], v[62:63]
	v_fmac_f32_e32 v0, v48, v48
	v_fmac_f32_e32 v61, v50, v50
	v_add_f32_e32 v0, v0, v61
	v_add_f32_e32 v61, v62, v63
	v_add_f32_e32 v62, v64, v65
	v_add_f32_e32 v62, v61, v62
	v_add_f32_dpp v0, v0, v0 quad_perm:[1,0,3,2] row_mask:0xf bank_mask:0xf bound_ctrl:1
	s_nop 0
	v_add_f32_dpp v62, v62, v62 quad_perm:[1,0,3,2] row_mask:0xf bank_mask:0xf bound_ctrl:1
	v_add_f32_dpp v0, v0, v0 quad_perm:[2,3,0,1] row_mask:0xf bank_mask:0xf bound_ctrl:1
	s_nop 0
	v_add_f32_dpp v62, v62, v62 quad_perm:[2,3,0,1] row_mask:0xf bank_mask:0xf bound_ctrl:1
	v_add_f32_dpp v0, v0, v0 row_half_mirror row_mask:0xf bank_mask:0xf bound_ctrl:1
	s_nop 0
	v_add_f32_dpp v62, v62, v62 row_half_mirror row_mask:0xf bank_mask:0xf bound_ctrl:1
	v_mov_b32_dpp v61, v0 row_mirror row_mask:0xf bank_mask:0xf bound_ctrl:1
	s_nop 0
	v_mov_b32_dpp v63, v62 row_mirror row_mask:0xf bank_mask:0xf bound_ctrl:1
	s_and_saveexec_b64 s[0:1], s[6:7]
	s_cbranch_execz .LBB0_191
	s_cmp_lt_u32 s3, 7
	s_cselect_b64 vcc, -1, 0
	v_add_f32_e32 v64, v62, v63
	v_lshl_add_u32 v62, s2, 5, v52
	s_and_b64 s[4:5], vcc, exec
	v_add_u32_e32 v63, 0xffffff00, v62
	s_cselect_b32 s3, 0xff, s80
	v_cndmask_b32_e32 v63, v63, v62, vcc
	v_sub_u32_e32 v62, s3, v62
	s_cselect_b32 s4, s31, s33
	v_cndmask_b32_e64 v62, v62, v63, s[12:13]
	v_add_u32_e32 v62, s4, v62
	v_ashrrev_i32_e32 v63, 31, v62
	v_lshlrev_b64 v[62:63], 7, v[62:63]
	v_lshl_add_u64 v[62:63], v[34:35], 0, v[62:63]
	global_store_dword v[62:63], v64, off
	s_branch .LBB0_191
